# v33 + softmax-epilogue SS1 prefetch (P4) + LDS-DMA saddr form (no VALU address math) in every GEMM K-loop
# speedup vs baseline: 1.0180x; 1.0029x over previous
.LBB0_241:
	s_add_u32 s94, s26, s92
	s_addc_u32 s95, s27, s93
	s_add_u32 s94, s94, 0x100
	s_addc_u32 s95, s95, 0
	s_add_u32 vcc_lo, s41, s92
	s_addc_u32 vcc_hi, s44, s93
	s_add_i32 s43, 0, 0x10000
	v_add_u32_e32 v152, s43, v171
	ds_read_b128 v[132:135], v152
	ds_read_b128 v[136:139], v152 offset:1024
	ds_read_b128 v[140:143], v152 offset:2048
	ds_read_b128 v[166:169], v152 offset:3072
	v_add_u32_e32 v152, s8, v171
	ds_read_b128 v[178:181], v152
	ds_read_b128 v[182:185], v152 offset:1024
	ds_read_b128 v[186:189], v152 offset:2048
	ds_read_b128 v[190:193], v152 offset:3072
	s_cmpk_eq_i32 s92, 0xf00
	s_cselect_b32 s97, s45, s95
	s_cselect_b32 s96, s50, s94
	s_cselect_b32 s95, s51, vcc_hi
	s_cselect_b32 s94, s81, vcc_lo
	v_lshl_add_u64 v[226:227], v[128:129], 0, s[92:93]
	s_add_i32 m0, s21, 0xc000
	ds_read_b128 v[194:197], v173
	ds_read_b128 v[198:201], v173 offset:1024
	ds_read_b128 v[202:205], v173 offset:2048
	ds_read_b128 v[206:209], v173 offset:3072
	ds_read_b128 v[210:213], v173 offset:4096
	ds_read_b128 v[214:217], v173 offset:5120
	ds_read_b128 v[218:221], v173 offset:6144
	ds_read_b128 v[222:225], v173 offset:7168
	global_load_lds_dwordx4 v[226:227], off
	v_lshl_add_u64 v[226:227], v[130:131], 0, s[92:93]
	s_add_i32 m0, s21, 0xe000
	s_nop 0
	global_load_lds_dwordx4 v[226:227], off
	s_waitcnt vmcnt(8)
	s_waitcnt lgkmcnt(0)
	s_barrier
	s_setprio 1
	s_waitcnt lgkmcnt(0)
	v_mfma_f32_16x16x32_bf16 v[124:127], v[132:135], v[194:197], v[124:127]
	v_mfma_f32_16x16x32_bf16 v[124:127], v[136:139], v[198:201], v[124:127]
	v_mfma_f32_16x16x32_bf16 v[120:123], v[140:143], v[194:197], v[120:123]
	v_mfma_f32_16x16x32_bf16 v[120:123], v[166:169], v[198:201], v[120:123]
	v_mfma_f32_16x16x32_bf16 v[116:119], v[132:135], v[202:205], v[116:119]
	v_mfma_f32_16x16x32_bf16 v[116:119], v[136:139], v[206:209], v[116:119]
	v_mfma_f32_16x16x32_bf16 v[112:115], v[140:143], v[202:205], v[112:115]
	v_mfma_f32_16x16x32_bf16 v[112:115], v[166:169], v[206:209], v[112:115]
	v_mfma_f32_16x16x32_bf16 v[108:111], v[132:135], v[210:213], v[108:111]
	v_mfma_f32_16x16x32_bf16 v[108:111], v[136:139], v[214:217], v[108:111]
	v_mfma_f32_16x16x32_bf16 v[104:107], v[140:143], v[210:213], v[104:107]
	v_mfma_f32_16x16x32_bf16 v[104:107], v[166:169], v[214:217], v[104:107]
	v_mfma_f32_16x16x32_bf16 v[100:103], v[132:135], v[218:221], v[100:103]
	v_mfma_f32_16x16x32_bf16 v[100:103], v[136:139], v[222:225], v[100:103]
	v_mfma_f32_16x16x32_bf16 v[96:99], v[140:143], v[218:221], v[96:99]
	v_mfma_f32_16x16x32_bf16 v[96:99], v[166:169], v[222:225], v[96:99]
	s_setprio 0
	s_setprio 1
	v_mfma_f32_16x16x32_bf16 v[92:95], v[178:181], v[194:197], v[92:95]
	v_mfma_f32_16x16x32_bf16 v[92:95], v[182:185], v[198:201], v[92:95]
	v_mfma_f32_16x16x32_bf16 v[88:91], v[186:189], v[194:197], v[88:91]
	v_mfma_f32_16x16x32_bf16 v[88:91], v[190:193], v[198:201], v[88:91]
	v_mfma_f32_16x16x32_bf16 v[84:87], v[178:181], v[202:205], v[84:87]
	v_mfma_f32_16x16x32_bf16 v[84:87], v[182:185], v[206:209], v[84:87]
	v_mfma_f32_16x16x32_bf16 v[80:83], v[186:189], v[202:205], v[80:83]
	v_mfma_f32_16x16x32_bf16 v[80:83], v[190:193], v[206:209], v[80:83]
	v_mfma_f32_16x16x32_bf16 v[76:79], v[178:181], v[210:213], v[76:79]
	v_mfma_f32_16x16x32_bf16 v[76:79], v[182:185], v[214:217], v[76:79]
	v_mfma_f32_16x16x32_bf16 v[72:75], v[186:189], v[210:213], v[72:75]
	v_mfma_f32_16x16x32_bf16 v[72:75], v[190:193], v[214:217], v[72:75]
	v_mfma_f32_16x16x32_bf16 v[68:71], v[178:181], v[218:221], v[68:71]
	v_mfma_f32_16x16x32_bf16 v[68:71], v[182:185], v[222:225], v[68:71]
	v_mfma_f32_16x16x32_bf16 v[64:67], v[186:189], v[218:221], v[64:67]
	v_mfma_f32_16x16x32_bf16 v[64:67], v[190:193], v[222:225], v[64:67]
	s_setprio 0
	s_barrier
	s_add_i32 s43, s43, s17
	s_add_u32 s98, s94, s70
	s_addc_u32 s99, s95, s71
	s_mov_b32 m0, s43
	ds_read_b128 v[194:197], v173 offset:16384
	ds_read_b128 v[198:201], v173 offset:17408
	ds_read_b128 v[202:205], v173 offset:18432
	ds_read_b128 v[206:209], v173 offset:19456
	ds_read_b128 v[210:213], v173 offset:20480
	ds_read_b128 v[214:217], v173 offset:21504
	ds_read_b128 v[218:221], v173 offset:22528
	ds_read_b128 v[222:225], v173 offset:23552
	global_load_lds_dwordx4 v146, s[94:95]
	s_add_i32 m0, s43, 0x2000
	s_add_u32 vcc_lo, s94, 0x80000
	s_addc_u32 vcc_hi, s95, 0
	s_add_i32 s43, s8, s17
	global_load_lds_dwordx4 v150, s[94:95]
	s_mov_b32 m0, s43
	s_nop 0
	global_load_lds_dwordx4 v146, vcc
	s_add_i32 m0, s43, 0x2000
	s_nop 0
	global_load_lds_dwordx4 v150, vcc
	s_add_u32 s100, s96, s70
	s_addc_u32 s101, s97, s71
	s_mov_b32 m0, s21
	s_nop 0
	global_load_lds_dwordx4 v144, s[96:97]
	s_mov_b32 m0, s39
	s_nop 0
	global_load_lds_dwordx4 v148, s[96:97]
	s_waitcnt vmcnt(8)
	s_waitcnt lgkmcnt(0)
	s_barrier
	s_setprio 1
	s_waitcnt lgkmcnt(0)
	v_mfma_f32_16x16x32_bf16 v[60:63], v[132:135], v[194:197], v[60:63]
	v_mfma_f32_16x16x32_bf16 v[60:63], v[136:139], v[198:201], v[60:63]
	v_mfma_f32_16x16x32_bf16 v[56:59], v[140:143], v[194:197], v[56:59]
	v_mfma_f32_16x16x32_bf16 v[56:59], v[166:169], v[198:201], v[56:59]
	v_mfma_f32_16x16x32_bf16 v[52:55], v[132:135], v[202:205], v[52:55]
	v_mfma_f32_16x16x32_bf16 v[52:55], v[136:139], v[206:209], v[52:55]
	v_mfma_f32_16x16x32_bf16 v[48:51], v[140:143], v[202:205], v[48:51]
	v_mfma_f32_16x16x32_bf16 v[48:51], v[166:169], v[206:209], v[48:51]
	v_mfma_f32_16x16x32_bf16 v[44:47], v[132:135], v[210:213], v[44:47]
	v_mfma_f32_16x16x32_bf16 v[44:47], v[136:139], v[214:217], v[44:47]
	v_mfma_f32_16x16x32_bf16 v[40:43], v[140:143], v[210:213], v[40:43]
	v_mfma_f32_16x16x32_bf16 v[40:43], v[166:169], v[214:217], v[40:43]
	v_mfma_f32_16x16x32_bf16 v[36:39], v[132:135], v[218:221], v[36:39]
	v_mfma_f32_16x16x32_bf16 v[36:39], v[136:139], v[222:225], v[36:39]
	v_mfma_f32_16x16x32_bf16 v[32:35], v[140:143], v[218:221], v[32:35]
	v_mfma_f32_16x16x32_bf16 v[32:35], v[166:169], v[222:225], v[32:35]
	s_setprio 0
	s_setprio 1
	v_mfma_f32_16x16x32_bf16 v[28:31], v[178:181], v[194:197], v[28:31]
	v_mfma_f32_16x16x32_bf16 v[28:31], v[182:185], v[198:201], v[28:31]
	v_mfma_f32_16x16x32_bf16 v[24:27], v[186:189], v[194:197], v[24:27]
	v_mfma_f32_16x16x32_bf16 v[24:27], v[190:193], v[198:201], v[24:27]
	v_mfma_f32_16x16x32_bf16 v[20:23], v[178:181], v[202:205], v[20:23]
	v_mfma_f32_16x16x32_bf16 v[20:23], v[182:185], v[206:209], v[20:23]
	v_mfma_f32_16x16x32_bf16 v[16:19], v[186:189], v[202:205], v[16:19]
	v_mfma_f32_16x16x32_bf16 v[16:19], v[190:193], v[206:209], v[16:19]
	v_mfma_f32_16x16x32_bf16 v[12:15], v[178:181], v[210:213], v[12:15]
	v_mfma_f32_16x16x32_bf16 v[12:15], v[182:185], v[214:217], v[12:15]
	v_mfma_f32_16x16x32_bf16 v[8:11], v[186:189], v[210:213], v[8:11]
	v_mfma_f32_16x16x32_bf16 v[8:11], v[190:193], v[214:217], v[8:11]
	v_mfma_f32_16x16x32_bf16 v[4:7], v[178:181], v[218:221], v[4:7]
	v_mfma_f32_16x16x32_bf16 v[4:7], v[182:185], v[222:225], v[4:7]
	v_mfma_f32_16x16x32_bf16 v[0:3], v[186:189], v[218:221], v[0:3]
	v_mfma_f32_16x16x32_bf16 v[0:3], v[190:193], v[222:225], v[0:3]
	s_setprio 0
	s_barrier
	s_add_i32 s43, 0, 0x18000
	v_add_u32_e32 v152, s43, v171
	s_add_i32 vcc_lo, 0, 0x1c000
	ds_read_b128 v[132:135], v152
	ds_read_b128 v[136:139], v152 offset:1024
	ds_read_b128 v[140:143], v152 offset:2048
	ds_read_b128 v[166:169], v152 offset:3072
	v_add_u32_e32 v152, vcc_lo, v171
	ds_read_b128 v[178:181], v152
	ds_read_b128 v[182:185], v152 offset:1024
	ds_read_b128 v[186:189], v152 offset:2048
	ds_read_b128 v[190:193], v152 offset:3072
	s_add_u32 s96, s96, 0x80000
	s_addc_u32 s97, s97, 0
	s_mov_b32 m0, s6
	ds_read_b128 v[194:197], v173 offset:32768
	ds_read_b128 v[198:201], v173 offset:33792
	ds_read_b128 v[202:205], v173 offset:34816
	ds_read_b128 v[206:209], v173 offset:35840
	ds_read_b128 v[210:213], v173 offset:36864
	ds_read_b128 v[214:217], v173 offset:37888
	ds_read_b128 v[218:221], v173 offset:38912
	ds_read_b128 v[222:225], v173 offset:39936
	global_load_lds_dwordx4 v144, s[96:97]
	s_mov_b32 m0, s10
	s_nop 0
	global_load_lds_dwordx4 v148, s[96:97]
	s_waitcnt vmcnt(8)
	s_waitcnt lgkmcnt(0)
	s_barrier
	s_setprio 1
	s_waitcnt lgkmcnt(0)
	v_mfma_f32_16x16x32_bf16 v[124:127], v[132:135], v[194:197], v[124:127]
	v_mfma_f32_16x16x32_bf16 v[124:127], v[136:139], v[198:201], v[124:127]
	v_mfma_f32_16x16x32_bf16 v[120:123], v[140:143], v[194:197], v[120:123]
	v_mfma_f32_16x16x32_bf16 v[120:123], v[166:169], v[198:201], v[120:123]
	v_mfma_f32_16x16x32_bf16 v[116:119], v[132:135], v[202:205], v[116:119]
	v_mfma_f32_16x16x32_bf16 v[116:119], v[136:139], v[206:209], v[116:119]
	v_mfma_f32_16x16x32_bf16 v[112:115], v[140:143], v[202:205], v[112:115]
	v_mfma_f32_16x16x32_bf16 v[112:115], v[166:169], v[206:209], v[112:115]
	v_mfma_f32_16x16x32_bf16 v[108:111], v[132:135], v[210:213], v[108:111]
	v_mfma_f32_16x16x32_bf16 v[108:111], v[136:139], v[214:217], v[108:111]
	v_mfma_f32_16x16x32_bf16 v[104:107], v[140:143], v[210:213], v[104:107]
	v_mfma_f32_16x16x32_bf16 v[104:107], v[166:169], v[214:217], v[104:107]
	v_mfma_f32_16x16x32_bf16 v[100:103], v[132:135], v[218:221], v[100:103]
	v_mfma_f32_16x16x32_bf16 v[100:103], v[136:139], v[222:225], v[100:103]
	v_mfma_f32_16x16x32_bf16 v[96:99], v[140:143], v[218:221], v[96:99]
	v_mfma_f32_16x16x32_bf16 v[96:99], v[166:169], v[222:225], v[96:99]
	s_setprio 0
	s_setprio 1
	v_mfma_f32_16x16x32_bf16 v[92:95], v[178:181], v[194:197], v[92:95]
	v_mfma_f32_16x16x32_bf16 v[92:95], v[182:185], v[198:201], v[92:95]
	v_mfma_f32_16x16x32_bf16 v[88:91], v[186:189], v[194:197], v[88:91]
	v_mfma_f32_16x16x32_bf16 v[88:91], v[190:193], v[198:201], v[88:91]
	v_mfma_f32_16x16x32_bf16 v[84:87], v[178:181], v[202:205], v[84:87]
	v_mfma_f32_16x16x32_bf16 v[84:87], v[182:185], v[206:209], v[84:87]
	v_mfma_f32_16x16x32_bf16 v[80:83], v[186:189], v[202:205], v[80:83]
	v_mfma_f32_16x16x32_bf16 v[80:83], v[190:193], v[206:209], v[80:83]
	v_mfma_f32_16x16x32_bf16 v[76:79], v[178:181], v[210:213], v[76:79]
	v_mfma_f32_16x16x32_bf16 v[76:79], v[182:185], v[214:217], v[76:79]
	v_mfma_f32_16x16x32_bf16 v[72:75], v[186:189], v[210:213], v[72:75]
	v_mfma_f32_16x16x32_bf16 v[72:75], v[190:193], v[214:217], v[72:75]
	v_mfma_f32_16x16x32_bf16 v[68:71], v[178:181], v[218:221], v[68:71]
	v_mfma_f32_16x16x32_bf16 v[68:71], v[182:185], v[222:225], v[68:71]
	v_mfma_f32_16x16x32_bf16 v[64:67], v[186:189], v[218:221], v[64:67]
	v_mfma_f32_16x16x32_bf16 v[64:67], v[190:193], v[222:225], v[64:67]
	s_setprio 0
	s_barrier
	s_add_i32 s43, s43, s17
	s_mov_b32 m0, s43
	ds_read_b128 v[194:197], v173 offset:49152
	ds_read_b128 v[198:201], v173 offset:50176
	ds_read_b128 v[202:205], v173 offset:51200
	ds_read_b128 v[206:209], v173 offset:52224
	ds_read_b128 v[210:213], v173 offset:53248
	ds_read_b128 v[214:217], v173 offset:54272
	ds_read_b128 v[218:221], v173 offset:55296
	ds_read_b128 v[222:225], v173 offset:56320
	global_load_lds_dwordx4 v146, s[98:99]
	s_add_i32 m0, s43, 0x2000
	s_add_u32 s94, s94, 0x80080
	s_addc_u32 s95, s95, 0
	s_add_i32 s43, vcc_lo, s17
	global_load_lds_dwordx4 v150, s[98:99]
	s_mov_b32 m0, s43
	s_nop 0
	global_load_lds_dwordx4 v146, s[94:95]
	s_add_i32 m0, s43, 0x2000
	s_nop 0
	global_load_lds_dwordx4 v150, s[94:95]
	s_mov_b32 m0, s33
	s_nop 0
	global_load_lds_dwordx4 v144, s[100:101]
	s_mov_b32 m0, s7
	s_nop 0
	global_load_lds_dwordx4 v148, s[100:101]
	s_waitcnt vmcnt(8)
	s_waitcnt lgkmcnt(0)
	s_barrier
	s_setprio 1
	s_waitcnt lgkmcnt(0)
	v_mfma_f32_16x16x32_bf16 v[60:63], v[132:135], v[194:197], v[60:63]
	v_mfma_f32_16x16x32_bf16 v[60:63], v[136:139], v[198:201], v[60:63]
	v_mfma_f32_16x16x32_bf16 v[56:59], v[140:143], v[194:197], v[56:59]
	v_mfma_f32_16x16x32_bf16 v[56:59], v[166:169], v[198:201], v[56:59]
	v_mfma_f32_16x16x32_bf16 v[52:55], v[132:135], v[202:205], v[52:55]
	v_mfma_f32_16x16x32_bf16 v[52:55], v[136:139], v[206:209], v[52:55]
	v_mfma_f32_16x16x32_bf16 v[48:51], v[140:143], v[202:205], v[48:51]
	v_mfma_f32_16x16x32_bf16 v[48:51], v[166:169], v[206:209], v[48:51]
	v_mfma_f32_16x16x32_bf16 v[44:47], v[132:135], v[210:213], v[44:47]
	v_mfma_f32_16x16x32_bf16 v[44:47], v[136:139], v[214:217], v[44:47]
	v_mfma_f32_16x16x32_bf16 v[40:43], v[140:143], v[210:213], v[40:43]
	v_mfma_f32_16x16x32_bf16 v[40:43], v[166:169], v[214:217], v[40:43]
	v_mfma_f32_16x16x32_bf16 v[36:39], v[132:135], v[218:221], v[36:39]
	v_mfma_f32_16x16x32_bf16 v[36:39], v[136:139], v[222:225], v[36:39]
	v_mfma_f32_16x16x32_bf16 v[32:35], v[140:143], v[218:221], v[32:35]
	v_mfma_f32_16x16x32_bf16 v[32:35], v[166:169], v[222:225], v[32:35]
	s_setprio 0
	s_setprio 1
	v_mfma_f32_16x16x32_bf16 v[28:31], v[178:181], v[194:197], v[28:31]
	v_mfma_f32_16x16x32_bf16 v[28:31], v[182:185], v[198:201], v[28:31]
	v_mfma_f32_16x16x32_bf16 v[24:27], v[186:189], v[194:197], v[24:27]
	v_mfma_f32_16x16x32_bf16 v[24:27], v[190:193], v[198:201], v[24:27]
	v_mfma_f32_16x16x32_bf16 v[20:23], v[178:181], v[202:205], v[20:23]
	v_mfma_f32_16x16x32_bf16 v[20:23], v[182:185], v[206:209], v[20:23]
	v_mfma_f32_16x16x32_bf16 v[16:19], v[186:189], v[202:205], v[16:19]
	v_mfma_f32_16x16x32_bf16 v[16:19], v[190:193], v[206:209], v[16:19]
	v_mfma_f32_16x16x32_bf16 v[12:15], v[178:181], v[210:213], v[12:15]
	v_mfma_f32_16x16x32_bf16 v[12:15], v[182:185], v[214:217], v[12:15]
	v_mfma_f32_16x16x32_bf16 v[8:11], v[186:189], v[210:213], v[8:11]
	v_mfma_f32_16x16x32_bf16 v[8:11], v[190:193], v[214:217], v[8:11]
	v_mfma_f32_16x16x32_bf16 v[4:7], v[178:181], v[218:221], v[4:7]
	v_mfma_f32_16x16x32_bf16 v[4:7], v[182:185], v[222:225], v[4:7]
	v_mfma_f32_16x16x32_bf16 v[0:3], v[186:189], v[218:221], v[0:3]
	v_mfma_f32_16x16x32_bf16 v[0:3], v[190:193], v[222:225], v[0:3]
	s_setprio 0
	s_barrier
	s_add_i32 s83, s83, 2
	s_add_u32 s92, s92, 0x100
	s_addc_u32 s93, s93, 0
	s_cmp_gt_u32 s83, 29
	s_cbranch_scc0 .LBB0_241
	s_and_b64 vcc, exec, s[72:73]
	s_cbranch_vccz .LBB0_244
	s_barrier

.LBB0_273:
	ds_read_b128 v[146:149], v141
	ds_read_b128 v[150:153], v141 offset:1024
	ds_read_b128 v[154:157], v141 offset:2048
	ds_read_b128 v[158:161], v141 offset:3072
	ds_read_b128 v[162:165], v142
	ds_read_b128 v[166:169], v142 offset:1024
	ds_read_b128 v[170:173], v142 offset:2048
	ds_read_b128 v[176:179], v142 offset:3072
	s_add_u32 s48, s46, 0xfff80080
	s_addc_u32 s49, s47, -1
	s_cmp_eq_u32 s80, 4
	s_cselect_b32 s69, s39, s49
	s_cselect_b32 s68, s38, s48
	s_cselect_b32 s49, s43, s79
	s_cselect_b32 s48, s42, s27
	s_add_i32 m0, s10, 0xc000
	ds_read_b128 v[180:183], v143
	ds_read_b128 v[184:187], v143 offset:1024
	ds_read_b128 v[188:191], v143 offset:2048
	ds_read_b128 v[192:195], v143 offset:3072
	ds_read_b128 v[196:199], v143 offset:4096
	ds_read_b128 v[200:203], v143 offset:5120
	ds_read_b128 v[204:207], v143 offset:6144
	ds_read_b128 v[208:211], v143 offset:7168
	global_load_lds_dwordx4 v136, s[46:47]
	s_add_i32 m0, s10, 0xe000
	s_nop 0
	global_load_lds_dwordx4 v138, s[46:47]
	s_waitcnt vmcnt(8)
	s_waitcnt lgkmcnt(0)
	s_barrier
	s_setprio 1
	s_waitcnt lgkmcnt(0)
	v_mfma_f32_16x16x32_bf16 v[124:127], v[146:149], v[180:183], v[124:127]
	v_mfma_f32_16x16x32_bf16 v[124:127], v[150:153], v[184:187], v[124:127]
	v_mfma_f32_16x16x32_bf16 v[120:123], v[154:157], v[180:183], v[120:123]
	v_mfma_f32_16x16x32_bf16 v[120:123], v[158:161], v[184:187], v[120:123]
	v_mfma_f32_16x16x32_bf16 v[116:119], v[146:149], v[188:191], v[116:119]
	v_mfma_f32_16x16x32_bf16 v[116:119], v[150:153], v[192:195], v[116:119]
	v_mfma_f32_16x16x32_bf16 v[112:115], v[154:157], v[188:191], v[112:115]
	v_mfma_f32_16x16x32_bf16 v[112:115], v[158:161], v[192:195], v[112:115]
	v_mfma_f32_16x16x32_bf16 v[100:103], v[146:149], v[196:199], v[100:103]
	v_mfma_f32_16x16x32_bf16 v[100:103], v[150:153], v[200:203], v[100:103]
	v_mfma_f32_16x16x32_bf16 v[96:99], v[154:157], v[196:199], v[96:99]
	v_mfma_f32_16x16x32_bf16 v[96:99], v[158:161], v[200:203], v[96:99]
	v_mfma_f32_16x16x32_bf16 v[84:87], v[146:149], v[204:207], v[84:87]
	v_mfma_f32_16x16x32_bf16 v[84:87], v[150:153], v[208:211], v[84:87]
	v_mfma_f32_16x16x32_bf16 v[80:83], v[154:157], v[204:207], v[80:83]
	v_mfma_f32_16x16x32_bf16 v[80:83], v[158:161], v[208:211], v[80:83]
	s_setprio 0
	s_setprio 1
	v_mfma_f32_16x16x32_bf16 v[108:111], v[162:165], v[180:183], v[108:111]
	v_mfma_f32_16x16x32_bf16 v[108:111], v[166:169], v[184:187], v[108:111]
	v_mfma_f32_16x16x32_bf16 v[104:107], v[170:173], v[180:183], v[104:107]
	v_mfma_f32_16x16x32_bf16 v[104:107], v[176:179], v[184:187], v[104:107]
	v_mfma_f32_16x16x32_bf16 v[92:95], v[162:165], v[188:191], v[92:95]
	v_mfma_f32_16x16x32_bf16 v[92:95], v[166:169], v[192:195], v[92:95]
	v_mfma_f32_16x16x32_bf16 v[88:91], v[170:173], v[188:191], v[88:91]
	v_mfma_f32_16x16x32_bf16 v[88:91], v[176:179], v[192:195], v[88:91]
	v_mfma_f32_16x16x32_bf16 v[76:79], v[162:165], v[196:199], v[76:79]
	v_mfma_f32_16x16x32_bf16 v[76:79], v[166:169], v[200:203], v[76:79]
	v_mfma_f32_16x16x32_bf16 v[72:75], v[170:173], v[196:199], v[72:75]
	v_mfma_f32_16x16x32_bf16 v[72:75], v[176:179], v[200:203], v[72:75]
	v_mfma_f32_16x16x32_bf16 v[68:71], v[162:165], v[204:207], v[68:71]
	v_mfma_f32_16x16x32_bf16 v[68:71], v[166:169], v[208:211], v[68:71]
	v_mfma_f32_16x16x32_bf16 v[64:67], v[170:173], v[204:207], v[64:67]
	v_mfma_f32_16x16x32_bf16 v[64:67], v[176:179], v[208:211], v[64:67]
	s_setprio 0
	s_barrier
	s_add_i32 s81, s45, s6
	s_add_u32 s98, s48, s16
	s_addc_u32 s99, s49, s17
	s_mov_b32 m0, s81
	ds_read_b128 v[180:183], v143 offset:16384
	ds_read_b128 v[184:187], v143 offset:17408
	ds_read_b128 v[188:191], v143 offset:18432
	ds_read_b128 v[192:195], v143 offset:19456
	ds_read_b128 v[196:199], v143 offset:20480
	ds_read_b128 v[200:203], v143 offset:21504
	ds_read_b128 v[204:207], v143 offset:22528
	ds_read_b128 v[208:211], v143 offset:23552
	global_load_lds_dwordx4 v132, s[48:49]
	s_add_i32 m0, s81, 0x2000
	s_add_u32 s82, s48, 0x80000
	s_addc_u32 s83, s49, 0
	s_add_i32 s81, s50, s6
	global_load_lds_dwordx4 v128, s[48:49]
	s_mov_b32 m0, s81
	s_nop 0
	global_load_lds_dwordx4 v132, s[82:83]
	s_add_i32 m0, s81, 0x2000
	s_nop 0
	global_load_lds_dwordx4 v128, s[82:83]
	s_add_u32 s100, s68, s16
	s_addc_u32 s101, s69, s17
	s_mov_b32 m0, s10
	s_nop 0
	global_load_lds_dwordx4 v134, s[68:69]
	s_mov_b32 m0, s22
	s_nop 0
	global_load_lds_dwordx4 v130, s[68:69]
	s_waitcnt vmcnt(8)
	s_waitcnt lgkmcnt(0)
	s_barrier
	s_setprio 1
	s_waitcnt lgkmcnt(0)
	v_mfma_f32_16x16x32_bf16 v[60:63], v[146:149], v[180:183], v[60:63]
	v_mfma_f32_16x16x32_bf16 v[60:63], v[150:153], v[184:187], v[60:63]
	v_mfma_f32_16x16x32_bf16 v[56:59], v[154:157], v[180:183], v[56:59]
	v_mfma_f32_16x16x32_bf16 v[56:59], v[158:161], v[184:187], v[56:59]
	v_mfma_f32_16x16x32_bf16 v[52:55], v[146:149], v[188:191], v[52:55]
	v_mfma_f32_16x16x32_bf16 v[52:55], v[150:153], v[192:195], v[52:55]
	v_mfma_f32_16x16x32_bf16 v[48:51], v[154:157], v[188:191], v[48:51]
	v_mfma_f32_16x16x32_bf16 v[48:51], v[158:161], v[192:195], v[48:51]
	v_mfma_f32_16x16x32_bf16 v[36:39], v[146:149], v[196:199], v[36:39]
	v_mfma_f32_16x16x32_bf16 v[36:39], v[150:153], v[200:203], v[36:39]
	v_mfma_f32_16x16x32_bf16 v[32:35], v[154:157], v[196:199], v[32:35]
	v_mfma_f32_16x16x32_bf16 v[32:35], v[158:161], v[200:203], v[32:35]
	v_mfma_f32_16x16x32_bf16 v[20:23], v[146:149], v[204:207], v[20:23]
	v_mfma_f32_16x16x32_bf16 v[20:23], v[150:153], v[208:211], v[20:23]
	v_mfma_f32_16x16x32_bf16 v[16:19], v[154:157], v[204:207], v[16:19]
	v_mfma_f32_16x16x32_bf16 v[16:19], v[158:161], v[208:211], v[16:19]
	s_setprio 0
	s_setprio 1
	v_mfma_f32_16x16x32_bf16 v[44:47], v[162:165], v[180:183], v[44:47]
	v_mfma_f32_16x16x32_bf16 v[44:47], v[166:169], v[184:187], v[44:47]
	v_mfma_f32_16x16x32_bf16 v[40:43], v[170:173], v[180:183], v[40:43]
	v_mfma_f32_16x16x32_bf16 v[40:43], v[176:179], v[184:187], v[40:43]
	v_mfma_f32_16x16x32_bf16 v[28:31], v[162:165], v[188:191], v[28:31]
	v_mfma_f32_16x16x32_bf16 v[28:31], v[166:169], v[192:195], v[28:31]
	v_mfma_f32_16x16x32_bf16 v[24:27], v[170:173], v[188:191], v[24:27]
	v_mfma_f32_16x16x32_bf16 v[24:27], v[176:179], v[192:195], v[24:27]
	v_mfma_f32_16x16x32_bf16 v[12:15], v[162:165], v[196:199], v[12:15]
	v_mfma_f32_16x16x32_bf16 v[12:15], v[166:169], v[200:203], v[12:15]
	v_mfma_f32_16x16x32_bf16 v[8:11], v[170:173], v[196:199], v[8:11]
	v_mfma_f32_16x16x32_bf16 v[8:11], v[176:179], v[200:203], v[8:11]
	v_mfma_f32_16x16x32_bf16 v[4:7], v[162:165], v[204:207], v[4:7]
	v_mfma_f32_16x16x32_bf16 v[4:7], v[166:169], v[208:211], v[4:7]
	v_mfma_f32_16x16x32_bf16 v[0:3], v[170:173], v[204:207], v[0:3]
	v_mfma_f32_16x16x32_bf16 v[0:3], v[176:179], v[208:211], v[0:3]
	s_setprio 0
	s_barrier
	s_add_i32 s81, 0, 0x18000
	v_add_u32_e32 v145, s81, v140
	s_add_i32 s82, 0, 0x1c000
	ds_read_b128 v[146:149], v145
	ds_read_b128 v[150:153], v145 offset:1024
	ds_read_b128 v[154:157], v145 offset:2048
	ds_read_b128 v[158:161], v145 offset:3072
	v_add_u32_e32 v145, s82, v140
	ds_read_b128 v[162:165], v145
	ds_read_b128 v[166:169], v145 offset:1024
	ds_read_b128 v[170:173], v145 offset:2048
	ds_read_b128 v[176:179], v145 offset:3072
	s_add_u32 s68, s68, 0x80000
	s_addc_u32 s69, s69, 0
	s_mov_b32 m0, s23
	ds_read_b128 v[180:183], v143 offset:32768
	ds_read_b128 v[184:187], v143 offset:33792
	ds_read_b128 v[188:191], v143 offset:34816
	ds_read_b128 v[192:195], v143 offset:35840
	ds_read_b128 v[196:199], v143 offset:36864
	ds_read_b128 v[200:203], v143 offset:37888
	ds_read_b128 v[204:207], v143 offset:38912
	ds_read_b128 v[208:211], v143 offset:39936
	global_load_lds_dwordx4 v134, s[68:69]
	s_mov_b32 m0, s33
	s_nop 0
	global_load_lds_dwordx4 v130, s[68:69]
	s_waitcnt vmcnt(8)
	s_waitcnt lgkmcnt(0)
	s_barrier
	s_setprio 1
	s_waitcnt lgkmcnt(0)
	v_mfma_f32_16x16x32_bf16 v[124:127], v[146:149], v[180:183], v[124:127]
	v_mfma_f32_16x16x32_bf16 v[124:127], v[150:153], v[184:187], v[124:127]
	v_mfma_f32_16x16x32_bf16 v[120:123], v[154:157], v[180:183], v[120:123]
	v_mfma_f32_16x16x32_bf16 v[120:123], v[158:161], v[184:187], v[120:123]
	v_mfma_f32_16x16x32_bf16 v[116:119], v[146:149], v[188:191], v[116:119]
	v_mfma_f32_16x16x32_bf16 v[116:119], v[150:153], v[192:195], v[116:119]
	v_mfma_f32_16x16x32_bf16 v[112:115], v[154:157], v[188:191], v[112:115]
	v_mfma_f32_16x16x32_bf16 v[112:115], v[158:161], v[192:195], v[112:115]
	v_mfma_f32_16x16x32_bf16 v[100:103], v[146:149], v[196:199], v[100:103]
	v_mfma_f32_16x16x32_bf16 v[100:103], v[150:153], v[200:203], v[100:103]
	v_mfma_f32_16x16x32_bf16 v[96:99], v[154:157], v[196:199], v[96:99]
	v_mfma_f32_16x16x32_bf16 v[96:99], v[158:161], v[200:203], v[96:99]
	v_mfma_f32_16x16x32_bf16 v[84:87], v[146:149], v[204:207], v[84:87]
	v_mfma_f32_16x16x32_bf16 v[84:87], v[150:153], v[208:211], v[84:87]
	v_mfma_f32_16x16x32_bf16 v[80:83], v[154:157], v[204:207], v[80:83]
	v_mfma_f32_16x16x32_bf16 v[80:83], v[158:161], v[208:211], v[80:83]
	s_setprio 0
	s_setprio 1
	v_mfma_f32_16x16x32_bf16 v[108:111], v[162:165], v[180:183], v[108:111]
	v_mfma_f32_16x16x32_bf16 v[108:111], v[166:169], v[184:187], v[108:111]
	v_mfma_f32_16x16x32_bf16 v[104:107], v[170:173], v[180:183], v[104:107]
	v_mfma_f32_16x16x32_bf16 v[104:107], v[176:179], v[184:187], v[104:107]
	v_mfma_f32_16x16x32_bf16 v[92:95], v[162:165], v[188:191], v[92:95]
	v_mfma_f32_16x16x32_bf16 v[92:95], v[166:169], v[192:195], v[92:95]
	v_mfma_f32_16x16x32_bf16 v[88:91], v[170:173], v[188:191], v[88:91]
	v_mfma_f32_16x16x32_bf16 v[88:91], v[176:179], v[192:195], v[88:91]
	v_mfma_f32_16x16x32_bf16 v[76:79], v[162:165], v[196:199], v[76:79]
	v_mfma_f32_16x16x32_bf16 v[76:79], v[166:169], v[200:203], v[76:79]
	v_mfma_f32_16x16x32_bf16 v[72:75], v[170:173], v[196:199], v[72:75]
	v_mfma_f32_16x16x32_bf16 v[72:75], v[176:179], v[200:203], v[72:75]
	v_mfma_f32_16x16x32_bf16 v[68:71], v[162:165], v[204:207], v[68:71]
	v_mfma_f32_16x16x32_bf16 v[68:71], v[166:169], v[208:211], v[68:71]
	v_mfma_f32_16x16x32_bf16 v[64:67], v[170:173], v[204:207], v[64:67]
	v_mfma_f32_16x16x32_bf16 v[64:67], v[176:179], v[208:211], v[64:67]
	s_setprio 0
	s_barrier
	s_add_i32 s68, s81, s6
	s_mov_b32 m0, s68
	ds_read_b128 v[180:183], v143 offset:49152
	ds_read_b128 v[184:187], v143 offset:50176
	ds_read_b128 v[188:191], v143 offset:51200
	ds_read_b128 v[192:195], v143 offset:52224
	ds_read_b128 v[196:199], v143 offset:53248
	ds_read_b128 v[200:203], v143 offset:54272
	ds_read_b128 v[204:207], v143 offset:55296
	ds_read_b128 v[208:211], v143 offset:56320
	global_load_lds_dwordx4 v132, s[98:99]
	s_add_i32 m0, s68, 0x2000
	s_add_u32 s48, s48, 0x80080
	s_addc_u32 s49, s49, 0
	s_add_i32 s68, s82, s6
	global_load_lds_dwordx4 v128, s[98:99]
	s_mov_b32 m0, s68
	s_nop 0
	global_load_lds_dwordx4 v132, s[48:49]
	s_add_i32 m0, s68, 0x2000
	s_nop 0
	global_load_lds_dwordx4 v128, s[48:49]
	s_mov_b32 m0, s41
	s_nop 0
	global_load_lds_dwordx4 v134, s[100:101]
	s_mov_b32 m0, s44
	s_nop 0
	global_load_lds_dwordx4 v130, s[100:101]
	s_waitcnt vmcnt(8)
	s_waitcnt lgkmcnt(0)
	s_barrier
	s_setprio 1
	s_waitcnt lgkmcnt(0)
	v_mfma_f32_16x16x32_bf16 v[60:63], v[146:149], v[180:183], v[60:63]
	v_mfma_f32_16x16x32_bf16 v[60:63], v[150:153], v[184:187], v[60:63]
	v_mfma_f32_16x16x32_bf16 v[56:59], v[154:157], v[180:183], v[56:59]
	v_mfma_f32_16x16x32_bf16 v[56:59], v[158:161], v[184:187], v[56:59]
	v_mfma_f32_16x16x32_bf16 v[52:55], v[146:149], v[188:191], v[52:55]
	v_mfma_f32_16x16x32_bf16 v[52:55], v[150:153], v[192:195], v[52:55]
	v_mfma_f32_16x16x32_bf16 v[48:51], v[154:157], v[188:191], v[48:51]
	v_mfma_f32_16x16x32_bf16 v[48:51], v[158:161], v[192:195], v[48:51]
	v_mfma_f32_16x16x32_bf16 v[36:39], v[146:149], v[196:199], v[36:39]
	v_mfma_f32_16x16x32_bf16 v[36:39], v[150:153], v[200:203], v[36:39]
	v_mfma_f32_16x16x32_bf16 v[32:35], v[154:157], v[196:199], v[32:35]
	v_mfma_f32_16x16x32_bf16 v[32:35], v[158:161], v[200:203], v[32:35]
	v_mfma_f32_16x16x32_bf16 v[20:23], v[146:149], v[204:207], v[20:23]
	v_mfma_f32_16x16x32_bf16 v[20:23], v[150:153], v[208:211], v[20:23]
	v_mfma_f32_16x16x32_bf16 v[16:19], v[154:157], v[204:207], v[16:19]
	v_mfma_f32_16x16x32_bf16 v[16:19], v[158:161], v[208:211], v[16:19]
	s_setprio 0
	s_setprio 1
	v_mfma_f32_16x16x32_bf16 v[44:47], v[162:165], v[180:183], v[44:47]
	v_mfma_f32_16x16x32_bf16 v[44:47], v[166:169], v[184:187], v[44:47]
	v_mfma_f32_16x16x32_bf16 v[40:43], v[170:173], v[180:183], v[40:43]
	v_mfma_f32_16x16x32_bf16 v[40:43], v[176:179], v[184:187], v[40:43]
	v_mfma_f32_16x16x32_bf16 v[28:31], v[162:165], v[188:191], v[28:31]
	v_mfma_f32_16x16x32_bf16 v[28:31], v[166:169], v[192:195], v[28:31]
	v_mfma_f32_16x16x32_bf16 v[24:27], v[170:173], v[188:191], v[24:27]
	v_mfma_f32_16x16x32_bf16 v[24:27], v[176:179], v[192:195], v[24:27]
	v_mfma_f32_16x16x32_bf16 v[12:15], v[162:165], v[196:199], v[12:15]
	v_mfma_f32_16x16x32_bf16 v[12:15], v[166:169], v[200:203], v[12:15]
	v_mfma_f32_16x16x32_bf16 v[8:11], v[170:173], v[196:199], v[8:11]
	v_mfma_f32_16x16x32_bf16 v[8:11], v[176:179], v[200:203], v[8:11]
	v_mfma_f32_16x16x32_bf16 v[4:7], v[162:165], v[204:207], v[4:7]
	v_mfma_f32_16x16x32_bf16 v[4:7], v[166:169], v[208:211], v[4:7]
	v_mfma_f32_16x16x32_bf16 v[0:3], v[170:173], v[204:207], v[0:3]
	v_mfma_f32_16x16x32_bf16 v[0:3], v[176:179], v[208:211], v[0:3]
	s_setprio 0
	s_barrier
	s_add_i32 s80, s80, 2
	s_add_u32 s46, s46, 0x100
	s_addc_u32 s47, s47, 0
	s_add_u32 s27, s27, 0x100
	s_addc_u32 s79, s79, 0
	s_cmp_gt_u32 s80, 5
	s_cbranch_scc0 .LBB0_273
	s_and_b64 vcc, exec, s[20:21]
	s_cbranch_vccz .LBB0_276
	s_barrier

.LBB0_414:
	ds_read_b128 v[146:149], v141
	ds_read_b128 v[150:153], v141 offset:1024
	ds_read_b128 v[154:157], v141 offset:2048
	ds_read_b128 v[158:161], v141 offset:3072
	ds_read_b128 v[162:165], v142
	ds_read_b128 v[166:169], v142 offset:1024
	ds_read_b128 v[170:173], v142 offset:2048
	ds_read_b128 v[176:179], v142 offset:3072
	s_add_u32 s46, s44, 0xfff80080
	s_addc_u32 s47, s45, -1
	s_cmp_eq_u32 s82, 4
	s_cselect_b32 s49, s41, s47
	s_cselect_b32 s48, s40, s46
	s_cselect_b32 s47, s43, s81
	s_cselect_b32 s46, s42, s39
	s_mov_b32 m0, s64
	ds_read_b128 v[180:183], v143
	ds_read_b128 v[184:187], v143 offset:1024
	ds_read_b128 v[188:191], v143 offset:2048
	ds_read_b128 v[192:195], v143 offset:3072
	ds_read_b128 v[196:199], v143 offset:4096
	ds_read_b128 v[200:203], v143 offset:5120
	ds_read_b128 v[204:207], v143 offset:6144
	ds_read_b128 v[208:211], v143 offset:7168
	global_load_lds_dwordx4 v136, s[44:45]
	s_mov_b32 m0, s65
	s_nop 0
	global_load_lds_dwordx4 v138, s[44:45]
	s_waitcnt vmcnt(8)
	s_waitcnt lgkmcnt(0)
	s_barrier
	s_setprio 1
	s_waitcnt lgkmcnt(0)
	v_mfma_f32_16x16x32_bf16 v[124:127], v[146:149], v[180:183], v[124:127]
	v_mfma_f32_16x16x32_bf16 v[124:127], v[150:153], v[184:187], v[124:127]
	v_mfma_f32_16x16x32_bf16 v[120:123], v[154:157], v[180:183], v[120:123]
	v_mfma_f32_16x16x32_bf16 v[120:123], v[158:161], v[184:187], v[120:123]
	v_mfma_f32_16x16x32_bf16 v[116:119], v[146:149], v[188:191], v[116:119]
	v_mfma_f32_16x16x32_bf16 v[116:119], v[150:153], v[192:195], v[116:119]
	v_mfma_f32_16x16x32_bf16 v[112:115], v[154:157], v[188:191], v[112:115]
	v_mfma_f32_16x16x32_bf16 v[112:115], v[158:161], v[192:195], v[112:115]
	v_mfma_f32_16x16x32_bf16 v[100:103], v[146:149], v[196:199], v[100:103]
	v_mfma_f32_16x16x32_bf16 v[100:103], v[150:153], v[200:203], v[100:103]
	v_mfma_f32_16x16x32_bf16 v[96:99], v[154:157], v[196:199], v[96:99]
	v_mfma_f32_16x16x32_bf16 v[96:99], v[158:161], v[200:203], v[96:99]
	v_mfma_f32_16x16x32_bf16 v[84:87], v[146:149], v[204:207], v[84:87]
	v_mfma_f32_16x16x32_bf16 v[84:87], v[150:153], v[208:211], v[84:87]
	v_mfma_f32_16x16x32_bf16 v[80:83], v[154:157], v[204:207], v[80:83]
	v_mfma_f32_16x16x32_bf16 v[80:83], v[158:161], v[208:211], v[80:83]
	s_setprio 0
	s_setprio 1
	v_mfma_f32_16x16x32_bf16 v[108:111], v[162:165], v[180:183], v[108:111]
	v_mfma_f32_16x16x32_bf16 v[108:111], v[166:169], v[184:187], v[108:111]
	v_mfma_f32_16x16x32_bf16 v[104:107], v[170:173], v[180:183], v[104:107]
	v_mfma_f32_16x16x32_bf16 v[104:107], v[176:179], v[184:187], v[104:107]
	v_mfma_f32_16x16x32_bf16 v[92:95], v[162:165], v[188:191], v[92:95]
	v_mfma_f32_16x16x32_bf16 v[92:95], v[166:169], v[192:195], v[92:95]
	v_mfma_f32_16x16x32_bf16 v[88:91], v[170:173], v[188:191], v[88:91]
	v_mfma_f32_16x16x32_bf16 v[88:91], v[176:179], v[192:195], v[88:91]
	v_mfma_f32_16x16x32_bf16 v[76:79], v[162:165], v[196:199], v[76:79]
	v_mfma_f32_16x16x32_bf16 v[76:79], v[166:169], v[200:203], v[76:79]
	v_mfma_f32_16x16x32_bf16 v[72:75], v[170:173], v[196:199], v[72:75]
	v_mfma_f32_16x16x32_bf16 v[72:75], v[176:179], v[200:203], v[72:75]
	v_mfma_f32_16x16x32_bf16 v[68:71], v[162:165], v[204:207], v[68:71]
	v_mfma_f32_16x16x32_bf16 v[68:71], v[166:169], v[208:211], v[68:71]
	v_mfma_f32_16x16x32_bf16 v[64:67], v[170:173], v[204:207], v[64:67]
	v_mfma_f32_16x16x32_bf16 v[64:67], v[176:179], v[208:211], v[64:67]
	s_setprio 0
	s_barrier
	s_mov_b32 m0, s68
	s_add_u32 s98, s46, s24
	s_addc_u32 s99, s47, s25
	s_add_u32 s84, s46, 0x80000
	ds_read_b128 v[180:183], v143 offset:16384
	ds_read_b128 v[184:187], v143 offset:17408
	ds_read_b128 v[188:191], v143 offset:18432
	ds_read_b128 v[192:195], v143 offset:19456
	ds_read_b128 v[196:199], v143 offset:20480
	ds_read_b128 v[200:203], v143 offset:21504
	ds_read_b128 v[204:207], v143 offset:22528
	ds_read_b128 v[208:211], v143 offset:23552
	global_load_lds_dwordx4 v132, s[46:47]
	s_mov_b32 m0, s69
	s_addc_u32 s85, s47, 0
	global_load_lds_dwordx4 v128, s[46:47]
	s_mov_b32 m0, s77
	s_nop 0
	global_load_lds_dwordx4 v132, s[84:85]
	s_add_i32 m0, s77, 0x2000
	s_nop 0
	global_load_lds_dwordx4 v128, s[84:85]
	s_add_u32 s100, s48, s24
	s_addc_u32 s101, s49, s25
	s_mov_b32 m0, s22
	s_nop 0
	global_load_lds_dwordx4 v134, s[48:49]
	s_mov_b32 m0, s23
	s_nop 0
	global_load_lds_dwordx4 v130, s[48:49]
	s_waitcnt vmcnt(8)
	s_waitcnt lgkmcnt(0)
	s_barrier
	s_setprio 1
	s_waitcnt lgkmcnt(0)
	v_mfma_f32_16x16x32_bf16 v[60:63], v[146:149], v[180:183], v[60:63]
	v_mfma_f32_16x16x32_bf16 v[60:63], v[150:153], v[184:187], v[60:63]
	v_mfma_f32_16x16x32_bf16 v[56:59], v[154:157], v[180:183], v[56:59]
	v_mfma_f32_16x16x32_bf16 v[56:59], v[158:161], v[184:187], v[56:59]
	v_mfma_f32_16x16x32_bf16 v[52:55], v[146:149], v[188:191], v[52:55]
	v_mfma_f32_16x16x32_bf16 v[52:55], v[150:153], v[192:195], v[52:55]
	v_mfma_f32_16x16x32_bf16 v[48:51], v[154:157], v[188:191], v[48:51]
	v_mfma_f32_16x16x32_bf16 v[48:51], v[158:161], v[192:195], v[48:51]
	v_mfma_f32_16x16x32_bf16 v[36:39], v[146:149], v[196:199], v[36:39]
	v_mfma_f32_16x16x32_bf16 v[36:39], v[150:153], v[200:203], v[36:39]
	v_mfma_f32_16x16x32_bf16 v[32:35], v[154:157], v[196:199], v[32:35]
	v_mfma_f32_16x16x32_bf16 v[32:35], v[158:161], v[200:203], v[32:35]
	v_mfma_f32_16x16x32_bf16 v[20:23], v[146:149], v[204:207], v[20:23]
	v_mfma_f32_16x16x32_bf16 v[20:23], v[150:153], v[208:211], v[20:23]
	v_mfma_f32_16x16x32_bf16 v[16:19], v[154:157], v[204:207], v[16:19]
	v_mfma_f32_16x16x32_bf16 v[16:19], v[158:161], v[208:211], v[16:19]
	s_setprio 0
	s_setprio 1
	v_mfma_f32_16x16x32_bf16 v[44:47], v[162:165], v[180:183], v[44:47]
	v_mfma_f32_16x16x32_bf16 v[44:47], v[166:169], v[184:187], v[44:47]
	v_mfma_f32_16x16x32_bf16 v[40:43], v[170:173], v[180:183], v[40:43]
	v_mfma_f32_16x16x32_bf16 v[40:43], v[176:179], v[184:187], v[40:43]
	v_mfma_f32_16x16x32_bf16 v[28:31], v[162:165], v[188:191], v[28:31]
	v_mfma_f32_16x16x32_bf16 v[28:31], v[166:169], v[192:195], v[28:31]
	v_mfma_f32_16x16x32_bf16 v[24:27], v[170:173], v[188:191], v[24:27]
	v_mfma_f32_16x16x32_bf16 v[24:27], v[176:179], v[192:195], v[24:27]
	v_mfma_f32_16x16x32_bf16 v[12:15], v[162:165], v[196:199], v[12:15]
	v_mfma_f32_16x16x32_bf16 v[12:15], v[166:169], v[200:203], v[12:15]
	v_mfma_f32_16x16x32_bf16 v[8:11], v[170:173], v[196:199], v[8:11]
	v_mfma_f32_16x16x32_bf16 v[8:11], v[176:179], v[200:203], v[8:11]
	v_mfma_f32_16x16x32_bf16 v[4:7], v[162:165], v[204:207], v[4:7]
	v_mfma_f32_16x16x32_bf16 v[4:7], v[166:169], v[208:211], v[4:7]
	v_mfma_f32_16x16x32_bf16 v[0:3], v[170:173], v[204:207], v[0:3]
	v_mfma_f32_16x16x32_bf16 v[0:3], v[176:179], v[208:211], v[0:3]
	s_setprio 0
	s_barrier
	s_add_i32 s83, 0, 0x18000
	v_add_u32_e32 v145, s83, v140
	s_add_i32 s84, 0, 0x1c000
	ds_read_b128 v[146:149], v145
	ds_read_b128 v[150:153], v145 offset:1024
	ds_read_b128 v[154:157], v145 offset:2048
	ds_read_b128 v[158:161], v145 offset:3072
	v_add_u32_e32 v145, s84, v140
	ds_read_b128 v[162:165], v145
	ds_read_b128 v[166:169], v145 offset:1024
	ds_read_b128 v[170:173], v145 offset:2048
	ds_read_b128 v[176:179], v145 offset:3072
	s_add_u32 s48, s48, 0x80000
	s_addc_u32 s49, s49, 0
	s_mov_b32 m0, s33
	ds_read_b128 v[180:183], v143 offset:32768
	ds_read_b128 v[184:187], v143 offset:33792
	ds_read_b128 v[188:191], v143 offset:34816
	ds_read_b128 v[192:195], v143 offset:35840
	ds_read_b128 v[196:199], v143 offset:36864
	ds_read_b128 v[200:203], v143 offset:37888
	ds_read_b128 v[204:207], v143 offset:38912
	ds_read_b128 v[208:211], v143 offset:39936
	global_load_lds_dwordx4 v134, s[48:49]
	s_mov_b32 m0, s50
	s_nop 0
	global_load_lds_dwordx4 v130, s[48:49]
	s_waitcnt vmcnt(8)
	s_waitcnt lgkmcnt(0)
	s_barrier
	s_setprio 1
	s_waitcnt lgkmcnt(0)
	v_mfma_f32_16x16x32_bf16 v[124:127], v[146:149], v[180:183], v[124:127]
	v_mfma_f32_16x16x32_bf16 v[124:127], v[150:153], v[184:187], v[124:127]
	v_mfma_f32_16x16x32_bf16 v[120:123], v[154:157], v[180:183], v[120:123]
	v_mfma_f32_16x16x32_bf16 v[120:123], v[158:161], v[184:187], v[120:123]
	v_mfma_f32_16x16x32_bf16 v[116:119], v[146:149], v[188:191], v[116:119]
	v_mfma_f32_16x16x32_bf16 v[116:119], v[150:153], v[192:195], v[116:119]
	v_mfma_f32_16x16x32_bf16 v[112:115], v[154:157], v[188:191], v[112:115]
	v_mfma_f32_16x16x32_bf16 v[112:115], v[158:161], v[192:195], v[112:115]
	v_mfma_f32_16x16x32_bf16 v[100:103], v[146:149], v[196:199], v[100:103]
	v_mfma_f32_16x16x32_bf16 v[100:103], v[150:153], v[200:203], v[100:103]
	v_mfma_f32_16x16x32_bf16 v[96:99], v[154:157], v[196:199], v[96:99]
	v_mfma_f32_16x16x32_bf16 v[96:99], v[158:161], v[200:203], v[96:99]
	v_mfma_f32_16x16x32_bf16 v[84:87], v[146:149], v[204:207], v[84:87]
	v_mfma_f32_16x16x32_bf16 v[84:87], v[150:153], v[208:211], v[84:87]
	v_mfma_f32_16x16x32_bf16 v[80:83], v[154:157], v[204:207], v[80:83]
	v_mfma_f32_16x16x32_bf16 v[80:83], v[158:161], v[208:211], v[80:83]
	s_setprio 0
	s_setprio 1
	v_mfma_f32_16x16x32_bf16 v[108:111], v[162:165], v[180:183], v[108:111]
	v_mfma_f32_16x16x32_bf16 v[108:111], v[166:169], v[184:187], v[108:111]
	v_mfma_f32_16x16x32_bf16 v[104:107], v[170:173], v[180:183], v[104:107]
	v_mfma_f32_16x16x32_bf16 v[104:107], v[176:179], v[184:187], v[104:107]
	v_mfma_f32_16x16x32_bf16 v[92:95], v[162:165], v[188:191], v[92:95]
	v_mfma_f32_16x16x32_bf16 v[92:95], v[166:169], v[192:195], v[92:95]
	v_mfma_f32_16x16x32_bf16 v[88:91], v[170:173], v[188:191], v[88:91]
	v_mfma_f32_16x16x32_bf16 v[88:91], v[176:179], v[192:195], v[88:91]
	v_mfma_f32_16x16x32_bf16 v[76:79], v[162:165], v[196:199], v[76:79]
	v_mfma_f32_16x16x32_bf16 v[76:79], v[166:169], v[200:203], v[76:79]
	v_mfma_f32_16x16x32_bf16 v[72:75], v[170:173], v[196:199], v[72:75]
	v_mfma_f32_16x16x32_bf16 v[72:75], v[176:179], v[200:203], v[72:75]
	v_mfma_f32_16x16x32_bf16 v[68:71], v[162:165], v[204:207], v[68:71]
	v_mfma_f32_16x16x32_bf16 v[68:71], v[166:169], v[208:211], v[68:71]
	v_mfma_f32_16x16x32_bf16 v[64:67], v[170:173], v[204:207], v[64:67]
	v_mfma_f32_16x16x32_bf16 v[64:67], v[176:179], v[208:211], v[64:67]
	s_setprio 0
	s_barrier
	s_add_i32 s48, s83, s10
	s_mov_b32 m0, s48
	ds_read_b128 v[180:183], v143 offset:49152
	ds_read_b128 v[184:187], v143 offset:50176
	ds_read_b128 v[188:191], v143 offset:51200
	ds_read_b128 v[192:195], v143 offset:52224
	ds_read_b128 v[196:199], v143 offset:53248
	ds_read_b128 v[200:203], v143 offset:54272
	ds_read_b128 v[204:207], v143 offset:55296
	ds_read_b128 v[208:211], v143 offset:56320
	global_load_lds_dwordx4 v132, s[98:99]
	s_add_i32 m0, s48, 0x2000
	s_add_u32 s46, s46, 0x80080
	s_addc_u32 s47, s47, 0
	s_add_i32 s48, s84, s10
	global_load_lds_dwordx4 v128, s[98:99]
	s_mov_b32 m0, s48
	s_nop 0
	global_load_lds_dwordx4 v132, s[46:47]
	s_add_i32 m0, s48, 0x2000
	s_nop 0
	global_load_lds_dwordx4 v128, s[46:47]
	s_mov_b32 m0, s62
	s_nop 0
	global_load_lds_dwordx4 v134, s[100:101]
	s_mov_b32 m0, s63
	s_nop 0
	global_load_lds_dwordx4 v130, s[100:101]
	s_waitcnt vmcnt(8)
	s_waitcnt lgkmcnt(0)
	s_barrier
	s_setprio 1
	s_waitcnt lgkmcnt(0)
	v_mfma_f32_16x16x32_bf16 v[60:63], v[146:149], v[180:183], v[60:63]
	v_mfma_f32_16x16x32_bf16 v[60:63], v[150:153], v[184:187], v[60:63]
	v_mfma_f32_16x16x32_bf16 v[56:59], v[154:157], v[180:183], v[56:59]
	v_mfma_f32_16x16x32_bf16 v[56:59], v[158:161], v[184:187], v[56:59]
	v_mfma_f32_16x16x32_bf16 v[52:55], v[146:149], v[188:191], v[52:55]
	v_mfma_f32_16x16x32_bf16 v[52:55], v[150:153], v[192:195], v[52:55]
	v_mfma_f32_16x16x32_bf16 v[48:51], v[154:157], v[188:191], v[48:51]
	v_mfma_f32_16x16x32_bf16 v[48:51], v[158:161], v[192:195], v[48:51]
	v_mfma_f32_16x16x32_bf16 v[36:39], v[146:149], v[196:199], v[36:39]
	v_mfma_f32_16x16x32_bf16 v[36:39], v[150:153], v[200:203], v[36:39]
	v_mfma_f32_16x16x32_bf16 v[32:35], v[154:157], v[196:199], v[32:35]
	v_mfma_f32_16x16x32_bf16 v[32:35], v[158:161], v[200:203], v[32:35]
	v_mfma_f32_16x16x32_bf16 v[20:23], v[146:149], v[204:207], v[20:23]
	v_mfma_f32_16x16x32_bf16 v[20:23], v[150:153], v[208:211], v[20:23]
	v_mfma_f32_16x16x32_bf16 v[16:19], v[154:157], v[204:207], v[16:19]
	v_mfma_f32_16x16x32_bf16 v[16:19], v[158:161], v[208:211], v[16:19]
	s_setprio 0
	s_setprio 1
	v_mfma_f32_16x16x32_bf16 v[44:47], v[162:165], v[180:183], v[44:47]
	v_mfma_f32_16x16x32_bf16 v[44:47], v[166:169], v[184:187], v[44:47]
	v_mfma_f32_16x16x32_bf16 v[40:43], v[170:173], v[180:183], v[40:43]
	v_mfma_f32_16x16x32_bf16 v[40:43], v[176:179], v[184:187], v[40:43]
	v_mfma_f32_16x16x32_bf16 v[28:31], v[162:165], v[188:191], v[28:31]
	v_mfma_f32_16x16x32_bf16 v[28:31], v[166:169], v[192:195], v[28:31]
	v_mfma_f32_16x16x32_bf16 v[24:27], v[170:173], v[188:191], v[24:27]
	v_mfma_f32_16x16x32_bf16 v[24:27], v[176:179], v[192:195], v[24:27]
	v_mfma_f32_16x16x32_bf16 v[12:15], v[162:165], v[196:199], v[12:15]
	v_mfma_f32_16x16x32_bf16 v[12:15], v[166:169], v[200:203], v[12:15]
	v_mfma_f32_16x16x32_bf16 v[8:11], v[170:173], v[196:199], v[8:11]
	v_mfma_f32_16x16x32_bf16 v[8:11], v[176:179], v[200:203], v[8:11]
	v_mfma_f32_16x16x32_bf16 v[4:7], v[162:165], v[204:207], v[4:7]
	v_mfma_f32_16x16x32_bf16 v[4:7], v[166:169], v[208:211], v[4:7]
	v_mfma_f32_16x16x32_bf16 v[0:3], v[170:173], v[204:207], v[0:3]
	v_mfma_f32_16x16x32_bf16 v[0:3], v[176:179], v[208:211], v[0:3]
	s_setprio 0
	s_barrier
	s_add_i32 s82, s82, 2
	s_add_u32 s44, s44, 0x100
	s_addc_u32 s45, s45, 0
	s_add_u32 s39, s39, 0x100
	s_addc_u32 s81, s81, 0
	s_cmp_gt_u32 s82, 5
	s_cbranch_scc0 .LBB0_414
	s_and_b64 vcc, exec, s[36:37]
	s_cbranch_vccz .LBB0_417
	s_barrier

.LBB0_428:
	ds_read_b128 v[148:151], v143
	ds_read_b128 v[152:155], v143 offset:1024
	ds_read_b128 v[156:159], v143 offset:2048
	ds_read_b128 v[160:163], v143 offset:3072
	ds_read_b128 v[164:167], v144
	ds_read_b128 v[168:171], v144 offset:1024
	ds_read_b128 v[176:179], v144 offset:2048
	ds_read_b128 v[180:183], v144 offset:3072
	s_add_u32 s48, s46, 0xfff80080
	s_addc_u32 s49, s47, -1
	s_cmp_eq_u32 s83, 4
	s_cselect_b32 s51, s77, s49
	s_cselect_b32 s50, s78, s48
	s_cselect_b32 s49, s79, s82
	s_cselect_b32 s48, s80, s81
	s_add_i32 m0, s15, 0xc000
	ds_read_b128 v[184:187], v145
	ds_read_b128 v[188:191], v145 offset:1024
	ds_read_b128 v[192:195], v145 offset:2048
	ds_read_b128 v[196:199], v145 offset:3072
	ds_read_b128 v[200:203], v145 offset:4096
	ds_read_b128 v[204:207], v145 offset:5120
	ds_read_b128 v[208:211], v145 offset:6144
	ds_read_b128 v[212:215], v145 offset:7168
	global_load_lds_dwordx4 v138, s[46:47]
	s_add_i32 m0, s15, 0xe000
	s_nop 0
	global_load_lds_dwordx4 v140, s[46:47]
	s_waitcnt vmcnt(8)
	s_waitcnt lgkmcnt(0)
	s_barrier
	s_setprio 1
	s_waitcnt lgkmcnt(0)
	v_mfma_f32_16x16x32_bf16 v[124:127], v[148:151], v[184:187], v[124:127]
	v_mfma_f32_16x16x32_bf16 v[124:127], v[152:155], v[188:191], v[124:127]
	v_mfma_f32_16x16x32_bf16 v[120:123], v[156:159], v[184:187], v[120:123]
	v_mfma_f32_16x16x32_bf16 v[120:123], v[160:163], v[188:191], v[120:123]
	v_mfma_f32_16x16x32_bf16 v[116:119], v[148:151], v[192:195], v[116:119]
	v_mfma_f32_16x16x32_bf16 v[116:119], v[152:155], v[196:199], v[116:119]
	v_mfma_f32_16x16x32_bf16 v[112:115], v[156:159], v[192:195], v[112:115]
	v_mfma_f32_16x16x32_bf16 v[112:115], v[160:163], v[196:199], v[112:115]
	v_mfma_f32_16x16x32_bf16 v[100:103], v[148:151], v[200:203], v[100:103]
	v_mfma_f32_16x16x32_bf16 v[100:103], v[152:155], v[204:207], v[100:103]
	v_mfma_f32_16x16x32_bf16 v[96:99], v[156:159], v[200:203], v[96:99]
	v_mfma_f32_16x16x32_bf16 v[96:99], v[160:163], v[204:207], v[96:99]
	v_mfma_f32_16x16x32_bf16 v[84:87], v[148:151], v[208:211], v[84:87]
	v_mfma_f32_16x16x32_bf16 v[84:87], v[152:155], v[212:215], v[84:87]
	v_mfma_f32_16x16x32_bf16 v[80:83], v[156:159], v[208:211], v[80:83]
	v_mfma_f32_16x16x32_bf16 v[80:83], v[160:163], v[212:215], v[80:83]
	s_setprio 0
	s_setprio 1
	v_mfma_f32_16x16x32_bf16 v[108:111], v[164:167], v[184:187], v[108:111]
	v_mfma_f32_16x16x32_bf16 v[108:111], v[168:171], v[188:191], v[108:111]
	v_mfma_f32_16x16x32_bf16 v[104:107], v[176:179], v[184:187], v[104:107]
	v_mfma_f32_16x16x32_bf16 v[104:107], v[180:183], v[188:191], v[104:107]
	v_mfma_f32_16x16x32_bf16 v[92:95], v[164:167], v[192:195], v[92:95]
	v_mfma_f32_16x16x32_bf16 v[92:95], v[168:171], v[196:199], v[92:95]
	v_mfma_f32_16x16x32_bf16 v[88:91], v[176:179], v[192:195], v[88:91]
	v_mfma_f32_16x16x32_bf16 v[88:91], v[180:183], v[196:199], v[88:91]
	v_mfma_f32_16x16x32_bf16 v[76:79], v[164:167], v[200:203], v[76:79]
	v_mfma_f32_16x16x32_bf16 v[76:79], v[168:171], v[204:207], v[76:79]
	v_mfma_f32_16x16x32_bf16 v[72:75], v[176:179], v[200:203], v[72:75]
	v_mfma_f32_16x16x32_bf16 v[72:75], v[180:183], v[204:207], v[72:75]
	v_mfma_f32_16x16x32_bf16 v[68:71], v[164:167], v[208:211], v[68:71]
	v_mfma_f32_16x16x32_bf16 v[68:71], v[168:171], v[212:215], v[68:71]
	v_mfma_f32_16x16x32_bf16 v[64:67], v[176:179], v[208:211], v[64:67]
	v_mfma_f32_16x16x32_bf16 v[64:67], v[180:183], v[212:215], v[64:67]
	s_setprio 0
	s_barrier
	s_add_i32 s84, s68, s10
	s_add_u32 s98, s48, s38
	s_addc_u32 s99, s49, s39
	s_mov_b32 m0, s84
	ds_read_b128 v[184:187], v145 offset:16384
	ds_read_b128 v[188:191], v145 offset:17408
	ds_read_b128 v[192:195], v145 offset:18432
	ds_read_b128 v[196:199], v145 offset:19456
	ds_read_b128 v[200:203], v145 offset:20480
	ds_read_b128 v[204:207], v145 offset:21504
	ds_read_b128 v[208:211], v145 offset:22528
	ds_read_b128 v[212:215], v145 offset:23552
	global_load_lds_dwordx4 v132, s[48:49]
	s_add_i32 m0, s84, 0x2000
	s_add_u32 s84, s48, 0x80000
	s_addc_u32 s85, s49, 0
	s_add_i32 s86, s69, s10
	global_load_lds_dwordx4 v128, s[48:49]
	s_mov_b32 m0, s86
	s_nop 0
	global_load_lds_dwordx4 v132, s[84:85]
	s_add_i32 m0, s86, 0x2000
	s_nop 0
	global_load_lds_dwordx4 v128, s[84:85]
	s_add_u32 s100, s50, s38
	s_addc_u32 s101, s51, s39
	s_mov_b32 m0, s15
	s_nop 0
	global_load_lds_dwordx4 v134, s[50:51]
	s_mov_b32 m0, s22
	s_nop 0
	global_load_lds_dwordx4 v130, s[50:51]
	s_waitcnt vmcnt(8)
	s_waitcnt lgkmcnt(0)
	s_barrier
	s_setprio 1
	s_waitcnt lgkmcnt(0)
	v_mfma_f32_16x16x32_bf16 v[60:63], v[148:151], v[184:187], v[60:63]
	v_mfma_f32_16x16x32_bf16 v[60:63], v[152:155], v[188:191], v[60:63]
	v_mfma_f32_16x16x32_bf16 v[56:59], v[156:159], v[184:187], v[56:59]
	v_mfma_f32_16x16x32_bf16 v[56:59], v[160:163], v[188:191], v[56:59]
	v_mfma_f32_16x16x32_bf16 v[52:55], v[148:151], v[192:195], v[52:55]
	v_mfma_f32_16x16x32_bf16 v[52:55], v[152:155], v[196:199], v[52:55]
	v_mfma_f32_16x16x32_bf16 v[48:51], v[156:159], v[192:195], v[48:51]
	v_mfma_f32_16x16x32_bf16 v[48:51], v[160:163], v[196:199], v[48:51]
	v_mfma_f32_16x16x32_bf16 v[36:39], v[148:151], v[200:203], v[36:39]
	v_mfma_f32_16x16x32_bf16 v[36:39], v[152:155], v[204:207], v[36:39]
	v_mfma_f32_16x16x32_bf16 v[32:35], v[156:159], v[200:203], v[32:35]
	v_mfma_f32_16x16x32_bf16 v[32:35], v[160:163], v[204:207], v[32:35]
	v_mfma_f32_16x16x32_bf16 v[20:23], v[148:151], v[208:211], v[20:23]
	v_mfma_f32_16x16x32_bf16 v[20:23], v[152:155], v[212:215], v[20:23]
	v_mfma_f32_16x16x32_bf16 v[16:19], v[156:159], v[208:211], v[16:19]
	v_mfma_f32_16x16x32_bf16 v[16:19], v[160:163], v[212:215], v[16:19]
	s_setprio 0
	s_setprio 1
	v_mfma_f32_16x16x32_bf16 v[44:47], v[164:167], v[184:187], v[44:47]
	v_mfma_f32_16x16x32_bf16 v[44:47], v[168:171], v[188:191], v[44:47]
	v_mfma_f32_16x16x32_bf16 v[40:43], v[176:179], v[184:187], v[40:43]
	v_mfma_f32_16x16x32_bf16 v[40:43], v[180:183], v[188:191], v[40:43]
	v_mfma_f32_16x16x32_bf16 v[28:31], v[164:167], v[192:195], v[28:31]
	v_mfma_f32_16x16x32_bf16 v[28:31], v[168:171], v[196:199], v[28:31]
	v_mfma_f32_16x16x32_bf16 v[24:27], v[176:179], v[192:195], v[24:27]
	v_mfma_f32_16x16x32_bf16 v[24:27], v[180:183], v[196:199], v[24:27]
	v_mfma_f32_16x16x32_bf16 v[12:15], v[164:167], v[200:203], v[12:15]
	v_mfma_f32_16x16x32_bf16 v[12:15], v[168:171], v[204:207], v[12:15]
	v_mfma_f32_16x16x32_bf16 v[8:11], v[176:179], v[200:203], v[8:11]
	v_mfma_f32_16x16x32_bf16 v[8:11], v[180:183], v[204:207], v[8:11]
	v_mfma_f32_16x16x32_bf16 v[4:7], v[164:167], v[208:211], v[4:7]
	v_mfma_f32_16x16x32_bf16 v[4:7], v[168:171], v[212:215], v[4:7]
	v_mfma_f32_16x16x32_bf16 v[0:3], v[176:179], v[208:211], v[0:3]
	v_mfma_f32_16x16x32_bf16 v[0:3], v[180:183], v[212:215], v[0:3]
	s_setprio 0
	s_barrier
	s_add_i32 s84, 0, 0x18000
	v_add_u32_e32 v136, s84, v142
	s_add_i32 s85, 0, 0x1c000
	ds_read_b128 v[148:151], v136
	ds_read_b128 v[152:155], v136 offset:1024
	ds_read_b128 v[156:159], v136 offset:2048
	ds_read_b128 v[160:163], v136 offset:3072
	v_add_u32_e32 v136, s85, v142
	ds_read_b128 v[164:167], v136
	ds_read_b128 v[168:171], v136 offset:1024
	ds_read_b128 v[176:179], v136 offset:2048
	ds_read_b128 v[180:183], v136 offset:3072
	s_add_u32 s50, s50, 0x80000
	s_addc_u32 s51, s51, 0
	s_mov_b32 m0, s23
	ds_read_b128 v[184:187], v145 offset:32768
	ds_read_b128 v[188:191], v145 offset:33792
	ds_read_b128 v[192:195], v145 offset:34816
	ds_read_b128 v[196:199], v145 offset:35840
	ds_read_b128 v[200:203], v145 offset:36864
	ds_read_b128 v[204:207], v145 offset:37888
	ds_read_b128 v[208:211], v145 offset:38912
	ds_read_b128 v[212:215], v145 offset:39936
	global_load_lds_dwordx4 v134, s[50:51]
	s_mov_b32 m0, s33
	s_nop 0
	global_load_lds_dwordx4 v130, s[50:51]
	s_waitcnt vmcnt(8)
	s_waitcnt lgkmcnt(0)
	s_barrier
	s_setprio 1
	s_waitcnt lgkmcnt(0)
	v_mfma_f32_16x16x32_bf16 v[124:127], v[148:151], v[184:187], v[124:127]
	v_mfma_f32_16x16x32_bf16 v[124:127], v[152:155], v[188:191], v[124:127]
	v_mfma_f32_16x16x32_bf16 v[120:123], v[156:159], v[184:187], v[120:123]
	v_mfma_f32_16x16x32_bf16 v[120:123], v[160:163], v[188:191], v[120:123]
	v_mfma_f32_16x16x32_bf16 v[116:119], v[148:151], v[192:195], v[116:119]
	v_mfma_f32_16x16x32_bf16 v[116:119], v[152:155], v[196:199], v[116:119]
	v_mfma_f32_16x16x32_bf16 v[112:115], v[156:159], v[192:195], v[112:115]
	v_mfma_f32_16x16x32_bf16 v[112:115], v[160:163], v[196:199], v[112:115]
	v_mfma_f32_16x16x32_bf16 v[100:103], v[148:151], v[200:203], v[100:103]
	v_mfma_f32_16x16x32_bf16 v[100:103], v[152:155], v[204:207], v[100:103]
	v_mfma_f32_16x16x32_bf16 v[96:99], v[156:159], v[200:203], v[96:99]
	v_mfma_f32_16x16x32_bf16 v[96:99], v[160:163], v[204:207], v[96:99]
	v_mfma_f32_16x16x32_bf16 v[84:87], v[148:151], v[208:211], v[84:87]
	v_mfma_f32_16x16x32_bf16 v[84:87], v[152:155], v[212:215], v[84:87]
	v_mfma_f32_16x16x32_bf16 v[80:83], v[156:159], v[208:211], v[80:83]
	v_mfma_f32_16x16x32_bf16 v[80:83], v[160:163], v[212:215], v[80:83]
	s_setprio 0
	s_setprio 1
	v_mfma_f32_16x16x32_bf16 v[108:111], v[164:167], v[184:187], v[108:111]
	v_mfma_f32_16x16x32_bf16 v[108:111], v[168:171], v[188:191], v[108:111]
	v_mfma_f32_16x16x32_bf16 v[104:107], v[176:179], v[184:187], v[104:107]
	v_mfma_f32_16x16x32_bf16 v[104:107], v[180:183], v[188:191], v[104:107]
	v_mfma_f32_16x16x32_bf16 v[92:95], v[164:167], v[192:195], v[92:95]
	v_mfma_f32_16x16x32_bf16 v[92:95], v[168:171], v[196:199], v[92:95]
	v_mfma_f32_16x16x32_bf16 v[88:91], v[176:179], v[192:195], v[88:91]
	v_mfma_f32_16x16x32_bf16 v[88:91], v[180:183], v[196:199], v[88:91]
	v_mfma_f32_16x16x32_bf16 v[76:79], v[164:167], v[200:203], v[76:79]
	v_mfma_f32_16x16x32_bf16 v[76:79], v[168:171], v[204:207], v[76:79]
	v_mfma_f32_16x16x32_bf16 v[72:75], v[176:179], v[200:203], v[72:75]
	v_mfma_f32_16x16x32_bf16 v[72:75], v[180:183], v[204:207], v[72:75]
	v_mfma_f32_16x16x32_bf16 v[68:71], v[164:167], v[208:211], v[68:71]
	v_mfma_f32_16x16x32_bf16 v[68:71], v[168:171], v[212:215], v[68:71]
	v_mfma_f32_16x16x32_bf16 v[64:67], v[176:179], v[208:211], v[64:67]
	v_mfma_f32_16x16x32_bf16 v[64:67], v[180:183], v[212:215], v[64:67]
	s_setprio 0
	s_barrier
	s_add_i32 s50, s84, s10
	s_mov_b32 m0, s50
	ds_read_b128 v[184:187], v145 offset:49152
	ds_read_b128 v[188:191], v145 offset:50176
	ds_read_b128 v[192:195], v145 offset:51200
	ds_read_b128 v[196:199], v145 offset:52224
	ds_read_b128 v[200:203], v145 offset:53248
	ds_read_b128 v[204:207], v145 offset:54272
	ds_read_b128 v[208:211], v145 offset:55296
	ds_read_b128 v[212:215], v145 offset:56320
	global_load_lds_dwordx4 v132, s[98:99]
	s_add_i32 m0, s50, 0x2000
	s_add_u32 s48, s48, 0x80080
	s_addc_u32 s49, s49, 0
	s_add_i32 s50, s85, s10
	global_load_lds_dwordx4 v128, s[98:99]
	s_mov_b32 m0, s50
	s_nop 0
	global_load_lds_dwordx4 v132, s[48:49]
	s_add_i32 m0, s50, 0x2000
	s_nop 0
	global_load_lds_dwordx4 v128, s[48:49]
	s_mov_b32 m0, s64
	s_nop 0
	global_load_lds_dwordx4 v134, s[100:101]
	s_mov_b32 m0, s65
	s_nop 0
	global_load_lds_dwordx4 v130, s[100:101]
	s_waitcnt vmcnt(8)
	s_waitcnt lgkmcnt(0)
	s_barrier
	s_setprio 1
	s_waitcnt lgkmcnt(0)
	v_mfma_f32_16x16x32_bf16 v[60:63], v[148:151], v[184:187], v[60:63]
	v_mfma_f32_16x16x32_bf16 v[60:63], v[152:155], v[188:191], v[60:63]
	v_mfma_f32_16x16x32_bf16 v[56:59], v[156:159], v[184:187], v[56:59]
	v_mfma_f32_16x16x32_bf16 v[56:59], v[160:163], v[188:191], v[56:59]
	v_mfma_f32_16x16x32_bf16 v[52:55], v[148:151], v[192:195], v[52:55]
	v_mfma_f32_16x16x32_bf16 v[52:55], v[152:155], v[196:199], v[52:55]
	v_mfma_f32_16x16x32_bf16 v[48:51], v[156:159], v[192:195], v[48:51]
	v_mfma_f32_16x16x32_bf16 v[48:51], v[160:163], v[196:199], v[48:51]
	v_mfma_f32_16x16x32_bf16 v[36:39], v[148:151], v[200:203], v[36:39]
	v_mfma_f32_16x16x32_bf16 v[36:39], v[152:155], v[204:207], v[36:39]
	v_mfma_f32_16x16x32_bf16 v[32:35], v[156:159], v[200:203], v[32:35]
	v_mfma_f32_16x16x32_bf16 v[32:35], v[160:163], v[204:207], v[32:35]
	v_mfma_f32_16x16x32_bf16 v[20:23], v[148:151], v[208:211], v[20:23]
	v_mfma_f32_16x16x32_bf16 v[20:23], v[152:155], v[212:215], v[20:23]
	v_mfma_f32_16x16x32_bf16 v[16:19], v[156:159], v[208:211], v[16:19]
	v_mfma_f32_16x16x32_bf16 v[16:19], v[160:163], v[212:215], v[16:19]
	s_setprio 0
	s_setprio 1
	v_mfma_f32_16x16x32_bf16 v[44:47], v[164:167], v[184:187], v[44:47]
	v_mfma_f32_16x16x32_bf16 v[44:47], v[168:171], v[188:191], v[44:47]
	v_mfma_f32_16x16x32_bf16 v[40:43], v[176:179], v[184:187], v[40:43]
	v_mfma_f32_16x16x32_bf16 v[40:43], v[180:183], v[188:191], v[40:43]
	v_mfma_f32_16x16x32_bf16 v[28:31], v[164:167], v[192:195], v[28:31]
	v_mfma_f32_16x16x32_bf16 v[28:31], v[168:171], v[196:199], v[28:31]
	v_mfma_f32_16x16x32_bf16 v[24:27], v[176:179], v[192:195], v[24:27]
	v_mfma_f32_16x16x32_bf16 v[24:27], v[180:183], v[196:199], v[24:27]
	v_mfma_f32_16x16x32_bf16 v[12:15], v[164:167], v[200:203], v[12:15]
	v_mfma_f32_16x16x32_bf16 v[12:15], v[168:171], v[204:207], v[12:15]
	v_mfma_f32_16x16x32_bf16 v[8:11], v[176:179], v[200:203], v[8:11]
	v_mfma_f32_16x16x32_bf16 v[8:11], v[180:183], v[204:207], v[8:11]
	v_mfma_f32_16x16x32_bf16 v[4:7], v[164:167], v[208:211], v[4:7]
	v_mfma_f32_16x16x32_bf16 v[4:7], v[168:171], v[212:215], v[4:7]
	v_mfma_f32_16x16x32_bf16 v[0:3], v[176:179], v[208:211], v[0:3]
	v_mfma_f32_16x16x32_bf16 v[0:3], v[180:183], v[212:215], v[0:3]
	s_setprio 0
	s_barrier
	s_add_i32 s83, s83, 2
	s_add_u32 s46, s46, 0x100
	s_addc_u32 s47, s47, 0
	s_add_u32 s81, s81, 0x100
	s_addc_u32 s82, s82, 0
	s_cmp_gt_u32 s83, 5
	s_cbranch_scc0 .LBB0_428
	s_and_b64 vcc, exec, s[40:41]
	s_cbranch_vccz .LBB0_431
	s_barrier

.LBB0_502:
	ds_read_b128 v[128:131], v192
	ds_read_b128 v[132:135], v192 offset:1024
	ds_read_b128 v[136:139], v192 offset:2048
	ds_read_b128 v[140:143], v192 offset:3072
	ds_read_b128 v[144:147], v193
	ds_read_b128 v[148:151], v193 offset:1024
	ds_read_b128 v[168:171], v193 offset:2048
	ds_read_b128 v[196:199], v193 offset:3072
	s_add_u32 s62, s60, 0xfff80080
	s_addc_u32 s63, s61, -1
	s_cmp_eq_u32 s76, 28
	s_cselect_b32 s65, s27, s63
	s_cselect_b32 s64, s45, s62
	s_cselect_b32 s63, s43, s75
	s_cselect_b32 s62, s51, s74
	s_add_i32 m0, s1, 0xc000
	ds_read_b128 v[200:203], v194
	ds_read_b128 v[204:207], v194 offset:1024
	ds_read_b128 v[208:211], v194 offset:2048
	ds_read_b128 v[212:215], v194 offset:3072
	ds_read_b128 v[216:219], v194 offset:4096
	ds_read_b128 v[220:223], v194 offset:5120
	ds_read_b128 v[224:227], v194 offset:6144
	ds_read_b128 v[228:231], v194 offset:7168
	global_load_lds_dwordx4 v160, s[60:61]
	s_add_i32 m0, s1, 0xe000
	s_nop 0
	global_load_lds_dwordx4 v162, s[60:61]
	s_waitcnt vmcnt(8)
	s_waitcnt lgkmcnt(0)
	s_barrier
	s_setprio 1
	s_waitcnt lgkmcnt(0)
	v_mfma_f32_16x16x32_bf16 v[124:127], v[128:131], v[200:203], v[124:127]
	v_mfma_f32_16x16x32_bf16 v[124:127], v[132:135], v[204:207], v[124:127]
	v_mfma_f32_16x16x32_bf16 v[120:123], v[136:139], v[200:203], v[120:123]
	v_mfma_f32_16x16x32_bf16 v[120:123], v[140:143], v[204:207], v[120:123]
	v_mfma_f32_16x16x32_bf16 v[108:111], v[128:131], v[208:211], v[108:111]
	v_mfma_f32_16x16x32_bf16 v[108:111], v[132:135], v[212:215], v[108:111]
	v_mfma_f32_16x16x32_bf16 v[104:107], v[136:139], v[208:211], v[104:107]
	v_mfma_f32_16x16x32_bf16 v[104:107], v[140:143], v[212:215], v[104:107]
	v_mfma_f32_16x16x32_bf16 v[92:95], v[128:131], v[216:219], v[92:95]
	v_mfma_f32_16x16x32_bf16 v[92:95], v[132:135], v[220:223], v[92:95]
	v_mfma_f32_16x16x32_bf16 v[88:91], v[136:139], v[216:219], v[88:91]
	v_mfma_f32_16x16x32_bf16 v[88:91], v[140:143], v[220:223], v[88:91]
	v_mfma_f32_16x16x32_bf16 v[76:79], v[128:131], v[224:227], v[76:79]
	v_mfma_f32_16x16x32_bf16 v[76:79], v[132:135], v[228:231], v[76:79]
	v_mfma_f32_16x16x32_bf16 v[72:75], v[136:139], v[224:227], v[72:75]
	v_mfma_f32_16x16x32_bf16 v[72:75], v[140:143], v[228:231], v[72:75]
	s_setprio 0
	s_setprio 1
	v_mfma_f32_16x16x32_bf16 v[116:119], v[144:147], v[200:203], v[116:119]
	v_mfma_f32_16x16x32_bf16 v[116:119], v[148:151], v[204:207], v[116:119]
	v_mfma_f32_16x16x32_bf16 v[112:115], v[168:171], v[200:203], v[112:115]
	v_mfma_f32_16x16x32_bf16 v[112:115], v[196:199], v[204:207], v[112:115]
	v_mfma_f32_16x16x32_bf16 v[100:103], v[144:147], v[208:211], v[100:103]
	v_mfma_f32_16x16x32_bf16 v[100:103], v[148:151], v[212:215], v[100:103]
	v_mfma_f32_16x16x32_bf16 v[96:99], v[168:171], v[208:211], v[96:99]
	v_mfma_f32_16x16x32_bf16 v[96:99], v[196:199], v[212:215], v[96:99]
	v_mfma_f32_16x16x32_bf16 v[84:87], v[144:147], v[216:219], v[84:87]
	v_mfma_f32_16x16x32_bf16 v[84:87], v[148:151], v[220:223], v[84:87]
	v_mfma_f32_16x16x32_bf16 v[80:83], v[168:171], v[216:219], v[80:83]
	v_mfma_f32_16x16x32_bf16 v[80:83], v[196:199], v[220:223], v[80:83]
	v_mfma_f32_16x16x32_bf16 v[68:71], v[144:147], v[224:227], v[68:71]
	v_mfma_f32_16x16x32_bf16 v[68:71], v[148:151], v[228:231], v[68:71]
	v_mfma_f32_16x16x32_bf16 v[64:67], v[168:171], v[224:227], v[64:67]
	v_mfma_f32_16x16x32_bf16 v[64:67], v[196:199], v[228:231], v[64:67]
	s_setprio 0
	s_barrier
	s_add_i32 s77, s69, s0
	s_add_u32 s98, s62, s38
	s_addc_u32 s99, s63, s39
	s_mov_b32 m0, s77
	ds_read_b128 v[200:203], v194 offset:16384
	ds_read_b128 v[204:207], v194 offset:17408
	ds_read_b128 v[208:211], v194 offset:18432
	ds_read_b128 v[212:215], v194 offset:19456
	ds_read_b128 v[216:219], v194 offset:20480
	ds_read_b128 v[220:223], v194 offset:21504
	ds_read_b128 v[224:227], v194 offset:22528
	ds_read_b128 v[228:231], v194 offset:23552
	global_load_lds_dwordx4 v154, s[62:63]
	s_add_i32 m0, s77, 0x2000
	s_add_u32 s78, s62, 0x80000
	s_addc_u32 s79, s63, 0
	s_add_i32 s77, s73, s0
	global_load_lds_dwordx4 v158, s[62:63]
	s_mov_b32 m0, s77
	s_nop 0
	global_load_lds_dwordx4 v154, s[78:79]
	s_add_i32 m0, s77, 0x2000
	s_nop 0
	global_load_lds_dwordx4 v158, s[78:79]
	s_add_u32 s100, s64, s38
	s_addc_u32 s101, s65, s39
	s_mov_b32 m0, s1
	s_nop 0
	global_load_lds_dwordx4 v152, s[64:65]
	s_mov_b32 m0, s10
	s_nop 0
	global_load_lds_dwordx4 v156, s[64:65]
	s_waitcnt vmcnt(8)
	s_waitcnt lgkmcnt(0)
	s_barrier
	s_setprio 1
	s_waitcnt lgkmcnt(0)
	v_mfma_f32_16x16x32_bf16 v[60:63], v[128:131], v[200:203], v[60:63]
	v_mfma_f32_16x16x32_bf16 v[60:63], v[132:135], v[204:207], v[60:63]
	v_mfma_f32_16x16x32_bf16 v[56:59], v[136:139], v[200:203], v[56:59]
	v_mfma_f32_16x16x32_bf16 v[56:59], v[140:143], v[204:207], v[56:59]
	v_mfma_f32_16x16x32_bf16 v[44:47], v[128:131], v[208:211], v[44:47]
	v_mfma_f32_16x16x32_bf16 v[44:47], v[132:135], v[212:215], v[44:47]
	v_mfma_f32_16x16x32_bf16 v[40:43], v[136:139], v[208:211], v[40:43]
	v_mfma_f32_16x16x32_bf16 v[40:43], v[140:143], v[212:215], v[40:43]
	v_mfma_f32_16x16x32_bf16 v[28:31], v[128:131], v[216:219], v[28:31]
	v_mfma_f32_16x16x32_bf16 v[28:31], v[132:135], v[220:223], v[28:31]
	v_mfma_f32_16x16x32_bf16 v[24:27], v[136:139], v[216:219], v[24:27]
	v_mfma_f32_16x16x32_bf16 v[24:27], v[140:143], v[220:223], v[24:27]
	v_mfma_f32_16x16x32_bf16 v[12:15], v[128:131], v[224:227], v[12:15]
	v_mfma_f32_16x16x32_bf16 v[12:15], v[132:135], v[228:231], v[12:15]
	v_mfma_f32_16x16x32_bf16 v[8:11], v[136:139], v[224:227], v[8:11]
	v_mfma_f32_16x16x32_bf16 v[8:11], v[140:143], v[228:231], v[8:11]
	s_setprio 0
	s_setprio 1
	v_mfma_f32_16x16x32_bf16 v[52:55], v[144:147], v[200:203], v[52:55]
	v_mfma_f32_16x16x32_bf16 v[52:55], v[148:151], v[204:207], v[52:55]
	v_mfma_f32_16x16x32_bf16 v[48:51], v[168:171], v[200:203], v[48:51]
	v_mfma_f32_16x16x32_bf16 v[48:51], v[196:199], v[204:207], v[48:51]
	v_mfma_f32_16x16x32_bf16 v[36:39], v[144:147], v[208:211], v[36:39]
	v_mfma_f32_16x16x32_bf16 v[36:39], v[148:151], v[212:215], v[36:39]
	v_mfma_f32_16x16x32_bf16 v[32:35], v[168:171], v[208:211], v[32:35]
	v_mfma_f32_16x16x32_bf16 v[32:35], v[196:199], v[212:215], v[32:35]
	v_mfma_f32_16x16x32_bf16 v[20:23], v[144:147], v[216:219], v[20:23]
	v_mfma_f32_16x16x32_bf16 v[20:23], v[148:151], v[220:223], v[20:23]
	v_mfma_f32_16x16x32_bf16 v[16:19], v[168:171], v[216:219], v[16:19]
	v_mfma_f32_16x16x32_bf16 v[16:19], v[196:199], v[220:223], v[16:19]
	v_mfma_f32_16x16x32_bf16 v[4:7], v[144:147], v[224:227], v[4:7]
	v_mfma_f32_16x16x32_bf16 v[4:7], v[148:151], v[228:231], v[4:7]
	v_mfma_f32_16x16x32_bf16 v[0:3], v[168:171], v[224:227], v[0:3]
	v_mfma_f32_16x16x32_bf16 v[0:3], v[196:199], v[228:231], v[0:3]
	s_setprio 0
	s_barrier
	s_add_i32 s77, 0, 0x18000
	s_add_i32 s78, 0, 0x1c000
	v_add_u32_e32 v140, s77, v177
	v_add_u32_e32 v196, s78, v177
	ds_read_b128 v[128:131], v140
	ds_read_b128 v[132:135], v140 offset:1024
	ds_read_b128 v[136:139], v140 offset:2048
	ds_read_b128 v[140:143], v140 offset:3072
	ds_read_b128 v[144:147], v196
	ds_read_b128 v[148:151], v196 offset:1024
	ds_read_b128 v[168:171], v196 offset:2048
	ds_read_b128 v[196:199], v196 offset:3072
	s_add_u32 s64, s64, 0x80000
	s_addc_u32 s65, s65, 0
	s_mov_b32 m0, s11
	ds_read_b128 v[200:203], v194 offset:32768
	ds_read_b128 v[204:207], v194 offset:33792
	ds_read_b128 v[208:211], v194 offset:34816
	ds_read_b128 v[212:215], v194 offset:35840
	ds_read_b128 v[216:219], v194 offset:36864
	ds_read_b128 v[220:223], v194 offset:37888
	ds_read_b128 v[224:227], v194 offset:38912
	ds_read_b128 v[228:231], v194 offset:39936
	global_load_lds_dwordx4 v152, s[64:65]
	s_mov_b32 m0, s14
	s_nop 0
	global_load_lds_dwordx4 v156, s[64:65]
	s_waitcnt vmcnt(8)
	s_waitcnt lgkmcnt(0)
	s_barrier
	s_setprio 1
	s_waitcnt lgkmcnt(0)
	v_mfma_f32_16x16x32_bf16 v[124:127], v[128:131], v[200:203], v[124:127]
	v_mfma_f32_16x16x32_bf16 v[124:127], v[132:135], v[204:207], v[124:127]
	v_mfma_f32_16x16x32_bf16 v[120:123], v[136:139], v[200:203], v[120:123]
	v_mfma_f32_16x16x32_bf16 v[120:123], v[140:143], v[204:207], v[120:123]
	v_mfma_f32_16x16x32_bf16 v[108:111], v[128:131], v[208:211], v[108:111]
	v_mfma_f32_16x16x32_bf16 v[108:111], v[132:135], v[212:215], v[108:111]
	v_mfma_f32_16x16x32_bf16 v[104:107], v[136:139], v[208:211], v[104:107]
	v_mfma_f32_16x16x32_bf16 v[104:107], v[140:143], v[212:215], v[104:107]
	v_mfma_f32_16x16x32_bf16 v[92:95], v[128:131], v[216:219], v[92:95]
	v_mfma_f32_16x16x32_bf16 v[92:95], v[132:135], v[220:223], v[92:95]
	v_mfma_f32_16x16x32_bf16 v[88:91], v[136:139], v[216:219], v[88:91]
	v_mfma_f32_16x16x32_bf16 v[88:91], v[140:143], v[220:223], v[88:91]
	v_mfma_f32_16x16x32_bf16 v[76:79], v[128:131], v[224:227], v[76:79]
	v_mfma_f32_16x16x32_bf16 v[76:79], v[132:135], v[228:231], v[76:79]
	v_mfma_f32_16x16x32_bf16 v[72:75], v[136:139], v[224:227], v[72:75]
	v_mfma_f32_16x16x32_bf16 v[72:75], v[140:143], v[228:231], v[72:75]
	s_setprio 0
	s_setprio 1
	v_mfma_f32_16x16x32_bf16 v[116:119], v[144:147], v[200:203], v[116:119]
	v_mfma_f32_16x16x32_bf16 v[116:119], v[148:151], v[204:207], v[116:119]
	v_mfma_f32_16x16x32_bf16 v[112:115], v[168:171], v[200:203], v[112:115]
	v_mfma_f32_16x16x32_bf16 v[112:115], v[196:199], v[204:207], v[112:115]
	v_mfma_f32_16x16x32_bf16 v[100:103], v[144:147], v[208:211], v[100:103]
	v_mfma_f32_16x16x32_bf16 v[100:103], v[148:151], v[212:215], v[100:103]
	v_mfma_f32_16x16x32_bf16 v[96:99], v[168:171], v[208:211], v[96:99]
	v_mfma_f32_16x16x32_bf16 v[96:99], v[196:199], v[212:215], v[96:99]
	v_mfma_f32_16x16x32_bf16 v[84:87], v[144:147], v[216:219], v[84:87]
	v_mfma_f32_16x16x32_bf16 v[84:87], v[148:151], v[220:223], v[84:87]
	v_mfma_f32_16x16x32_bf16 v[80:83], v[168:171], v[216:219], v[80:83]
	v_mfma_f32_16x16x32_bf16 v[80:83], v[196:199], v[220:223], v[80:83]
	v_mfma_f32_16x16x32_bf16 v[68:71], v[144:147], v[224:227], v[68:71]
	v_mfma_f32_16x16x32_bf16 v[68:71], v[148:151], v[228:231], v[68:71]
	v_mfma_f32_16x16x32_bf16 v[64:67], v[168:171], v[224:227], v[64:67]
	v_mfma_f32_16x16x32_bf16 v[64:67], v[196:199], v[228:231], v[64:67]
	s_setprio 0
	s_barrier
	s_add_i32 s64, s77, s0
	s_mov_b32 m0, s64
	ds_read_b128 v[200:203], v194 offset:49152
	ds_read_b128 v[204:207], v194 offset:50176
	ds_read_b128 v[208:211], v194 offset:51200
	ds_read_b128 v[212:215], v194 offset:52224
	ds_read_b128 v[216:219], v194 offset:53248
	ds_read_b128 v[220:223], v194 offset:54272
	ds_read_b128 v[224:227], v194 offset:55296
	ds_read_b128 v[228:231], v194 offset:56320
	global_load_lds_dwordx4 v154, s[98:99]
	s_add_i32 m0, s64, 0x2000
	s_add_u32 s62, s62, 0x80080
	s_addc_u32 s63, s63, 0
	s_add_i32 s64, s78, s0
	global_load_lds_dwordx4 v158, s[98:99]
	s_mov_b32 m0, s64
	s_nop 0
	global_load_lds_dwordx4 v154, s[62:63]
	s_add_i32 m0, s64, 0x2000
	s_nop 0
	global_load_lds_dwordx4 v158, s[62:63]
	s_mov_b32 m0, s33
	s_nop 0
	global_load_lds_dwordx4 v152, s[100:101]
	s_mov_b32 m0, s68
	s_nop 0
	global_load_lds_dwordx4 v156, s[100:101]
	s_waitcnt vmcnt(8)
	s_waitcnt lgkmcnt(0)
	s_barrier
	s_setprio 1
	s_waitcnt lgkmcnt(0)
	v_mfma_f32_16x16x32_bf16 v[60:63], v[128:131], v[200:203], v[60:63]
	v_mfma_f32_16x16x32_bf16 v[60:63], v[132:135], v[204:207], v[60:63]
	v_mfma_f32_16x16x32_bf16 v[56:59], v[136:139], v[200:203], v[56:59]
	v_mfma_f32_16x16x32_bf16 v[56:59], v[140:143], v[204:207], v[56:59]
	v_mfma_f32_16x16x32_bf16 v[44:47], v[128:131], v[208:211], v[44:47]
	v_mfma_f32_16x16x32_bf16 v[44:47], v[132:135], v[212:215], v[44:47]
	v_mfma_f32_16x16x32_bf16 v[40:43], v[136:139], v[208:211], v[40:43]
	v_mfma_f32_16x16x32_bf16 v[40:43], v[140:143], v[212:215], v[40:43]
	v_mfma_f32_16x16x32_bf16 v[28:31], v[128:131], v[216:219], v[28:31]
	v_mfma_f32_16x16x32_bf16 v[28:31], v[132:135], v[220:223], v[28:31]
	v_mfma_f32_16x16x32_bf16 v[24:27], v[136:139], v[216:219], v[24:27]
	v_mfma_f32_16x16x32_bf16 v[24:27], v[140:143], v[220:223], v[24:27]
	v_mfma_f32_16x16x32_bf16 v[12:15], v[128:131], v[224:227], v[12:15]
	v_mfma_f32_16x16x32_bf16 v[12:15], v[132:135], v[228:231], v[12:15]
	v_mfma_f32_16x16x32_bf16 v[8:11], v[136:139], v[224:227], v[8:11]
	v_mfma_f32_16x16x32_bf16 v[8:11], v[140:143], v[228:231], v[8:11]
	s_setprio 0
	s_setprio 1
	v_mfma_f32_16x16x32_bf16 v[52:55], v[144:147], v[200:203], v[52:55]
	v_mfma_f32_16x16x32_bf16 v[52:55], v[148:151], v[204:207], v[52:55]
	v_mfma_f32_16x16x32_bf16 v[48:51], v[168:171], v[200:203], v[48:51]
	v_mfma_f32_16x16x32_bf16 v[48:51], v[196:199], v[204:207], v[48:51]
	v_mfma_f32_16x16x32_bf16 v[36:39], v[144:147], v[208:211], v[36:39]
	v_mfma_f32_16x16x32_bf16 v[36:39], v[148:151], v[212:215], v[36:39]
	v_mfma_f32_16x16x32_bf16 v[32:35], v[168:171], v[208:211], v[32:35]
	v_mfma_f32_16x16x32_bf16 v[32:35], v[196:199], v[212:215], v[32:35]
	v_mfma_f32_16x16x32_bf16 v[20:23], v[144:147], v[216:219], v[20:23]
	v_mfma_f32_16x16x32_bf16 v[20:23], v[148:151], v[220:223], v[20:23]
	v_mfma_f32_16x16x32_bf16 v[16:19], v[168:171], v[216:219], v[16:19]
	v_mfma_f32_16x16x32_bf16 v[16:19], v[196:199], v[220:223], v[16:19]
	v_mfma_f32_16x16x32_bf16 v[4:7], v[144:147], v[224:227], v[4:7]
	v_mfma_f32_16x16x32_bf16 v[4:7], v[148:151], v[228:231], v[4:7]
	v_mfma_f32_16x16x32_bf16 v[0:3], v[168:171], v[224:227], v[0:3]
	v_mfma_f32_16x16x32_bf16 v[0:3], v[196:199], v[228:231], v[0:3]
	s_setprio 0
	s_barrier
	s_add_i32 s76, s76, 2
	s_add_u32 s60, s60, 0x100
	s_addc_u32 s61, s61, 0
	s_add_u32 s74, s74, 0x100
	s_addc_u32 s75, s75, 0
	s_cmp_gt_u32 s76, 29
	s_cbranch_scc0 .LBB0_502
	s_and_b64 vcc, exec, s[40:41]
	s_cbranch_vccz .LBB0_505
	s_barrier

.LBB0_596:
	ds_read_b128 v[142:145], v159
	ds_read_b128 v[146:149], v159 offset:1024
	ds_read_b128 v[150:153], v159 offset:2048
	ds_read_b128 v[154:157], v159 offset:3072
	ds_read_b128 v[166:169], v160
	ds_read_b128 v[170:173], v160 offset:1024
	ds_read_b128 v[176:179], v160 offset:2048
	ds_read_b128 v[180:183], v160 offset:3072
	s_add_u32 s50, s48, 0xfff80080
	s_addc_u32 s51, s49, -1
	s_cmp_eq_u32 s76, 28
	s_cselect_b32 s61, s39, s51
	s_cselect_b32 s60, s47, s50
	s_cselect_b32 s51, s72, s75
	s_cselect_b32 s50, s73, s74
	s_add_i32 m0, s1, 0xc000
	ds_read_b128 v[184:187], v161
	ds_read_b128 v[188:191], v161 offset:1024
	ds_read_b128 v[192:195], v161 offset:2048
	ds_read_b128 v[196:199], v161 offset:3072
	ds_read_b128 v[200:203], v161 offset:4096
	ds_read_b128 v[204:207], v161 offset:5120
	ds_read_b128 v[208:211], v161 offset:6144
	ds_read_b128 v[212:215], v161 offset:7168
	global_load_lds_dwordx4 v138, s[48:49]
	s_add_i32 m0, s1, 0xe000
	s_nop 0
	global_load_lds_dwordx4 v140, s[48:49]
	s_waitcnt vmcnt(8)
	s_waitcnt lgkmcnt(0)
	s_barrier
	s_setprio 1
	s_waitcnt lgkmcnt(0)
	v_mfma_f32_16x16x32_bf16 v[124:127], v[142:145], v[184:187], v[124:127]
	v_mfma_f32_16x16x32_bf16 v[124:127], v[146:149], v[188:191], v[124:127]
	v_mfma_f32_16x16x32_bf16 v[120:123], v[150:153], v[184:187], v[120:123]
	v_mfma_f32_16x16x32_bf16 v[120:123], v[154:157], v[188:191], v[120:123]
	v_mfma_f32_16x16x32_bf16 v[108:111], v[142:145], v[192:195], v[108:111]
	v_mfma_f32_16x16x32_bf16 v[108:111], v[146:149], v[196:199], v[108:111]
	v_mfma_f32_16x16x32_bf16 v[104:107], v[150:153], v[192:195], v[104:107]
	v_mfma_f32_16x16x32_bf16 v[104:107], v[154:157], v[196:199], v[104:107]
	v_mfma_f32_16x16x32_bf16 v[92:95], v[142:145], v[200:203], v[92:95]
	v_mfma_f32_16x16x32_bf16 v[92:95], v[146:149], v[204:207], v[92:95]
	v_mfma_f32_16x16x32_bf16 v[88:91], v[150:153], v[200:203], v[88:91]
	v_mfma_f32_16x16x32_bf16 v[88:91], v[154:157], v[204:207], v[88:91]
	v_mfma_f32_16x16x32_bf16 v[76:79], v[142:145], v[208:211], v[76:79]
	v_mfma_f32_16x16x32_bf16 v[76:79], v[146:149], v[212:215], v[76:79]
	v_mfma_f32_16x16x32_bf16 v[72:75], v[150:153], v[208:211], v[72:75]
	v_mfma_f32_16x16x32_bf16 v[72:75], v[154:157], v[212:215], v[72:75]
	s_setprio 0
	s_setprio 1
	v_mfma_f32_16x16x32_bf16 v[116:119], v[166:169], v[184:187], v[116:119]
	v_mfma_f32_16x16x32_bf16 v[116:119], v[170:173], v[188:191], v[116:119]
	v_mfma_f32_16x16x32_bf16 v[112:115], v[176:179], v[184:187], v[112:115]
	v_mfma_f32_16x16x32_bf16 v[112:115], v[180:183], v[188:191], v[112:115]
	v_mfma_f32_16x16x32_bf16 v[100:103], v[166:169], v[192:195], v[100:103]
	v_mfma_f32_16x16x32_bf16 v[100:103], v[170:173], v[196:199], v[100:103]
	v_mfma_f32_16x16x32_bf16 v[96:99], v[176:179], v[192:195], v[96:99]
	v_mfma_f32_16x16x32_bf16 v[96:99], v[180:183], v[196:199], v[96:99]
	v_mfma_f32_16x16x32_bf16 v[84:87], v[166:169], v[200:203], v[84:87]
	v_mfma_f32_16x16x32_bf16 v[84:87], v[170:173], v[204:207], v[84:87]
	v_mfma_f32_16x16x32_bf16 v[80:83], v[176:179], v[200:203], v[80:83]
	v_mfma_f32_16x16x32_bf16 v[80:83], v[180:183], v[204:207], v[80:83]
	v_mfma_f32_16x16x32_bf16 v[68:71], v[166:169], v[208:211], v[68:71]
	v_mfma_f32_16x16x32_bf16 v[68:71], v[170:173], v[212:215], v[68:71]
	v_mfma_f32_16x16x32_bf16 v[64:67], v[176:179], v[208:211], v[64:67]
	v_mfma_f32_16x16x32_bf16 v[64:67], v[180:183], v[212:215], v[64:67]
	s_setprio 0
	s_barrier
	s_add_i32 s77, s64, s0
	s_add_u32 s98, s50, s34
	s_addc_u32 s99, s51, s35
	s_mov_b32 m0, s77
	ds_read_b128 v[184:187], v161 offset:16384
	ds_read_b128 v[188:191], v161 offset:17408
	ds_read_b128 v[192:195], v161 offset:18432
	ds_read_b128 v[196:199], v161 offset:19456
	ds_read_b128 v[200:203], v161 offset:20480
	ds_read_b128 v[204:207], v161 offset:21504
	ds_read_b128 v[208:211], v161 offset:22528
	ds_read_b128 v[212:215], v161 offset:23552
	global_load_lds_dwordx4 v130, s[50:51]
	s_add_i32 m0, s77, 0x2000
	s_add_u32 s78, s50, 0x80000
	s_addc_u32 s79, s51, 0
	s_add_i32 s77, s65, s0
	global_load_lds_dwordx4 v134, s[50:51]
	s_mov_b32 m0, s77
	s_nop 0
	global_load_lds_dwordx4 v130, s[78:79]
	s_add_i32 m0, s77, 0x2000
	s_nop 0
	global_load_lds_dwordx4 v134, s[78:79]
	s_add_u32 s100, s60, s34
	s_addc_u32 s101, s61, s35
	s_mov_b32 m0, s1
	s_nop 0
	global_load_lds_dwordx4 v128, s[60:61]
	s_mov_b32 m0, s10
	s_nop 0
	global_load_lds_dwordx4 v132, s[60:61]
	s_waitcnt vmcnt(8)
	s_waitcnt lgkmcnt(0)
	s_barrier
	s_setprio 1
	s_waitcnt lgkmcnt(0)
	v_mfma_f32_16x16x32_bf16 v[60:63], v[142:145], v[184:187], v[60:63]
	v_mfma_f32_16x16x32_bf16 v[60:63], v[146:149], v[188:191], v[60:63]
	v_mfma_f32_16x16x32_bf16 v[56:59], v[150:153], v[184:187], v[56:59]
	v_mfma_f32_16x16x32_bf16 v[56:59], v[154:157], v[188:191], v[56:59]
	v_mfma_f32_16x16x32_bf16 v[44:47], v[142:145], v[192:195], v[44:47]
	v_mfma_f32_16x16x32_bf16 v[44:47], v[146:149], v[196:199], v[44:47]
	v_mfma_f32_16x16x32_bf16 v[40:43], v[150:153], v[192:195], v[40:43]
	v_mfma_f32_16x16x32_bf16 v[40:43], v[154:157], v[196:199], v[40:43]
	v_mfma_f32_16x16x32_bf16 v[28:31], v[142:145], v[200:203], v[28:31]
	v_mfma_f32_16x16x32_bf16 v[28:31], v[146:149], v[204:207], v[28:31]
	v_mfma_f32_16x16x32_bf16 v[24:27], v[150:153], v[200:203], v[24:27]
	v_mfma_f32_16x16x32_bf16 v[24:27], v[154:157], v[204:207], v[24:27]
	v_mfma_f32_16x16x32_bf16 v[12:15], v[142:145], v[208:211], v[12:15]
	v_mfma_f32_16x16x32_bf16 v[12:15], v[146:149], v[212:215], v[12:15]
	v_mfma_f32_16x16x32_bf16 v[8:11], v[150:153], v[208:211], v[8:11]
	v_mfma_f32_16x16x32_bf16 v[8:11], v[154:157], v[212:215], v[8:11]
	s_setprio 0
	s_setprio 1
	v_mfma_f32_16x16x32_bf16 v[52:55], v[166:169], v[184:187], v[52:55]
	v_mfma_f32_16x16x32_bf16 v[52:55], v[170:173], v[188:191], v[52:55]
	v_mfma_f32_16x16x32_bf16 v[48:51], v[176:179], v[184:187], v[48:51]
	v_mfma_f32_16x16x32_bf16 v[48:51], v[180:183], v[188:191], v[48:51]
	v_mfma_f32_16x16x32_bf16 v[36:39], v[166:169], v[192:195], v[36:39]
	v_mfma_f32_16x16x32_bf16 v[36:39], v[170:173], v[196:199], v[36:39]
	v_mfma_f32_16x16x32_bf16 v[32:35], v[176:179], v[192:195], v[32:35]
	v_mfma_f32_16x16x32_bf16 v[32:35], v[180:183], v[196:199], v[32:35]
	v_mfma_f32_16x16x32_bf16 v[20:23], v[166:169], v[200:203], v[20:23]
	v_mfma_f32_16x16x32_bf16 v[20:23], v[170:173], v[204:207], v[20:23]
	v_mfma_f32_16x16x32_bf16 v[16:19], v[176:179], v[200:203], v[16:19]
	v_mfma_f32_16x16x32_bf16 v[16:19], v[180:183], v[204:207], v[16:19]
	v_mfma_f32_16x16x32_bf16 v[4:7], v[166:169], v[208:211], v[4:7]
	v_mfma_f32_16x16x32_bf16 v[4:7], v[170:173], v[212:215], v[4:7]
	v_mfma_f32_16x16x32_bf16 v[0:3], v[176:179], v[208:211], v[0:3]
	v_mfma_f32_16x16x32_bf16 v[0:3], v[180:183], v[212:215], v[0:3]
	s_setprio 0
	s_barrier
	s_add_i32 s77, 0, 0x18000
	v_add_u32_e32 v136, s77, v158
	s_add_i32 s78, 0, 0x1c000
	ds_read_b128 v[142:145], v136
	ds_read_b128 v[146:149], v136 offset:1024
	ds_read_b128 v[150:153], v136 offset:2048
	ds_read_b128 v[154:157], v136 offset:3072
	v_add_u32_e32 v136, s78, v158
	ds_read_b128 v[166:169], v136
	ds_read_b128 v[170:173], v136 offset:1024
	ds_read_b128 v[176:179], v136 offset:2048
	ds_read_b128 v[180:183], v136 offset:3072
	s_add_u32 s60, s60, 0x80000
	s_addc_u32 s61, s61, 0
	s_mov_b32 m0, s11
	ds_read_b128 v[184:187], v161 offset:32768
	ds_read_b128 v[188:191], v161 offset:33792
	ds_read_b128 v[192:195], v161 offset:34816
	ds_read_b128 v[196:199], v161 offset:35840
	ds_read_b128 v[200:203], v161 offset:36864
	ds_read_b128 v[204:207], v161 offset:37888
	ds_read_b128 v[208:211], v161 offset:38912
	ds_read_b128 v[212:215], v161 offset:39936
	global_load_lds_dwordx4 v128, s[60:61]
	s_mov_b32 m0, s14
	s_nop 0
	global_load_lds_dwordx4 v132, s[60:61]
	s_waitcnt vmcnt(8)
	s_waitcnt lgkmcnt(0)
	s_barrier
	s_setprio 1
	s_waitcnt lgkmcnt(0)
	v_mfma_f32_16x16x32_bf16 v[124:127], v[142:145], v[184:187], v[124:127]
	v_mfma_f32_16x16x32_bf16 v[124:127], v[146:149], v[188:191], v[124:127]
	v_mfma_f32_16x16x32_bf16 v[120:123], v[150:153], v[184:187], v[120:123]
	v_mfma_f32_16x16x32_bf16 v[120:123], v[154:157], v[188:191], v[120:123]
	v_mfma_f32_16x16x32_bf16 v[108:111], v[142:145], v[192:195], v[108:111]
	v_mfma_f32_16x16x32_bf16 v[108:111], v[146:149], v[196:199], v[108:111]
	v_mfma_f32_16x16x32_bf16 v[104:107], v[150:153], v[192:195], v[104:107]
	v_mfma_f32_16x16x32_bf16 v[104:107], v[154:157], v[196:199], v[104:107]
	v_mfma_f32_16x16x32_bf16 v[92:95], v[142:145], v[200:203], v[92:95]
	v_mfma_f32_16x16x32_bf16 v[92:95], v[146:149], v[204:207], v[92:95]
	v_mfma_f32_16x16x32_bf16 v[88:91], v[150:153], v[200:203], v[88:91]
	v_mfma_f32_16x16x32_bf16 v[88:91], v[154:157], v[204:207], v[88:91]
	v_mfma_f32_16x16x32_bf16 v[76:79], v[142:145], v[208:211], v[76:79]
	v_mfma_f32_16x16x32_bf16 v[76:79], v[146:149], v[212:215], v[76:79]
	v_mfma_f32_16x16x32_bf16 v[72:75], v[150:153], v[208:211], v[72:75]
	v_mfma_f32_16x16x32_bf16 v[72:75], v[154:157], v[212:215], v[72:75]
	s_setprio 0
	s_setprio 1
	v_mfma_f32_16x16x32_bf16 v[116:119], v[166:169], v[184:187], v[116:119]
	v_mfma_f32_16x16x32_bf16 v[116:119], v[170:173], v[188:191], v[116:119]
	v_mfma_f32_16x16x32_bf16 v[112:115], v[176:179], v[184:187], v[112:115]
	v_mfma_f32_16x16x32_bf16 v[112:115], v[180:183], v[188:191], v[112:115]
	v_mfma_f32_16x16x32_bf16 v[100:103], v[166:169], v[192:195], v[100:103]
	v_mfma_f32_16x16x32_bf16 v[100:103], v[170:173], v[196:199], v[100:103]
	v_mfma_f32_16x16x32_bf16 v[96:99], v[176:179], v[192:195], v[96:99]
	v_mfma_f32_16x16x32_bf16 v[96:99], v[180:183], v[196:199], v[96:99]
	v_mfma_f32_16x16x32_bf16 v[84:87], v[166:169], v[200:203], v[84:87]
	v_mfma_f32_16x16x32_bf16 v[84:87], v[170:173], v[204:207], v[84:87]
	v_mfma_f32_16x16x32_bf16 v[80:83], v[176:179], v[200:203], v[80:83]
	v_mfma_f32_16x16x32_bf16 v[80:83], v[180:183], v[204:207], v[80:83]
	v_mfma_f32_16x16x32_bf16 v[68:71], v[166:169], v[208:211], v[68:71]
	v_mfma_f32_16x16x32_bf16 v[68:71], v[170:173], v[212:215], v[68:71]
	v_mfma_f32_16x16x32_bf16 v[64:67], v[176:179], v[208:211], v[64:67]
	v_mfma_f32_16x16x32_bf16 v[64:67], v[180:183], v[212:215], v[64:67]
	s_setprio 0
	s_barrier
	s_add_i32 s60, s77, s0
	s_mov_b32 m0, s60
	ds_read_b128 v[184:187], v161 offset:49152
	ds_read_b128 v[188:191], v161 offset:50176
	ds_read_b128 v[192:195], v161 offset:51200
	ds_read_b128 v[196:199], v161 offset:52224
	ds_read_b128 v[200:203], v161 offset:53248
	ds_read_b128 v[204:207], v161 offset:54272
	ds_read_b128 v[208:211], v161 offset:55296
	ds_read_b128 v[212:215], v161 offset:56320
	global_load_lds_dwordx4 v130, s[98:99]
	s_add_i32 m0, s60, 0x2000
	s_add_u32 s50, s50, 0x80080
	s_addc_u32 s51, s51, 0
	s_add_i32 s60, s78, s0
	global_load_lds_dwordx4 v134, s[98:99]
	s_mov_b32 m0, s60
	s_nop 0
	global_load_lds_dwordx4 v130, s[50:51]
	s_add_i32 m0, s60, 0x2000
	s_nop 0
	global_load_lds_dwordx4 v134, s[50:51]
	s_mov_b32 m0, s15
	s_nop 0
	global_load_lds_dwordx4 v128, s[100:101]
	s_mov_b32 m0, s33
	s_nop 0
	global_load_lds_dwordx4 v132, s[100:101]
	s_waitcnt vmcnt(8)
	s_waitcnt lgkmcnt(0)
	s_barrier
	s_setprio 1
	s_waitcnt lgkmcnt(0)
	v_mfma_f32_16x16x32_bf16 v[60:63], v[142:145], v[184:187], v[60:63]
	v_mfma_f32_16x16x32_bf16 v[60:63], v[146:149], v[188:191], v[60:63]
	v_mfma_f32_16x16x32_bf16 v[56:59], v[150:153], v[184:187], v[56:59]
	v_mfma_f32_16x16x32_bf16 v[56:59], v[154:157], v[188:191], v[56:59]
	v_mfma_f32_16x16x32_bf16 v[44:47], v[142:145], v[192:195], v[44:47]
	v_mfma_f32_16x16x32_bf16 v[44:47], v[146:149], v[196:199], v[44:47]
	v_mfma_f32_16x16x32_bf16 v[40:43], v[150:153], v[192:195], v[40:43]
	v_mfma_f32_16x16x32_bf16 v[40:43], v[154:157], v[196:199], v[40:43]
	v_mfma_f32_16x16x32_bf16 v[28:31], v[142:145], v[200:203], v[28:31]
	v_mfma_f32_16x16x32_bf16 v[28:31], v[146:149], v[204:207], v[28:31]
	v_mfma_f32_16x16x32_bf16 v[24:27], v[150:153], v[200:203], v[24:27]
	v_mfma_f32_16x16x32_bf16 v[24:27], v[154:157], v[204:207], v[24:27]
	v_mfma_f32_16x16x32_bf16 v[12:15], v[142:145], v[208:211], v[12:15]
	v_mfma_f32_16x16x32_bf16 v[12:15], v[146:149], v[212:215], v[12:15]
	v_mfma_f32_16x16x32_bf16 v[8:11], v[150:153], v[208:211], v[8:11]
	v_mfma_f32_16x16x32_bf16 v[8:11], v[154:157], v[212:215], v[8:11]
	s_setprio 0
	s_setprio 1
	v_mfma_f32_16x16x32_bf16 v[52:55], v[166:169], v[184:187], v[52:55]
	v_mfma_f32_16x16x32_bf16 v[52:55], v[170:173], v[188:191], v[52:55]
	v_mfma_f32_16x16x32_bf16 v[48:51], v[176:179], v[184:187], v[48:51]
	v_mfma_f32_16x16x32_bf16 v[48:51], v[180:183], v[188:191], v[48:51]
	v_mfma_f32_16x16x32_bf16 v[36:39], v[166:169], v[192:195], v[36:39]
	v_mfma_f32_16x16x32_bf16 v[36:39], v[170:173], v[196:199], v[36:39]
	v_mfma_f32_16x16x32_bf16 v[32:35], v[176:179], v[192:195], v[32:35]
	v_mfma_f32_16x16x32_bf16 v[32:35], v[180:183], v[196:199], v[32:35]
	v_mfma_f32_16x16x32_bf16 v[20:23], v[166:169], v[200:203], v[20:23]
	v_mfma_f32_16x16x32_bf16 v[20:23], v[170:173], v[204:207], v[20:23]
	v_mfma_f32_16x16x32_bf16 v[16:19], v[176:179], v[200:203], v[16:19]
	v_mfma_f32_16x16x32_bf16 v[16:19], v[180:183], v[204:207], v[16:19]
	v_mfma_f32_16x16x32_bf16 v[4:7], v[166:169], v[208:211], v[4:7]
	v_mfma_f32_16x16x32_bf16 v[4:7], v[170:173], v[212:215], v[4:7]
	v_mfma_f32_16x16x32_bf16 v[0:3], v[176:179], v[208:211], v[0:3]
	v_mfma_f32_16x16x32_bf16 v[0:3], v[180:183], v[212:215], v[0:3]
	s_setprio 0
	s_barrier
	s_add_i32 s76, s76, 2
	s_add_u32 s48, s48, 0x100
	s_addc_u32 s49, s49, 0
	s_add_u32 s74, s74, 0x100
	s_addc_u32 s75, s75, 0
	s_cmp_gt_u32 s76, 29
	s_cbranch_scc0 .LBB0_596
	s_and_b64 vcc, exec, s[36:37]
	s_cbranch_vccz .LBB0_599
	s_barrier
.LBB0_599:
	s_lshl_b32 s39, s46, 8
	v_add_u32_e32 v242, s39, v163
	v_add_u32_e32 v242, 64, v242
	v_ashrrev_i32_e32 v243, 31, v242
	v_lshlrev_b64 v[242:243], 5, v[242:243]
	v_lshl_add_u64 v[242:243], s[22:23], 0, v[242:243]
	global_load_dwordx4 v[192:195], v[242:243], off offset:-2048
	global_load_dwordx4 v[196:199], v[242:243], off offset:-2032
	global_load_dwordx4 v[200:203], v[242:243], off offset:-1536
	global_load_dwordx4 v[204:207], v[242:243], off offset:-1520
	global_load_dwordx4 v[208:211], v[242:243], off offset:-1024
	global_load_dwordx4 v[212:215], v[242:243], off offset:-1008
	global_load_dwordx4 v[216:219], v[242:243], off offset:-512
	global_load_dwordx4 v[220:223], v[242:243], off offset:-496
	global_load_dwordx4 v[224:227], v[242:243], off offset:2048
	global_load_dwordx4 v[228:231], v[242:243], off offset:2064
	global_load_dwordx4 v[232:235], v[242:243], off offset:2560
	global_load_dwordx4 v[236:239], v[242:243], off offset:2576
	v_max_f32_e32 v143, v127, v127
	v_max_f32_e32 v144, v126, v126
	v_max_f32_e32 v143, v144, v143
	v_max_f32_e32 v144, v123, v123
	v_max_f32_e32 v145, v122, v122
	v_max_f32_e32 v144, v145, v144
	v_max3_f32 v143, v124, v125, v143
	v_max3_f32 v144, v120, v121, v144
	v_and_b32_e32 v142, 64, v162
	v_max3_f32 v143, v143, s66, v144
	v_max_f32_e32 v144, v119, v119
	v_max_f32_e32 v145, v118, v118
	v_xor_b32_e32 v136, 16, v162
	v_add_u32_e32 v142, 64, v142
	v_max_f32_e32 v144, v145, v144
	v_max_f32_e32 v145, v115, v115
	v_max_f32_e32 v146, v114, v114
	v_cmp_lt_i32_e32 vcc, v136, v142
	v_max_f32_e32 v145, v146, v145
	v_max3_f32 v144, v116, v117, v144
	v_cndmask_b32_e32 v136, v162, v136, vcc
	v_max3_f32 v145, v112, v113, v145
	v_lshlrev_b32_e32 v136, 2, v136
	v_max3_f32 v143, v143, v144, v145
	ds_bpermute_b32 v144, v136, v143
	v_xor_b32_e32 v145, 32, v162
	v_cmp_lt_i32_e32 vcc, v145, v142
	s_nop 1
	v_cndmask_b32_e32 v142, v162, v145, vcc
	v_lshlrev_b32_e32 v165, 2, v142
	s_waitcnt lgkmcnt(0)
	v_max_f32_e32 v142, v144, v144
	v_max_f32_e32 v143, v143, v142
	ds_bpermute_b32 v144, v165, v143
	v_cmp_gt_u32_e32 vcc, 16, v162
	v_lshl_add_u32 v142, v162, 4, s62
	s_and_saveexec_b64 s[48:49], vcc
	s_cbranch_execz .LBB0_601
	s_waitcnt lgkmcnt(0)
	v_max_f32_e32 v144, v144, v144
	v_max_f32_e32 v143, v143, v143
	v_max_f32_e32 v143, v143, v144
	ds_write_b32 v142, v143

.LBB0_615:
	s_or_b64 exec, exec, s[48:49]
	s_lshl_b32 s39, s46, 8
	v_add_u32_e32 v142, s39, v163
	v_ashrrev_i32_e32 v143, 31, v142
	s_waitcnt lgkmcnt(0)
	v_lshlrev_b64 v[144:145], 5, v[142:143]
	s_waitcnt lgkmcnt(0)
	s_barrier
	v_lshl_add_u64 v[148:149], s[22:23], 0, v[144:145]
	s_waitcnt vmcnt(0)
	v_mov_b32_e32 v144, v192
	v_mov_b32_e32 v145, v193
	v_mov_b32_e32 v146, v194
	v_mov_b32_e32 v147, v195
	v_mov_b32_e32 v148, v196
	v_mov_b32_e32 v149, v197
	v_mov_b32_e32 v150, v198
	v_mov_b32_e32 v151, v199
	global_load_dwordx4 v[192:195], v[242:243], off offset:3072
	global_load_dwordx4 v[196:199], v[242:243], off offset:3088
	v_lshl_add_u32 v152, v163, 4, 0
	v_add_u32_e32 v152, 0x20000, v152
	ds_read_b128 v[152:155], v152
	v_mov_b32_e32 v156, v115
	s_waitcnt lgkmcnt(0)
	v_max_f32_e32 v115, v155, v155
	v_mov_b32_e32 v166, v144
	v_mov_b32_e32 v167, v148
	v_mov_b32_e32 v148, v145
	v_mov_b32_e32 v144, v146
	v_mov_b32_e32 v145, v150
	v_mov_b32_e32 v150, v147
	v_pk_add_f32 v[146:147], v[166:167], v[148:149]
	v_pk_add_f32 v[144:145], v[144:145], v[150:151]
	s_nop 0
	v_pk_add_f32 v[144:145], v[146:147], v[144:145]
	s_nop 0
	v_add_f32_e32 v144, v144, v145
	v_fmamk_f32 v144, v144, 0x3a000000, v164
	v_rsq_f32_e32 v144, v144
	v_max_f32_e32 v145, v154, v154
	v_max_f32_e32 v115, v145, v115
	v_max3_f32 v157, v152, v153, v115
	v_mul_f32_e32 v144, 0x3d8293ee, v144
	v_pk_mul_f32 v[146:147], v[156:157], v[144:145] op_sel_hi:[1,0]
	s_nop 0
	v_fma_f32 v115, v124, v144, -v147
	v_fma_f32 v124, v125, v144, -v147
	v_fma_f32 v125, v126, v144, -v147
	v_fma_f32 v127, v127, v144, -v147
	v_fma_f32 v145, v120, v144, -v147
	v_fma_f32 v148, v121, v144, -v147
	v_fma_f32 v149, v122, v144, -v147
	v_fma_f32 v150, v123, v144, -v147
	v_exp_f32_e32 v120, v115
	v_exp_f32_e32 v121, v124
	v_exp_f32_e32 v126, v125
	v_exp_f32_e32 v127, v127
	v_fma_f32 v116, v116, v144, -v147
	v_fma_f32 v117, v117, v144, -v147
	v_fma_f32 v118, v118, v144, -v147
	v_fma_f32 v119, v119, v144, -v147
	v_fma_f32 v151, v112, v144, -v147
	v_fma_f32 v152, v113, v144, -v147
	v_fma_f32 v153, v114, v144, -v147
	v_exp_f32_e32 v122, v145
	v_exp_f32_e32 v123, v148
	v_exp_f32_e32 v144, v149
	v_exp_f32_e32 v145, v150
	v_sub_f32_e32 v146, v146, v147
	v_exp_f32_e32 v112, v116
	v_exp_f32_e32 v113, v117
	v_exp_f32_e32 v116, v118
	v_exp_f32_e32 v117, v119
	v_exp_f32_e32 v114, v151
	v_exp_f32_e32 v115, v152
	v_exp_f32_e32 v118, v153
	v_exp_f32_e32 v119, v146
	v_add_f32_e32 v124, v120, v121
	v_add_f32_e32 v125, v126, v127
	v_add_f32_e32 v146, v122, v123
	v_add_f32_e32 v147, v144, v145
	v_add_f32_e32 v124, v124, v125
	v_add_f32_e32 v148, v112, v113
	v_add_f32_e32 v149, v116, v117
	v_add_f32_e32 v125, v146, v147
	v_add_f32_e32 v124, 0, v124
	v_add_f32_e32 v150, v114, v115
	v_add_f32_e32 v151, v118, v119
	v_add_f32_e32 v146, v148, v149
	v_add_f32_e32 v124, v125, v124
	v_add_f32_e32 v124, v146, v124
	v_add_f32_e32 v125, v150, v151
	v_add_f32_e32 v124, v125, v124
	ds_bpermute_b32 v125, v136, v124
	s_waitcnt lgkmcnt(0)
	v_add_f32_e32 v124, v124, v125
	ds_bpermute_b32 v125, v165, v124
	s_and_saveexec_b64 s[46:47], vcc
	s_cbranch_execz .LBB0_617
	v_lshlrev_b32_e32 v146, 2, v163
	v_lshl_add_u32 v146, v146, 2, s63
	s_waitcnt lgkmcnt(0)
	v_add_f32_e32 v124, v124, v125
	ds_write_b32 v146, v124
.LBB0_617:
	s_or_b64 exec, exec, s[46:47]
	v_or_b32_e32 v166, 16, v163
	v_add_u32_e32 v124, s39, v166
	s_waitcnt lgkmcnt(0)
	v_ashrrev_i32_e32 v125, 31, v124
	v_lshlrev_b64 v[146:147], 5, v[124:125]
	v_lshl_add_u64 v[150:151], s[22:23], 0, v[146:147]
	s_waitcnt vmcnt(2)
	v_mov_b32_e32 v146, v200
	v_mov_b32_e32 v147, v201
	v_mov_b32_e32 v148, v202
	v_mov_b32_e32 v149, v203
	v_mov_b32_e32 v150, v204
	v_mov_b32_e32 v151, v205
	v_mov_b32_e32 v152, v206
	v_mov_b32_e32 v153, v207
	global_load_dwordx4 v[200:203], v[242:243], off offset:3584
	global_load_dwordx4 v[204:207], v[242:243], off offset:3600
	v_lshl_add_u32 v154, v166, 4, 0
	v_add_u32_e32 v154, 0x20000, v154
	ds_read_b128 v[154:157], v154
	v_mov_b32_e32 v168, v99
	s_waitcnt lgkmcnt(0)
	v_max_f32_e32 v99, v157, v157
	v_mov_b32_e32 v170, v146
	v_mov_b32_e32 v171, v150
	v_mov_b32_e32 v150, v147
	v_mov_b32_e32 v146, v148
	v_mov_b32_e32 v147, v152
	v_mov_b32_e32 v152, v149
	v_pk_add_f32 v[148:149], v[170:171], v[150:151]
	v_pk_add_f32 v[146:147], v[146:147], v[152:153]
	s_nop 0
	v_pk_add_f32 v[146:147], v[148:149], v[146:147]
	s_nop 0
	v_add_f32_e32 v146, v146, v147
	v_fmamk_f32 v146, v146, 0x3a000000, v164
	v_rsq_f32_e32 v146, v146
	v_max_f32_e32 v147, v156, v156
	v_max_f32_e32 v99, v147, v99
	v_max3_f32 v169, v154, v155, v99
	v_mul_f32_e32 v146, 0x3d8293ee, v146
	v_pk_mul_f32 v[148:149], v[168:169], v[146:147] op_sel_hi:[1,0]
	s_nop 0
	v_fma_f32 v99, v108, v146, -v149
	v_fma_f32 v109, v109, v146, -v149
	v_fma_f32 v110, v110, v146, -v149
	v_fma_f32 v111, v111, v146, -v149
	v_fma_f32 v104, v104, v146, -v149
	v_fma_f32 v105, v105, v146, -v149
	v_fma_f32 v150, v106, v146, -v149
	v_fma_f32 v151, v107, v146, -v149
	v_fma_f32 v100, v100, v146, -v149
	v_fma_f32 v101, v101, v146, -v149
	v_fma_f32 v102, v102, v146, -v149
	v_fma_f32 v103, v103, v146, -v149
	v_fma_f32 v96, v96, v146, -v149
	v_fma_f32 v97, v97, v146, -v149
	v_fma_f32 v152, v98, v146, -v149
	v_exp_f32_e32 v108, v99
	v_exp_f32_e32 v109, v109
	v_exp_f32_e32 v146, v110
	v_exp_f32_e32 v147, v111
	v_exp_f32_e32 v106, v104
	v_exp_f32_e32 v107, v105
	v_exp_f32_e32 v110, v150
	v_exp_f32_e32 v111, v151
	v_sub_f32_e32 v148, v148, v149
	v_exp_f32_e32 v100, v100
	v_exp_f32_e32 v101, v101
	v_exp_f32_e32 v104, v102
	v_exp_f32_e32 v105, v103
	v_exp_f32_e32 v98, v96
	v_exp_f32_e32 v99, v97
	v_exp_f32_e32 v102, v152
	v_exp_f32_e32 v103, v148
	v_add_f32_e32 v96, v108, v109
	v_add_f32_e32 v97, v146, v147
	v_add_f32_e32 v148, v106, v107
	v_add_f32_e32 v149, v110, v111
	v_add_f32_e32 v96, v96, v97
	v_add_f32_e32 v150, v100, v101
	v_add_f32_e32 v151, v104, v105
	v_add_f32_e32 v97, v148, v149
	v_add_f32_e32 v96, 0, v96
	v_add_f32_e32 v152, v98, v99
	v_add_f32_e32 v153, v102, v103
	v_add_f32_e32 v148, v150, v151
	v_add_f32_e32 v96, v97, v96
	v_add_f32_e32 v96, v148, v96
	v_add_f32_e32 v97, v152, v153
	v_add_f32_e32 v96, v97, v96
	ds_bpermute_b32 v97, v136, v96
	s_waitcnt lgkmcnt(0)
	v_add_f32_e32 v96, v96, v97
	ds_bpermute_b32 v97, v165, v96
	s_and_saveexec_b64 s[46:47], vcc
	s_cbranch_execz .LBB0_619
	v_lshlrev_b32_e32 v148, 2, v166
	v_lshl_add_u32 v148, v148, 2, s63
	s_waitcnt lgkmcnt(0)
	v_add_f32_e32 v96, v96, v97
	ds_write_b32 v148, v96
.LBB0_619:
	s_or_b64 exec, exec, s[46:47]
	v_or_b32_e32 v167, 32, v163
	v_add_u32_e32 v96, s39, v167
	s_waitcnt lgkmcnt(0)
	v_ashrrev_i32_e32 v97, 31, v96
	v_lshlrev_b64 v[148:149], 5, v[96:97]
	v_lshl_add_u64 v[152:153], s[22:23], 0, v[148:149]
	v_mov_b32_e32 v148, v208
	v_mov_b32_e32 v149, v209
	v_mov_b32_e32 v150, v210
	v_mov_b32_e32 v151, v211
	v_mov_b32_e32 v152, v212
	v_mov_b32_e32 v153, v213
	v_mov_b32_e32 v154, v214
	v_mov_b32_e32 v155, v215
	v_lshl_add_u32 v156, v167, 4, 0
	v_add_u32_e32 v156, 0x20000, v156
	ds_read_b128 v[168:171], v156
	v_mov_b32_e32 v156, v83
	s_waitcnt lgkmcnt(0)
	v_max_f32_e32 v83, v171, v171
	v_mov_b32_e32 v172, v148
	v_mov_b32_e32 v173, v152
	v_mov_b32_e32 v152, v149
	v_mov_b32_e32 v148, v150
	v_mov_b32_e32 v149, v154
	v_mov_b32_e32 v154, v151
	v_pk_add_f32 v[150:151], v[172:173], v[152:153]
	v_pk_add_f32 v[148:149], v[148:149], v[154:155]
	s_nop 0
	v_pk_add_f32 v[148:149], v[150:151], v[148:149]
	s_nop 0
	v_add_f32_e32 v148, v148, v149
	v_fmamk_f32 v148, v148, 0x3a000000, v164
	v_rsq_f32_e32 v148, v148
	v_max_f32_e32 v149, v170, v170
	v_max_f32_e32 v83, v149, v83
	v_max3_f32 v157, v168, v169, v83
	v_mul_f32_e32 v148, 0x3d8293ee, v148
	v_pk_mul_f32 v[150:151], v[156:157], v[148:149] op_sel_hi:[1,0]
	s_nop 0
	v_fma_f32 v83, v92, v148, -v151
	v_fma_f32 v92, v93, v148, -v151
	v_fma_f32 v93, v94, v148, -v151
	v_fma_f32 v94, v95, v148, -v151
	v_fma_f32 v95, v88, v148, -v151
	v_fma_f32 v149, v89, v148, -v151
	v_fma_f32 v152, v90, v148, -v151
	v_fma_f32 v153, v91, v148, -v151
	v_exp_f32_e32 v88, v83
	v_exp_f32_e32 v89, v92
	v_exp_f32_e32 v92, v93
	v_exp_f32_e32 v93, v94
	v_fma_f32 v84, v84, v148, -v151
	v_fma_f32 v85, v85, v148, -v151
	v_fma_f32 v86, v86, v148, -v151
	v_fma_f32 v87, v87, v148, -v151
	v_fma_f32 v154, v80, v148, -v151
	v_fma_f32 v155, v81, v148, -v151
	v_fma_f32 v156, v82, v148, -v151
	v_exp_f32_e32 v90, v95
	v_exp_f32_e32 v91, v149
	v_exp_f32_e32 v148, v152
	v_exp_f32_e32 v149, v153
	v_sub_f32_e32 v150, v150, v151
	v_exp_f32_e32 v80, v84
	v_exp_f32_e32 v81, v85
	v_exp_f32_e32 v84, v86
	v_exp_f32_e32 v85, v87
	v_exp_f32_e32 v82, v154
	v_exp_f32_e32 v83, v155
	v_exp_f32_e32 v86, v156
	v_exp_f32_e32 v87, v150
	v_add_f32_e32 v94, v88, v89
	v_add_f32_e32 v95, v92, v93
	v_add_f32_e32 v150, v90, v91
	v_add_f32_e32 v151, v148, v149
	v_add_f32_e32 v94, v94, v95
	v_add_f32_e32 v152, v80, v81
	v_add_f32_e32 v153, v84, v85
	v_add_f32_e32 v95, v150, v151
	v_add_f32_e32 v94, 0, v94
	v_add_f32_e32 v154, v82, v83
	v_add_f32_e32 v155, v86, v87
	v_add_f32_e32 v150, v152, v153
	v_add_f32_e32 v94, v95, v94
	v_add_f32_e32 v94, v150, v94
	v_add_f32_e32 v95, v154, v155
	v_add_f32_e32 v94, v95, v94
	ds_bpermute_b32 v95, v136, v94
	s_waitcnt lgkmcnt(0)
	v_add_f32_e32 v94, v94, v95
	ds_bpermute_b32 v95, v165, v94
	s_and_saveexec_b64 s[46:47], vcc
	s_cbranch_execz .LBB0_621
	v_lshlrev_b32_e32 v150, 2, v167
	v_lshl_add_u32 v150, v150, 2, s63
	s_waitcnt lgkmcnt(0)
	v_add_f32_e32 v94, v94, v95
	ds_write_b32 v150, v94
.LBB0_621:
	s_or_b64 exec, exec, s[46:47]
	v_or_b32_e32 v168, 48, v163
	v_add_u32_e32 v94, s39, v168
	s_waitcnt lgkmcnt(0)
	v_ashrrev_i32_e32 v95, 31, v94
	v_lshlrev_b64 v[150:151], 5, v[94:95]
	v_lshl_add_u64 v[154:155], s[22:23], 0, v[150:151]
	v_mov_b32_e32 v150, v216
	v_mov_b32_e32 v151, v217
	v_mov_b32_e32 v152, v218
	v_mov_b32_e32 v153, v219
	v_mov_b32_e32 v154, v220
	v_mov_b32_e32 v155, v221
	v_mov_b32_e32 v156, v222
	v_mov_b32_e32 v157, v223
	v_lshl_add_u32 v169, v168, 4, 0
	v_add_u32_e32 v169, 0x20000, v169
	ds_read_b128 v[170:173], v169
	v_mov_b32_e32 v176, v67
	s_waitcnt lgkmcnt(0)
	v_max_f32_e32 v67, v173, v173
	v_mov_b32_e32 v178, v150
	v_mov_b32_e32 v179, v154
	v_mov_b32_e32 v154, v151
	v_mov_b32_e32 v150, v152
	v_mov_b32_e32 v151, v156
	v_mov_b32_e32 v156, v153
	v_pk_add_f32 v[152:153], v[178:179], v[154:155]
	v_pk_add_f32 v[150:151], v[150:151], v[156:157]
	s_nop 0
	v_pk_add_f32 v[150:151], v[152:153], v[150:151]
	s_nop 0
	v_add_f32_e32 v150, v150, v151
	v_fmamk_f32 v150, v150, 0x3a000000, v164
	v_rsq_f32_e32 v150, v150
	v_max_f32_e32 v151, v172, v172
	v_max_f32_e32 v67, v151, v67
	v_max3_f32 v177, v170, v171, v67
	v_mul_f32_e32 v150, 0x3d8293ee, v150
	v_pk_mul_f32 v[152:153], v[176:177], v[150:151] op_sel_hi:[1,0]
	s_nop 0
	v_fma_f32 v67, v76, v150, -v153
	v_fma_f32 v77, v77, v150, -v153
	v_fma_f32 v78, v78, v150, -v153
	v_fma_f32 v79, v79, v150, -v153
	v_fma_f32 v72, v72, v150, -v153
	v_fma_f32 v73, v73, v150, -v153
	v_fma_f32 v154, v74, v150, -v153
	v_fma_f32 v155, v75, v150, -v153
	v_fma_f32 v68, v68, v150, -v153
	v_fma_f32 v69, v69, v150, -v153
	v_fma_f32 v70, v70, v150, -v153
	v_fma_f32 v71, v71, v150, -v153
	v_fma_f32 v64, v64, v150, -v153
	v_fma_f32 v65, v65, v150, -v153
	v_fma_f32 v156, v66, v150, -v153
	v_exp_f32_e32 v76, v67
	v_exp_f32_e32 v77, v77
	v_exp_f32_e32 v150, v78
	v_exp_f32_e32 v151, v79
	v_exp_f32_e32 v74, v72
	v_exp_f32_e32 v75, v73
	v_exp_f32_e32 v78, v154
	v_exp_f32_e32 v79, v155
	v_sub_f32_e32 v152, v152, v153
	v_exp_f32_e32 v68, v68
	v_exp_f32_e32 v69, v69
	v_exp_f32_e32 v72, v70
	v_exp_f32_e32 v73, v71
	v_exp_f32_e32 v66, v64
	v_exp_f32_e32 v67, v65
	v_exp_f32_e32 v70, v156
	v_exp_f32_e32 v71, v152
	v_add_f32_e32 v64, v76, v77
	v_add_f32_e32 v65, v150, v151
	v_add_f32_e32 v152, v74, v75
	v_add_f32_e32 v153, v78, v79
	v_add_f32_e32 v64, v64, v65
	v_add_f32_e32 v154, v68, v69
	v_add_f32_e32 v155, v72, v73
	v_add_f32_e32 v65, v152, v153
	v_add_f32_e32 v64, 0, v64
	v_add_f32_e32 v156, v66, v67
	v_add_f32_e32 v157, v70, v71
	v_add_f32_e32 v152, v154, v155
	v_add_f32_e32 v64, v65, v64
	v_add_f32_e32 v64, v152, v64
	v_add_f32_e32 v65, v156, v157
	v_add_f32_e32 v64, v65, v64
	ds_bpermute_b32 v65, v136, v64
	s_waitcnt lgkmcnt(0)
	v_add_f32_e32 v64, v64, v65
	ds_bpermute_b32 v65, v165, v64
	s_and_saveexec_b64 s[46:47], vcc
	s_cbranch_execz .LBB0_623
	v_lshlrev_b32_e32 v152, 2, v168
	v_lshl_add_u32 v152, v152, 2, s63
	s_waitcnt lgkmcnt(0)
	v_add_f32_e32 v64, v64, v65
	ds_write_b32 v152, v64
.LBB0_623:
	s_or_b64 exec, exec, s[46:47]
	v_add_u32_e32 v169, 0x80, v163
	v_add_u32_e32 v64, s39, v169
	s_waitcnt lgkmcnt(0)
	v_ashrrev_i32_e32 v65, 31, v64
	v_lshlrev_b64 v[152:153], 5, v[64:65]
	v_lshl_add_u64 v[156:157], s[22:23], 0, v[152:153]
	v_mov_b32_e32 v152, v224
	v_mov_b32_e32 v153, v225
	v_mov_b32_e32 v154, v226
	v_mov_b32_e32 v155, v227
	v_mov_b32_e32 v170, v228
	v_mov_b32_e32 v171, v229
	v_mov_b32_e32 v172, v230
	v_mov_b32_e32 v173, v231
	v_lshl_add_u32 v156, v169, 4, 0
	v_add_u32_e32 v156, 0x20000, v156
	ds_read_b128 v[176:179], v156
	v_mov_b32_e32 v156, v51
	s_waitcnt lgkmcnt(0)
	v_max_f32_e32 v51, v179, v179
	v_mov_b32_e32 v180, v152
	v_mov_b32_e32 v181, v170
	v_mov_b32_e32 v170, v153
	v_mov_b32_e32 v152, v154
	v_mov_b32_e32 v153, v172
	v_mov_b32_e32 v172, v155
	v_pk_add_f32 v[154:155], v[180:181], v[170:171]
	v_pk_add_f32 v[152:153], v[152:153], v[172:173]
	s_nop 0
	v_pk_add_f32 v[152:153], v[154:155], v[152:153]
	s_nop 0
	v_add_f32_e32 v152, v152, v153
	v_fmamk_f32 v152, v152, 0x3a000000, v164
	v_rsq_f32_e32 v152, v152
	v_max_f32_e32 v153, v178, v178
	v_max_f32_e32 v51, v153, v51
	v_max3_f32 v157, v176, v177, v51
	v_mul_f32_e32 v152, 0x3d8293ee, v152
	v_pk_mul_f32 v[154:155], v[156:157], v[152:153] op_sel_hi:[1,0]
	s_nop 0
	v_fma_f32 v51, v60, v152, -v155
	v_fma_f32 v60, v61, v152, -v155
	v_fma_f32 v61, v62, v152, -v155
	v_fma_f32 v62, v63, v152, -v155
	v_fma_f32 v63, v56, v152, -v155
	v_fma_f32 v153, v57, v152, -v155
	v_fma_f32 v156, v58, v152, -v155
	v_fma_f32 v157, v59, v152, -v155
	v_exp_f32_e32 v56, v51
	v_exp_f32_e32 v57, v60
	v_exp_f32_e32 v60, v61
	v_exp_f32_e32 v61, v62
	v_fma_f32 v52, v52, v152, -v155
	v_fma_f32 v53, v53, v152, -v155
	v_fma_f32 v54, v54, v152, -v155
	v_fma_f32 v55, v55, v152, -v155
	v_fma_f32 v170, v48, v152, -v155
	v_fma_f32 v171, v49, v152, -v155
	v_fma_f32 v172, v50, v152, -v155
	v_exp_f32_e32 v58, v63
	v_exp_f32_e32 v59, v153
	v_exp_f32_e32 v152, v156
	v_exp_f32_e32 v153, v157
	v_sub_f32_e32 v154, v154, v155
	v_exp_f32_e32 v48, v52
	v_exp_f32_e32 v49, v53
	v_exp_f32_e32 v52, v54
	v_exp_f32_e32 v53, v55
	v_exp_f32_e32 v50, v170
	v_exp_f32_e32 v51, v171
	v_exp_f32_e32 v54, v172
	v_exp_f32_e32 v55, v154
	v_add_f32_e32 v62, v56, v57
	v_add_f32_e32 v63, v60, v61
	v_add_f32_e32 v154, v58, v59
	v_add_f32_e32 v155, v152, v153
	v_add_f32_e32 v62, v62, v63
	v_add_f32_e32 v156, v48, v49
	v_add_f32_e32 v157, v52, v53
	v_add_f32_e32 v63, v154, v155
	v_add_f32_e32 v62, 0, v62
	v_add_f32_e32 v170, v50, v51
	v_add_f32_e32 v171, v54, v55
	v_add_f32_e32 v154, v156, v157
	v_add_f32_e32 v62, v63, v62
	v_add_f32_e32 v62, v154, v62
	v_add_f32_e32 v63, v170, v171
	v_add_f32_e32 v62, v63, v62
	ds_bpermute_b32 v63, v136, v62
	s_waitcnt lgkmcnt(0)
	v_add_f32_e32 v62, v62, v63
	ds_bpermute_b32 v63, v165, v62
	s_and_saveexec_b64 s[46:47], vcc
	s_cbranch_execz .LBB0_625
	v_lshlrev_b32_e32 v154, 2, v169
	v_lshl_add_u32 v154, v154, 2, s63
	s_waitcnt lgkmcnt(0)
	v_add_f32_e32 v62, v62, v63
	ds_write_b32 v154, v62
.LBB0_625:
	s_or_b64 exec, exec, s[46:47]
	v_add_u32_e32 v170, 0x90, v163
	v_add_u32_e32 v62, s39, v170
	s_waitcnt lgkmcnt(0)
	v_ashrrev_i32_e32 v63, 31, v62
	v_lshlrev_b64 v[154:155], 5, v[62:63]
	v_lshl_add_u64 v[172:173], s[22:23], 0, v[154:155]
	v_mov_b32_e32 v154, v232
	v_mov_b32_e32 v155, v233
	v_mov_b32_e32 v156, v234
	v_mov_b32_e32 v157, v235
	v_mov_b32_e32 v176, v236
	v_mov_b32_e32 v177, v237
	v_mov_b32_e32 v178, v238
	v_mov_b32_e32 v179, v239
	v_lshl_add_u32 v171, v170, 4, 0
	v_add_u32_e32 v171, 0x20000, v171
	ds_read_b128 v[180:183], v171
	v_mov_b32_e32 v172, v35
	s_waitcnt lgkmcnt(0)
	v_max_f32_e32 v35, v183, v183
	v_mov_b32_e32 v184, v154
	v_mov_b32_e32 v185, v176
	v_mov_b32_e32 v176, v155
	v_mov_b32_e32 v154, v156
	v_mov_b32_e32 v155, v178
	v_mov_b32_e32 v178, v157
	v_pk_add_f32 v[156:157], v[184:185], v[176:177]
	v_pk_add_f32 v[154:155], v[154:155], v[178:179]
	s_nop 0
	v_pk_add_f32 v[154:155], v[156:157], v[154:155]
	s_nop 0
	v_add_f32_e32 v154, v154, v155
	v_fmamk_f32 v154, v154, 0x3a000000, v164
	v_rsq_f32_e32 v154, v154
	v_max_f32_e32 v155, v182, v182
	v_max_f32_e32 v35, v155, v35
	v_max3_f32 v173, v180, v181, v35
	v_mul_f32_e32 v154, 0x3d8293ee, v154
	v_pk_mul_f32 v[156:157], v[172:173], v[154:155] op_sel_hi:[1,0]
	s_nop 0
	v_fma_f32 v35, v44, v154, -v157
	v_fma_f32 v45, v45, v154, -v157
	v_fma_f32 v46, v46, v154, -v157
	v_fma_f32 v47, v47, v154, -v157
	v_fma_f32 v40, v40, v154, -v157
	v_fma_f32 v41, v41, v154, -v157
	v_fma_f32 v171, v42, v154, -v157
	v_fma_f32 v172, v43, v154, -v157
	v_fma_f32 v36, v36, v154, -v157
	v_fma_f32 v37, v37, v154, -v157
	v_fma_f32 v38, v38, v154, -v157
	v_fma_f32 v39, v39, v154, -v157
	v_fma_f32 v32, v32, v154, -v157
	v_fma_f32 v33, v33, v154, -v157
	v_fma_f32 v173, v34, v154, -v157
	v_exp_f32_e32 v44, v35
	v_exp_f32_e32 v45, v45
	v_exp_f32_e32 v154, v46
	v_exp_f32_e32 v155, v47
	v_exp_f32_e32 v42, v40
	v_exp_f32_e32 v43, v41
	v_exp_f32_e32 v46, v171
	v_exp_f32_e32 v47, v172
	v_sub_f32_e32 v156, v156, v157
	v_exp_f32_e32 v36, v36
	v_exp_f32_e32 v37, v37
	v_exp_f32_e32 v40, v38
	v_exp_f32_e32 v41, v39
	v_exp_f32_e32 v34, v32
	v_exp_f32_e32 v35, v33
	v_exp_f32_e32 v38, v173
	v_exp_f32_e32 v39, v156
	v_add_f32_e32 v32, v44, v45
	v_add_f32_e32 v33, v154, v155
	v_add_f32_e32 v156, v42, v43
	v_add_f32_e32 v157, v46, v47
	v_add_f32_e32 v32, v32, v33
	v_add_f32_e32 v171, v36, v37
	v_add_f32_e32 v172, v40, v41
	v_add_f32_e32 v33, v156, v157
	v_add_f32_e32 v32, 0, v32
	v_add_f32_e32 v173, v34, v35
	v_add_f32_e32 v176, v38, v39
	v_add_f32_e32 v156, v171, v172
	v_add_f32_e32 v32, v33, v32
	v_add_f32_e32 v32, v156, v32
	v_add_f32_e32 v33, v173, v176
	v_add_f32_e32 v32, v33, v32
	ds_bpermute_b32 v33, v136, v32
	s_waitcnt lgkmcnt(0)
	v_add_f32_e32 v32, v32, v33
	ds_bpermute_b32 v33, v165, v32
	s_and_saveexec_b64 s[46:47], vcc
	s_cbranch_execz .LBB0_627
	v_lshlrev_b32_e32 v156, 2, v170
	v_lshl_add_u32 v156, v156, 2, s63
	s_waitcnt lgkmcnt(0)
	v_add_f32_e32 v32, v32, v33
	ds_write_b32 v156, v32
.LBB0_627:
	s_or_b64 exec, exec, s[46:47]
	v_add_u32_e32 v171, 0xa0, v163
	v_add_u32_e32 v32, s39, v171
	s_waitcnt lgkmcnt(0)
	v_ashrrev_i32_e32 v33, 31, v32
	v_lshlrev_b64 v[156:157], 5, v[32:33]
	v_lshl_add_u64 v[156:157], s[22:23], 0, v[156:157]
	s_waitcnt vmcnt(2)
	v_mov_b32_e32 v176, v192
	v_mov_b32_e32 v177, v193
	v_mov_b32_e32 v178, v194
	v_mov_b32_e32 v179, v195
	v_mov_b32_e32 v180, v196
	v_mov_b32_e32 v181, v197
	v_mov_b32_e32 v182, v198
	v_mov_b32_e32 v183, v199
	v_lshl_add_u32 v156, v171, 4, 0
	v_add_u32_e32 v156, 0x20000, v156
	ds_read_b128 v[184:187], v156
	v_mov_b32_e32 v156, v19
	s_waitcnt lgkmcnt(0)
	v_max_f32_e32 v19, v187, v187
	v_mov_b32_e32 v172, v176
	v_mov_b32_e32 v173, v180
	v_mov_b32_e32 v180, v177
	v_mov_b32_e32 v176, v178
	v_mov_b32_e32 v177, v182
	v_mov_b32_e32 v182, v179
	v_pk_add_f32 v[172:173], v[172:173], v[180:181]
	v_pk_add_f32 v[176:177], v[176:177], v[182:183]
	s_nop 0
	v_pk_add_f32 v[172:173], v[172:173], v[176:177]
	s_nop 0
	v_add_f32_e32 v157, v172, v173
	v_fmamk_f32 v157, v157, 0x3a000000, v164
	v_rsq_f32_e32 v172, v157
	v_max_f32_e32 v157, v186, v186
	v_max_f32_e32 v19, v157, v19
	v_max3_f32 v157, v184, v185, v19
	v_mul_f32_e32 v172, 0x3d8293ee, v172
	v_pk_mul_f32 v[156:157], v[156:157], v[172:173] op_sel_hi:[1,0]
	s_nop 0
	v_fma_f32 v19, v28, v172, -v157
	v_fma_f32 v28, v29, v172, -v157
	v_fma_f32 v29, v30, v172, -v157
	v_fma_f32 v30, v31, v172, -v157
	v_fma_f32 v31, v24, v172, -v157
	v_fma_f32 v173, v25, v172, -v157
	v_fma_f32 v176, v26, v172, -v157
	v_fma_f32 v177, v27, v172, -v157
	v_exp_f32_e32 v24, v19
	v_exp_f32_e32 v25, v28
	v_exp_f32_e32 v28, v29
	v_exp_f32_e32 v29, v30
	v_fma_f32 v20, v20, v172, -v157
	v_fma_f32 v21, v21, v172, -v157
	v_fma_f32 v22, v22, v172, -v157
	v_fma_f32 v23, v23, v172, -v157
	v_fma_f32 v178, v16, v172, -v157
	v_fma_f32 v179, v17, v172, -v157
	v_fma_f32 v172, v18, v172, -v157
	v_sub_f32_e32 v180, v156, v157
	v_exp_f32_e32 v26, v31
	v_exp_f32_e32 v27, v173
	v_exp_f32_e32 v156, v176
	v_exp_f32_e32 v157, v177
	v_exp_f32_e32 v16, v20
	v_exp_f32_e32 v17, v21
	v_exp_f32_e32 v20, v22
	v_exp_f32_e32 v21, v23
	v_exp_f32_e32 v18, v178
	v_exp_f32_e32 v19, v179
	v_exp_f32_e32 v22, v172
	v_exp_f32_e32 v23, v180
	v_add_f32_e32 v30, v24, v25
	v_add_f32_e32 v31, v28, v29
	v_add_f32_e32 v172, v26, v27
	v_add_f32_e32 v173, v156, v157
	v_add_f32_e32 v30, v30, v31
	v_add_f32_e32 v176, v16, v17
	v_add_f32_e32 v177, v20, v21
	v_add_f32_e32 v31, v172, v173
	v_add_f32_e32 v30, 0, v30
	v_add_f32_e32 v178, v18, v19
	v_add_f32_e32 v179, v22, v23
	v_add_f32_e32 v172, v176, v177
	v_add_f32_e32 v30, v31, v30
	v_add_f32_e32 v30, v172, v30
	v_add_f32_e32 v31, v178, v179
	v_add_f32_e32 v30, v31, v30
	ds_bpermute_b32 v31, v136, v30
	s_waitcnt lgkmcnt(0)
	v_add_f32_e32 v30, v30, v31
	ds_bpermute_b32 v31, v165, v30
	s_and_saveexec_b64 s[46:47], vcc
	s_cbranch_execz .LBB0_629
	v_lshlrev_b32_e32 v172, 2, v171
	v_lshl_add_u32 v172, v172, 2, s63
	s_waitcnt lgkmcnt(0)
	v_add_f32_e32 v30, v30, v31
	ds_write_b32 v172, v30
.LBB0_629:
	s_or_b64 exec, exec, s[46:47]
	v_add_u32_e32 v172, 0xb0, v163
	v_add_u32_e32 v30, s39, v172
	s_waitcnt lgkmcnt(0)
	v_ashrrev_i32_e32 v31, 31, v30
	v_lshlrev_b64 v[176:177], 5, v[30:31]
	v_lshl_add_u64 v[180:181], s[22:23], 0, v[176:177]
	s_waitcnt vmcnt(0)
	v_mov_b32_e32 v176, v200
	v_mov_b32_e32 v177, v201
	v_mov_b32_e32 v178, v202
	v_mov_b32_e32 v179, v203
	v_mov_b32_e32 v180, v204
	v_mov_b32_e32 v181, v205
	v_mov_b32_e32 v182, v206
	v_mov_b32_e32 v183, v207
	v_lshl_add_u32 v173, v172, 4, 0
	v_add_u32_e32 v173, 0x20000, v173
	ds_read_b128 v[184:187], v173
	v_mov_b32_e32 v188, v3
	s_waitcnt lgkmcnt(0)
	v_max_f32_e32 v3, v187, v187
	v_mov_b32_e32 v190, v176
	v_mov_b32_e32 v191, v180
	v_mov_b32_e32 v180, v177
	v_mov_b32_e32 v176, v178
	v_mov_b32_e32 v177, v182
	v_mov_b32_e32 v182, v179
	v_pk_add_f32 v[178:179], v[190:191], v[180:181]
	v_pk_add_f32 v[176:177], v[176:177], v[182:183]
	s_nop 0
	v_pk_add_f32 v[176:177], v[178:179], v[176:177]
	s_nop 0
	v_add_f32_e32 v173, v176, v177
	v_fmamk_f32 v173, v173, 0x3a000000, v164
	v_rsq_f32_e32 v173, v173
	v_max_f32_e32 v176, v186, v186
	v_max_f32_e32 v3, v176, v3
	v_max3_f32 v189, v184, v185, v3
	v_mul_f32_e32 v176, 0x3d8293ee, v173
	v_pk_mul_f32 v[178:179], v[188:189], v[176:177] op_sel_hi:[1,0]
	s_nop 0
	v_fma_f32 v3, v12, v176, -v179
	v_fma_f32 v12, v13, v176, -v179
	v_fma_f32 v13, v14, v176, -v179
	v_fma_f32 v15, v15, v176, -v179
	v_fma_f32 v8, v8, v176, -v179
	v_fma_f32 v9, v9, v176, -v179
	v_fma_f32 v173, v10, v176, -v179
	v_fma_f32 v177, v11, v176, -v179
	v_exp_f32_e32 v10, v3
	v_exp_f32_e32 v11, v12
	v_exp_f32_e32 v14, v13
	v_exp_f32_e32 v15, v15
	v_fma_f32 v4, v4, v176, -v179
	v_fma_f32 v5, v5, v176, -v179
	v_fma_f32 v6, v6, v176, -v179
	v_fma_f32 v7, v7, v176, -v179
	v_exp_f32_e32 v8, v8
	v_exp_f32_e32 v9, v9
	v_exp_f32_e32 v12, v173
	v_exp_f32_e32 v13, v177
	v_fma_f32 v0, v0, v176, -v179
	v_fma_f32 v1, v1, v176, -v179
	v_fma_f32 v176, v2, v176, -v179
	v_sub_f32_e32 v178, v178, v179
	v_exp_f32_e32 v2, v4
	v_exp_f32_e32 v3, v5
	v_exp_f32_e32 v6, v6
	v_exp_f32_e32 v7, v7
	v_exp_f32_e32 v0, v0
	v_exp_f32_e32 v1, v1
	v_exp_f32_e32 v4, v176
	v_exp_f32_e32 v5, v178
	v_add_f32_e32 v173, v10, v11
	v_add_f32_e32 v176, v14, v15
	v_add_f32_e32 v177, v8, v9
	v_add_f32_e32 v178, v12, v13
	v_add_f32_e32 v173, v173, v176
	v_add_f32_e32 v179, v2, v3
	v_add_f32_e32 v180, v6, v7
	v_add_f32_e32 v176, v177, v178
	v_add_f32_e32 v173, 0, v173
	v_add_f32_e32 v181, v0, v1
	v_add_f32_e32 v182, v4, v5
	v_add_f32_e32 v177, v179, v180
	v_add_f32_e32 v173, v176, v173
	v_add_f32_e32 v173, v177, v173
	v_add_f32_e32 v176, v181, v182
	v_add_f32_e32 v173, v176, v173
	ds_bpermute_b32 v136, v136, v173
	s_waitcnt lgkmcnt(0)
	v_add_f32_e32 v136, v173, v136
	ds_bpermute_b32 v165, v165, v136
	s_and_saveexec_b64 s[46:47], vcc
	s_cbranch_execz .LBB0_631
	v_lshlrev_b32_e32 v173, 2, v172
	v_lshl_add_u32 v173, v173, 2, s63
	s_waitcnt lgkmcnt(0)
	v_add_f32_e32 v136, v136, v165
	ds_write_b32 v173, v136

.LBB0_707:
	ds_read_b128 v[128:131], v188
	ds_read_b128 v[132:135], v188 offset:1024
	ds_read_b128 v[136:139], v188 offset:2048
	ds_read_b128 v[140:143], v188 offset:3072
	ds_read_b128 v[144:147], v189
	ds_read_b128 v[148:151], v189 offset:1024
	ds_read_b128 v[164:167], v189 offset:2048
	ds_read_b128 v[192:195], v189 offset:3072
	s_add_u32 s60, s50, 0xfffc0080
	s_addc_u32 s61, s51, -1
	s_cmp_eq_u32 s73, 12
	s_cselect_b32 s63, s27, s61
	s_cselect_b32 s62, s41, s60
	s_cselect_b32 s61, s49, s72
	s_cselect_b32 s60, s70, s71
	s_add_i32 m0, s1, 0xc000
	ds_read_b128 v[196:199], v190
	ds_read_b128 v[200:203], v190 offset:1024
	ds_read_b128 v[204:207], v190 offset:2048
	ds_read_b128 v[208:211], v190 offset:3072
	ds_read_b128 v[212:215], v190 offset:4096
	ds_read_b128 v[216:219], v190 offset:5120
	ds_read_b128 v[220:223], v190 offset:6144
	ds_read_b128 v[224:227], v190 offset:7168
	global_load_lds_dwordx4 v160, s[50:51]
	s_add_i32 m0, s1, 0xe000
	s_nop 0
	global_load_lds_dwordx4 v162, s[50:51]
	s_waitcnt vmcnt(8)
	s_waitcnt lgkmcnt(0)
	s_barrier
	s_setprio 1
	s_waitcnt lgkmcnt(0)
	v_mfma_f32_16x16x32_bf16 v[124:127], v[128:131], v[196:199], v[124:127]
	v_mfma_f32_16x16x32_bf16 v[124:127], v[132:135], v[200:203], v[124:127]
	v_mfma_f32_16x16x32_bf16 v[120:123], v[136:139], v[196:199], v[120:123]
	v_mfma_f32_16x16x32_bf16 v[120:123], v[140:143], v[200:203], v[120:123]
	v_mfma_f32_16x16x32_bf16 v[108:111], v[128:131], v[204:207], v[108:111]
	v_mfma_f32_16x16x32_bf16 v[108:111], v[132:135], v[208:211], v[108:111]
	v_mfma_f32_16x16x32_bf16 v[104:107], v[136:139], v[204:207], v[104:107]
	v_mfma_f32_16x16x32_bf16 v[104:107], v[140:143], v[208:211], v[104:107]
	v_mfma_f32_16x16x32_bf16 v[92:95], v[128:131], v[212:215], v[92:95]
	v_mfma_f32_16x16x32_bf16 v[92:95], v[132:135], v[216:219], v[92:95]
	v_mfma_f32_16x16x32_bf16 v[88:91], v[136:139], v[212:215], v[88:91]
	v_mfma_f32_16x16x32_bf16 v[88:91], v[140:143], v[216:219], v[88:91]
	v_mfma_f32_16x16x32_bf16 v[76:79], v[128:131], v[220:223], v[76:79]
	v_mfma_f32_16x16x32_bf16 v[76:79], v[132:135], v[224:227], v[76:79]
	v_mfma_f32_16x16x32_bf16 v[72:75], v[136:139], v[220:223], v[72:75]
	v_mfma_f32_16x16x32_bf16 v[72:75], v[140:143], v[224:227], v[72:75]
	s_setprio 0
	s_setprio 1
	v_mfma_f32_16x16x32_bf16 v[116:119], v[144:147], v[196:199], v[116:119]
	v_mfma_f32_16x16x32_bf16 v[116:119], v[148:151], v[200:203], v[116:119]
	v_mfma_f32_16x16x32_bf16 v[112:115], v[164:167], v[196:199], v[112:115]
	v_mfma_f32_16x16x32_bf16 v[112:115], v[192:195], v[200:203], v[112:115]
	v_mfma_f32_16x16x32_bf16 v[100:103], v[144:147], v[204:207], v[100:103]
	v_mfma_f32_16x16x32_bf16 v[100:103], v[148:151], v[208:211], v[100:103]
	v_mfma_f32_16x16x32_bf16 v[96:99], v[164:167], v[204:207], v[96:99]
	v_mfma_f32_16x16x32_bf16 v[96:99], v[192:195], v[208:211], v[96:99]
	v_mfma_f32_16x16x32_bf16 v[84:87], v[144:147], v[212:215], v[84:87]
	v_mfma_f32_16x16x32_bf16 v[84:87], v[148:151], v[216:219], v[84:87]
	v_mfma_f32_16x16x32_bf16 v[80:83], v[164:167], v[212:215], v[80:83]
	v_mfma_f32_16x16x32_bf16 v[80:83], v[192:195], v[216:219], v[80:83]
	v_mfma_f32_16x16x32_bf16 v[68:71], v[144:147], v[220:223], v[68:71]
	v_mfma_f32_16x16x32_bf16 v[68:71], v[148:151], v[224:227], v[68:71]
	v_mfma_f32_16x16x32_bf16 v[64:67], v[164:167], v[220:223], v[64:67]
	v_mfma_f32_16x16x32_bf16 v[64:67], v[192:195], v[224:227], v[64:67]
	s_setprio 0
	s_barrier
	s_add_i32 s74, s66, s0
	s_add_u32 s98, s60, s36
	s_addc_u32 s99, s61, s37
	s_mov_b32 m0, s74
	ds_read_b128 v[196:199], v190 offset:16384
	ds_read_b128 v[200:203], v190 offset:17408
	ds_read_b128 v[204:207], v190 offset:18432
	ds_read_b128 v[208:211], v190 offset:19456
	ds_read_b128 v[212:215], v190 offset:20480
	ds_read_b128 v[216:219], v190 offset:21504
	ds_read_b128 v[220:223], v190 offset:22528
	ds_read_b128 v[224:227], v190 offset:23552
	global_load_lds_dwordx4 v154, s[60:61]
	s_add_i32 m0, s74, 0x2000
	s_add_u32 s74, s60, 0x40000
	s_addc_u32 s75, s61, 0
	s_add_i32 s76, s67, s0
	global_load_lds_dwordx4 v158, s[60:61]
	s_mov_b32 m0, s76
	s_nop 0
	global_load_lds_dwordx4 v154, s[74:75]
	s_add_i32 m0, s76, 0x2000
	s_nop 0
	global_load_lds_dwordx4 v158, s[74:75]
	s_add_u32 s100, s62, s36
	s_addc_u32 s101, s63, s37
	s_mov_b32 m0, s1
	s_nop 0
	global_load_lds_dwordx4 v152, s[62:63]
	s_mov_b32 m0, s10
	s_nop 0
	global_load_lds_dwordx4 v156, s[62:63]
	s_waitcnt vmcnt(8)
	s_waitcnt lgkmcnt(0)
	s_barrier
	s_setprio 1
	s_waitcnt lgkmcnt(0)
	v_mfma_f32_16x16x32_bf16 v[60:63], v[128:131], v[196:199], v[60:63]
	v_mfma_f32_16x16x32_bf16 v[60:63], v[132:135], v[200:203], v[60:63]
	v_mfma_f32_16x16x32_bf16 v[56:59], v[136:139], v[196:199], v[56:59]
	v_mfma_f32_16x16x32_bf16 v[56:59], v[140:143], v[200:203], v[56:59]
	v_mfma_f32_16x16x32_bf16 v[44:47], v[128:131], v[204:207], v[44:47]
	v_mfma_f32_16x16x32_bf16 v[44:47], v[132:135], v[208:211], v[44:47]
	v_mfma_f32_16x16x32_bf16 v[40:43], v[136:139], v[204:207], v[40:43]
	v_mfma_f32_16x16x32_bf16 v[40:43], v[140:143], v[208:211], v[40:43]
	v_mfma_f32_16x16x32_bf16 v[28:31], v[128:131], v[212:215], v[28:31]
	v_mfma_f32_16x16x32_bf16 v[28:31], v[132:135], v[216:219], v[28:31]
	v_mfma_f32_16x16x32_bf16 v[24:27], v[136:139], v[212:215], v[24:27]
	v_mfma_f32_16x16x32_bf16 v[24:27], v[140:143], v[216:219], v[24:27]
	v_mfma_f32_16x16x32_bf16 v[12:15], v[128:131], v[220:223], v[12:15]
	v_mfma_f32_16x16x32_bf16 v[12:15], v[132:135], v[224:227], v[12:15]
	v_mfma_f32_16x16x32_bf16 v[8:11], v[136:139], v[220:223], v[8:11]
	v_mfma_f32_16x16x32_bf16 v[8:11], v[140:143], v[224:227], v[8:11]
	s_setprio 0
	s_setprio 1
	v_mfma_f32_16x16x32_bf16 v[52:55], v[144:147], v[196:199], v[52:55]
	v_mfma_f32_16x16x32_bf16 v[52:55], v[148:151], v[200:203], v[52:55]
	v_mfma_f32_16x16x32_bf16 v[48:51], v[164:167], v[196:199], v[48:51]
	v_mfma_f32_16x16x32_bf16 v[48:51], v[192:195], v[200:203], v[48:51]
	v_mfma_f32_16x16x32_bf16 v[36:39], v[144:147], v[204:207], v[36:39]
	v_mfma_f32_16x16x32_bf16 v[36:39], v[148:151], v[208:211], v[36:39]
	v_mfma_f32_16x16x32_bf16 v[32:35], v[164:167], v[204:207], v[32:35]
	v_mfma_f32_16x16x32_bf16 v[32:35], v[192:195], v[208:211], v[32:35]
	v_mfma_f32_16x16x32_bf16 v[20:23], v[144:147], v[212:215], v[20:23]
	v_mfma_f32_16x16x32_bf16 v[20:23], v[148:151], v[216:219], v[20:23]
	v_mfma_f32_16x16x32_bf16 v[16:19], v[164:167], v[212:215], v[16:19]
	v_mfma_f32_16x16x32_bf16 v[16:19], v[192:195], v[216:219], v[16:19]
	v_mfma_f32_16x16x32_bf16 v[4:7], v[144:147], v[220:223], v[4:7]
	v_mfma_f32_16x16x32_bf16 v[4:7], v[148:151], v[224:227], v[4:7]
	v_mfma_f32_16x16x32_bf16 v[0:3], v[164:167], v[220:223], v[0:3]
	v_mfma_f32_16x16x32_bf16 v[0:3], v[192:195], v[224:227], v[0:3]
	s_setprio 0
	s_barrier
	s_add_i32 s74, 0, 0x18000
	s_add_i32 s75, 0, 0x1c000
	v_add_u32_e32 v140, s74, v171
	v_add_u32_e32 v192, s75, v171
	ds_read_b128 v[128:131], v140
	ds_read_b128 v[132:135], v140 offset:1024
	ds_read_b128 v[136:139], v140 offset:2048
	ds_read_b128 v[140:143], v140 offset:3072
	ds_read_b128 v[144:147], v192
	ds_read_b128 v[148:151], v192 offset:1024
	ds_read_b128 v[164:167], v192 offset:2048
	ds_read_b128 v[192:195], v192 offset:3072
	s_add_u32 s62, s62, 0x40000
	s_addc_u32 s63, s63, 0
	s_mov_b32 m0, s11
	ds_read_b128 v[196:199], v190 offset:32768
	ds_read_b128 v[200:203], v190 offset:33792
	ds_read_b128 v[204:207], v190 offset:34816
	ds_read_b128 v[208:211], v190 offset:35840
	ds_read_b128 v[212:215], v190 offset:36864
	ds_read_b128 v[216:219], v190 offset:37888
	ds_read_b128 v[220:223], v190 offset:38912
	ds_read_b128 v[224:227], v190 offset:39936
	global_load_lds_dwordx4 v152, s[62:63]
	s_mov_b32 m0, s14
	s_nop 0
	global_load_lds_dwordx4 v156, s[62:63]
	s_waitcnt vmcnt(8)
	s_waitcnt lgkmcnt(0)
	s_barrier
	s_setprio 1
	s_waitcnt lgkmcnt(0)
	v_mfma_f32_16x16x32_bf16 v[124:127], v[128:131], v[196:199], v[124:127]
	v_mfma_f32_16x16x32_bf16 v[124:127], v[132:135], v[200:203], v[124:127]
	v_mfma_f32_16x16x32_bf16 v[120:123], v[136:139], v[196:199], v[120:123]
	v_mfma_f32_16x16x32_bf16 v[120:123], v[140:143], v[200:203], v[120:123]
	v_mfma_f32_16x16x32_bf16 v[108:111], v[128:131], v[204:207], v[108:111]
	v_mfma_f32_16x16x32_bf16 v[108:111], v[132:135], v[208:211], v[108:111]
	v_mfma_f32_16x16x32_bf16 v[104:107], v[136:139], v[204:207], v[104:107]
	v_mfma_f32_16x16x32_bf16 v[104:107], v[140:143], v[208:211], v[104:107]
	v_mfma_f32_16x16x32_bf16 v[92:95], v[128:131], v[212:215], v[92:95]
	v_mfma_f32_16x16x32_bf16 v[92:95], v[132:135], v[216:219], v[92:95]
	v_mfma_f32_16x16x32_bf16 v[88:91], v[136:139], v[212:215], v[88:91]
	v_mfma_f32_16x16x32_bf16 v[88:91], v[140:143], v[216:219], v[88:91]
	v_mfma_f32_16x16x32_bf16 v[76:79], v[128:131], v[220:223], v[76:79]
	v_mfma_f32_16x16x32_bf16 v[76:79], v[132:135], v[224:227], v[76:79]
	v_mfma_f32_16x16x32_bf16 v[72:75], v[136:139], v[220:223], v[72:75]
	v_mfma_f32_16x16x32_bf16 v[72:75], v[140:143], v[224:227], v[72:75]
	s_setprio 0
	s_setprio 1
	v_mfma_f32_16x16x32_bf16 v[116:119], v[144:147], v[196:199], v[116:119]
	v_mfma_f32_16x16x32_bf16 v[116:119], v[148:151], v[200:203], v[116:119]
	v_mfma_f32_16x16x32_bf16 v[112:115], v[164:167], v[196:199], v[112:115]
	v_mfma_f32_16x16x32_bf16 v[112:115], v[192:195], v[200:203], v[112:115]
	v_mfma_f32_16x16x32_bf16 v[100:103], v[144:147], v[204:207], v[100:103]
	v_mfma_f32_16x16x32_bf16 v[100:103], v[148:151], v[208:211], v[100:103]
	v_mfma_f32_16x16x32_bf16 v[96:99], v[164:167], v[204:207], v[96:99]
	v_mfma_f32_16x16x32_bf16 v[96:99], v[192:195], v[208:211], v[96:99]
	v_mfma_f32_16x16x32_bf16 v[84:87], v[144:147], v[212:215], v[84:87]
	v_mfma_f32_16x16x32_bf16 v[84:87], v[148:151], v[216:219], v[84:87]
	v_mfma_f32_16x16x32_bf16 v[80:83], v[164:167], v[212:215], v[80:83]
	v_mfma_f32_16x16x32_bf16 v[80:83], v[192:195], v[216:219], v[80:83]
	v_mfma_f32_16x16x32_bf16 v[68:71], v[144:147], v[220:223], v[68:71]
	v_mfma_f32_16x16x32_bf16 v[68:71], v[148:151], v[224:227], v[68:71]
	v_mfma_f32_16x16x32_bf16 v[64:67], v[164:167], v[220:223], v[64:67]
	v_mfma_f32_16x16x32_bf16 v[64:67], v[192:195], v[224:227], v[64:67]
	s_setprio 0
	s_barrier
	s_add_i32 s62, s74, s0
	s_mov_b32 m0, s62
	ds_read_b128 v[196:199], v190 offset:49152
	ds_read_b128 v[200:203], v190 offset:50176
	ds_read_b128 v[204:207], v190 offset:51200
	ds_read_b128 v[208:211], v190 offset:52224
	ds_read_b128 v[212:215], v190 offset:53248
	ds_read_b128 v[216:219], v190 offset:54272
	ds_read_b128 v[220:223], v190 offset:55296
	ds_read_b128 v[224:227], v190 offset:56320
	global_load_lds_dwordx4 v154, s[98:99]
	s_add_i32 m0, s62, 0x2000
	s_add_u32 s60, s60, 0x40080
	s_addc_u32 s61, s61, 0
	s_add_i32 s62, s75, s0
	global_load_lds_dwordx4 v158, s[98:99]
	s_mov_b32 m0, s62
	s_nop 0
	global_load_lds_dwordx4 v154, s[60:61]
	s_add_i32 m0, s62, 0x2000
	s_nop 0
	global_load_lds_dwordx4 v158, s[60:61]
	s_mov_b32 m0, s15
	s_nop 0
	global_load_lds_dwordx4 v152, s[100:101]
	s_mov_b32 m0, s33
	s_nop 0
	global_load_lds_dwordx4 v156, s[100:101]
	s_waitcnt vmcnt(8)
	s_waitcnt lgkmcnt(0)
	s_barrier
	s_setprio 1
	s_waitcnt lgkmcnt(0)
	v_mfma_f32_16x16x32_bf16 v[60:63], v[128:131], v[196:199], v[60:63]
	v_mfma_f32_16x16x32_bf16 v[60:63], v[132:135], v[200:203], v[60:63]
	v_mfma_f32_16x16x32_bf16 v[56:59], v[136:139], v[196:199], v[56:59]
	v_mfma_f32_16x16x32_bf16 v[56:59], v[140:143], v[200:203], v[56:59]
	v_mfma_f32_16x16x32_bf16 v[44:47], v[128:131], v[204:207], v[44:47]
	v_mfma_f32_16x16x32_bf16 v[44:47], v[132:135], v[208:211], v[44:47]
	v_mfma_f32_16x16x32_bf16 v[40:43], v[136:139], v[204:207], v[40:43]
	v_mfma_f32_16x16x32_bf16 v[40:43], v[140:143], v[208:211], v[40:43]
	v_mfma_f32_16x16x32_bf16 v[28:31], v[128:131], v[212:215], v[28:31]
	v_mfma_f32_16x16x32_bf16 v[28:31], v[132:135], v[216:219], v[28:31]
	v_mfma_f32_16x16x32_bf16 v[24:27], v[136:139], v[212:215], v[24:27]
	v_mfma_f32_16x16x32_bf16 v[24:27], v[140:143], v[216:219], v[24:27]
	v_mfma_f32_16x16x32_bf16 v[12:15], v[128:131], v[220:223], v[12:15]
	v_mfma_f32_16x16x32_bf16 v[12:15], v[132:135], v[224:227], v[12:15]
	v_mfma_f32_16x16x32_bf16 v[8:11], v[136:139], v[220:223], v[8:11]
	v_mfma_f32_16x16x32_bf16 v[8:11], v[140:143], v[224:227], v[8:11]
	s_setprio 0
	s_setprio 1
	v_mfma_f32_16x16x32_bf16 v[52:55], v[144:147], v[196:199], v[52:55]
	v_mfma_f32_16x16x32_bf16 v[52:55], v[148:151], v[200:203], v[52:55]
	v_mfma_f32_16x16x32_bf16 v[48:51], v[164:167], v[196:199], v[48:51]
	v_mfma_f32_16x16x32_bf16 v[48:51], v[192:195], v[200:203], v[48:51]
	v_mfma_f32_16x16x32_bf16 v[36:39], v[144:147], v[204:207], v[36:39]
	v_mfma_f32_16x16x32_bf16 v[36:39], v[148:151], v[208:211], v[36:39]
	v_mfma_f32_16x16x32_bf16 v[32:35], v[164:167], v[204:207], v[32:35]
	v_mfma_f32_16x16x32_bf16 v[32:35], v[192:195], v[208:211], v[32:35]
	v_mfma_f32_16x16x32_bf16 v[20:23], v[144:147], v[212:215], v[20:23]
	v_mfma_f32_16x16x32_bf16 v[20:23], v[148:151], v[216:219], v[20:23]
	v_mfma_f32_16x16x32_bf16 v[16:19], v[164:167], v[212:215], v[16:19]
	v_mfma_f32_16x16x32_bf16 v[16:19], v[192:195], v[216:219], v[16:19]
	v_mfma_f32_16x16x32_bf16 v[4:7], v[144:147], v[220:223], v[4:7]
	v_mfma_f32_16x16x32_bf16 v[4:7], v[148:151], v[224:227], v[4:7]
	v_mfma_f32_16x16x32_bf16 v[0:3], v[164:167], v[220:223], v[0:3]
	v_mfma_f32_16x16x32_bf16 v[0:3], v[192:195], v[224:227], v[0:3]
	s_setprio 0
	s_barrier
	s_add_i32 s73, s73, 2
	s_add_u32 s50, s50, 0x100
	s_addc_u32 s51, s51, 0
	s_add_u32 s71, s71, 0x100
	s_addc_u32 s72, s72, 0
	s_cmp_gt_u32 s73, 13
	s_cbranch_scc0 .LBB0_707
	s_and_b64 vcc, exec, s[38:39]
	s_cbranch_vccz .LBB0_710
	s_barrier

.LBB0_975:
	ds_read_b128 v[132:135], v179
	ds_read_b128 v[136:139], v179 offset:1024
	ds_read_b128 v[140:143], v179 offset:2048
	ds_read_b128 v[144:147], v179 offset:3072
	ds_read_b128 v[148:151], v180
	ds_read_b128 v[166:169], v180 offset:1024
	ds_read_b128 v[170:173], v180 offset:2048
	ds_read_b128 v[174:177], v180 offset:3072
	s_add_u32 s22, s20, 0x100
	s_addc_u32 s23, s21, 0
	s_add_u32 s24, s62, s20
	s_addc_u32 s25, s63, s21
	s_cmpk_eq_i32 s64, 0x54
	s_cselect_b32 s26, s16, s24
	s_cselect_b32 s24, 0, s22
	s_cselect_b32 s27, s17, s25
	s_cselect_b32 s25, 0, s23
	s_add_u32 s24, s2, s24
	s_addc_u32 s25, s3, s25
	s_mov_b32 m0, s57
	v_lshl_add_u64 v[218:219], v[128:129], 0, s[20:21]
	ds_read_b128 v[186:189], v181
	ds_read_b128 v[190:193], v181 offset:1024
	ds_read_b128 v[194:197], v181 offset:2048
	ds_read_b128 v[198:201], v181 offset:3072
	ds_read_b128 v[202:205], v181 offset:4096
	ds_read_b128 v[206:209], v181 offset:5120
	ds_read_b128 v[210:213], v181 offset:6144
	ds_read_b128 v[214:217], v181 offset:7168
	global_load_lds_dwordx4 v[218:219], off
	v_lshl_add_u64 v[218:219], v[130:131], 0, s[20:21]
	s_mov_b32 m0, s58
	s_nop 0
	global_load_lds_dwordx4 v[218:219], off
	s_waitcnt vmcnt(8)
	s_waitcnt lgkmcnt(0)
	s_barrier
	s_setprio 1
	s_waitcnt lgkmcnt(0)
	v_mfma_f32_16x16x32_bf16 v[124:127], v[132:135], v[186:189], v[124:127]
	v_mfma_f32_16x16x32_bf16 v[124:127], v[136:139], v[190:193], v[124:127]
	v_mfma_f32_16x16x32_bf16 v[120:123], v[140:143], v[186:189], v[120:123]
	v_mfma_f32_16x16x32_bf16 v[120:123], v[144:147], v[190:193], v[120:123]
	v_mfma_f32_16x16x32_bf16 v[108:111], v[132:135], v[194:197], v[108:111]
	v_mfma_f32_16x16x32_bf16 v[108:111], v[136:139], v[198:201], v[108:111]
	v_mfma_f32_16x16x32_bf16 v[104:107], v[140:143], v[194:197], v[104:107]
	v_mfma_f32_16x16x32_bf16 v[104:107], v[144:147], v[198:201], v[104:107]
	v_mfma_f32_16x16x32_bf16 v[92:95], v[132:135], v[202:205], v[92:95]
	v_mfma_f32_16x16x32_bf16 v[92:95], v[136:139], v[206:209], v[92:95]
	v_mfma_f32_16x16x32_bf16 v[88:91], v[140:143], v[202:205], v[88:91]
	v_mfma_f32_16x16x32_bf16 v[88:91], v[144:147], v[206:209], v[88:91]
	v_mfma_f32_16x16x32_bf16 v[76:79], v[132:135], v[210:213], v[76:79]
	v_mfma_f32_16x16x32_bf16 v[76:79], v[136:139], v[214:217], v[76:79]
	v_mfma_f32_16x16x32_bf16 v[72:75], v[140:143], v[210:213], v[72:75]
	v_mfma_f32_16x16x32_bf16 v[72:75], v[144:147], v[214:217], v[72:75]
	s_setprio 0
	s_setprio 1
	v_mfma_f32_16x16x32_bf16 v[116:119], v[148:151], v[186:189], v[116:119]
	v_mfma_f32_16x16x32_bf16 v[116:119], v[166:169], v[190:193], v[116:119]
	v_mfma_f32_16x16x32_bf16 v[112:115], v[170:173], v[186:189], v[112:115]
	v_mfma_f32_16x16x32_bf16 v[112:115], v[174:177], v[190:193], v[112:115]
	v_mfma_f32_16x16x32_bf16 v[100:103], v[148:151], v[194:197], v[100:103]
	v_mfma_f32_16x16x32_bf16 v[100:103], v[166:169], v[198:201], v[100:103]
	v_mfma_f32_16x16x32_bf16 v[96:99], v[170:173], v[194:197], v[96:99]
	v_mfma_f32_16x16x32_bf16 v[96:99], v[174:177], v[198:201], v[96:99]
	v_mfma_f32_16x16x32_bf16 v[84:87], v[148:151], v[202:205], v[84:87]
	v_mfma_f32_16x16x32_bf16 v[84:87], v[166:169], v[206:209], v[84:87]
	v_mfma_f32_16x16x32_bf16 v[80:83], v[170:173], v[202:205], v[80:83]
	v_mfma_f32_16x16x32_bf16 v[80:83], v[174:177], v[206:209], v[80:83]
	v_mfma_f32_16x16x32_bf16 v[68:71], v[148:151], v[210:213], v[68:71]
	v_mfma_f32_16x16x32_bf16 v[68:71], v[166:169], v[214:217], v[68:71]
	v_mfma_f32_16x16x32_bf16 v[64:67], v[170:173], v[210:213], v[64:67]
	v_mfma_f32_16x16x32_bf16 v[64:67], v[174:177], v[214:217], v[64:67]
	s_setprio 0
	s_barrier
	s_mov_b32 m0, s59
	s_add_u32 s98, s24, s6
	s_addc_u32 s99, s25, s7
	ds_read_b128 v[186:189], v181 offset:16384
	ds_read_b128 v[190:193], v181 offset:17408
	ds_read_b128 v[194:197], v181 offset:18432
	ds_read_b128 v[198:201], v181 offset:19456
	ds_read_b128 v[202:205], v181 offset:20480
	ds_read_b128 v[206:209], v181 offset:21504
	ds_read_b128 v[210:213], v181 offset:22528
	ds_read_b128 v[214:217], v181 offset:23552
	global_load_lds_dwordx4 v154, s[24:25]
	s_add_i32 m0, s59, 0x2000
	s_add_u32 s20, s24, 0x160000
	s_addc_u32 s21, s25, 0
	s_add_i32 s65, s56, s31
	global_load_lds_dwordx4 v158, s[24:25]
	s_mov_b32 m0, s65
	s_nop 0
	global_load_lds_dwordx4 v154, s[20:21]
	s_add_i32 m0, s65, 0x2000
	s_nop 0
	global_load_lds_dwordx4 v158, s[20:21]
	s_add_u32 s100, s26, s6
	s_addc_u32 s101, s27, s7
	s_mov_b32 m0, s33
	s_nop 0
	global_load_lds_dwordx4 v152, s[26:27]
	s_mov_b32 m0, s34
	s_nop 0
	global_load_lds_dwordx4 v156, s[26:27]
	s_waitcnt vmcnt(8)
	s_waitcnt lgkmcnt(0)
	s_barrier
	s_setprio 1
	s_waitcnt lgkmcnt(0)
	v_mfma_f32_16x16x32_bf16 v[60:63], v[132:135], v[186:189], v[60:63]
	v_mfma_f32_16x16x32_bf16 v[60:63], v[136:139], v[190:193], v[60:63]
	v_mfma_f32_16x16x32_bf16 v[56:59], v[140:143], v[186:189], v[56:59]
	v_mfma_f32_16x16x32_bf16 v[56:59], v[144:147], v[190:193], v[56:59]
	v_mfma_f32_16x16x32_bf16 v[44:47], v[132:135], v[194:197], v[44:47]
	v_mfma_f32_16x16x32_bf16 v[44:47], v[136:139], v[198:201], v[44:47]
	v_mfma_f32_16x16x32_bf16 v[40:43], v[140:143], v[194:197], v[40:43]
	v_mfma_f32_16x16x32_bf16 v[40:43], v[144:147], v[198:201], v[40:43]
	v_mfma_f32_16x16x32_bf16 v[28:31], v[132:135], v[202:205], v[28:31]
	v_mfma_f32_16x16x32_bf16 v[28:31], v[136:139], v[206:209], v[28:31]
	v_mfma_f32_16x16x32_bf16 v[24:27], v[140:143], v[202:205], v[24:27]
	v_mfma_f32_16x16x32_bf16 v[24:27], v[144:147], v[206:209], v[24:27]
	v_mfma_f32_16x16x32_bf16 v[12:15], v[132:135], v[210:213], v[12:15]
	v_mfma_f32_16x16x32_bf16 v[12:15], v[136:139], v[214:217], v[12:15]
	v_mfma_f32_16x16x32_bf16 v[8:11], v[140:143], v[210:213], v[8:11]
	v_mfma_f32_16x16x32_bf16 v[8:11], v[144:147], v[214:217], v[8:11]
	s_setprio 0
	s_setprio 1
	v_mfma_f32_16x16x32_bf16 v[52:55], v[148:151], v[186:189], v[52:55]
	v_mfma_f32_16x16x32_bf16 v[52:55], v[166:169], v[190:193], v[52:55]
	v_mfma_f32_16x16x32_bf16 v[48:51], v[170:173], v[186:189], v[48:51]
	v_mfma_f32_16x16x32_bf16 v[48:51], v[174:177], v[190:193], v[48:51]
	v_mfma_f32_16x16x32_bf16 v[36:39], v[148:151], v[194:197], v[36:39]
	v_mfma_f32_16x16x32_bf16 v[36:39], v[166:169], v[198:201], v[36:39]
	v_mfma_f32_16x16x32_bf16 v[32:35], v[170:173], v[194:197], v[32:35]
	v_mfma_f32_16x16x32_bf16 v[32:35], v[174:177], v[198:201], v[32:35]
	v_mfma_f32_16x16x32_bf16 v[20:23], v[148:151], v[202:205], v[20:23]
	v_mfma_f32_16x16x32_bf16 v[20:23], v[166:169], v[206:209], v[20:23]
	v_mfma_f32_16x16x32_bf16 v[16:19], v[170:173], v[202:205], v[16:19]
	v_mfma_f32_16x16x32_bf16 v[16:19], v[174:177], v[206:209], v[16:19]
	v_mfma_f32_16x16x32_bf16 v[4:7], v[148:151], v[210:213], v[4:7]
	v_mfma_f32_16x16x32_bf16 v[4:7], v[166:169], v[214:217], v[4:7]
	v_mfma_f32_16x16x32_bf16 v[0:3], v[170:173], v[210:213], v[0:3]
	v_mfma_f32_16x16x32_bf16 v[0:3], v[174:177], v[214:217], v[0:3]
	s_setprio 0
	s_barrier
	s_add_i32 s65, 0, 0x18000
	s_add_i32 s66, 0, 0x1c000
	v_add_u32_e32 v144, s65, v178
	v_add_u32_e32 v160, s66, v178
	ds_read_b128 v[132:135], v144
	ds_read_b128 v[136:139], v144 offset:1024
	ds_read_b128 v[140:143], v144 offset:2048
	ds_read_b128 v[144:147], v144 offset:3072
	ds_read_b128 v[148:151], v160
	ds_read_b128 v[166:169], v160 offset:1024
	ds_read_b128 v[170:173], v160 offset:2048
	ds_read_b128 v[174:177], v160 offset:3072
	s_add_u32 s20, s26, 0x160000
	s_addc_u32 s21, s27, 0
	s_mov_b32 m0, s35
	ds_read_b128 v[186:189], v181 offset:32768
	ds_read_b128 v[190:193], v181 offset:33792
	ds_read_b128 v[194:197], v181 offset:34816
	ds_read_b128 v[198:201], v181 offset:35840
	ds_read_b128 v[202:205], v181 offset:36864
	ds_read_b128 v[206:209], v181 offset:37888
	ds_read_b128 v[210:213], v181 offset:38912
	ds_read_b128 v[214:217], v181 offset:39936
	global_load_lds_dwordx4 v152, s[20:21]
	s_mov_b32 m0, s36
	s_nop 0
	global_load_lds_dwordx4 v156, s[20:21]
	s_waitcnt vmcnt(8)
	s_waitcnt lgkmcnt(0)
	s_barrier
	s_setprio 1
	s_waitcnt lgkmcnt(0)
	v_mfma_f32_16x16x32_bf16 v[124:127], v[132:135], v[186:189], v[124:127]
	v_mfma_f32_16x16x32_bf16 v[124:127], v[136:139], v[190:193], v[124:127]
	v_mfma_f32_16x16x32_bf16 v[120:123], v[140:143], v[186:189], v[120:123]
	v_mfma_f32_16x16x32_bf16 v[120:123], v[144:147], v[190:193], v[120:123]
	v_mfma_f32_16x16x32_bf16 v[108:111], v[132:135], v[194:197], v[108:111]
	v_mfma_f32_16x16x32_bf16 v[108:111], v[136:139], v[198:201], v[108:111]
	v_mfma_f32_16x16x32_bf16 v[104:107], v[140:143], v[194:197], v[104:107]
	v_mfma_f32_16x16x32_bf16 v[104:107], v[144:147], v[198:201], v[104:107]
	v_mfma_f32_16x16x32_bf16 v[92:95], v[132:135], v[202:205], v[92:95]
	v_mfma_f32_16x16x32_bf16 v[92:95], v[136:139], v[206:209], v[92:95]
	v_mfma_f32_16x16x32_bf16 v[88:91], v[140:143], v[202:205], v[88:91]
	v_mfma_f32_16x16x32_bf16 v[88:91], v[144:147], v[206:209], v[88:91]
	v_mfma_f32_16x16x32_bf16 v[76:79], v[132:135], v[210:213], v[76:79]
	v_mfma_f32_16x16x32_bf16 v[76:79], v[136:139], v[214:217], v[76:79]
	v_mfma_f32_16x16x32_bf16 v[72:75], v[140:143], v[210:213], v[72:75]
	v_mfma_f32_16x16x32_bf16 v[72:75], v[144:147], v[214:217], v[72:75]
	s_setprio 0
	s_setprio 1
	v_mfma_f32_16x16x32_bf16 v[116:119], v[148:151], v[186:189], v[116:119]
	v_mfma_f32_16x16x32_bf16 v[116:119], v[166:169], v[190:193], v[116:119]
	v_mfma_f32_16x16x32_bf16 v[112:115], v[170:173], v[186:189], v[112:115]
	v_mfma_f32_16x16x32_bf16 v[112:115], v[174:177], v[190:193], v[112:115]
	v_mfma_f32_16x16x32_bf16 v[100:103], v[148:151], v[194:197], v[100:103]
	v_mfma_f32_16x16x32_bf16 v[100:103], v[166:169], v[198:201], v[100:103]
	v_mfma_f32_16x16x32_bf16 v[96:99], v[170:173], v[194:197], v[96:99]
	v_mfma_f32_16x16x32_bf16 v[96:99], v[174:177], v[198:201], v[96:99]
	v_mfma_f32_16x16x32_bf16 v[84:87], v[148:151], v[202:205], v[84:87]
	v_mfma_f32_16x16x32_bf16 v[84:87], v[166:169], v[206:209], v[84:87]
	v_mfma_f32_16x16x32_bf16 v[80:83], v[170:173], v[202:205], v[80:83]
	v_mfma_f32_16x16x32_bf16 v[80:83], v[174:177], v[206:209], v[80:83]
	v_mfma_f32_16x16x32_bf16 v[68:71], v[148:151], v[210:213], v[68:71]
	v_mfma_f32_16x16x32_bf16 v[68:71], v[166:169], v[214:217], v[68:71]
	v_mfma_f32_16x16x32_bf16 v[64:67], v[170:173], v[210:213], v[64:67]
	v_mfma_f32_16x16x32_bf16 v[64:67], v[174:177], v[214:217], v[64:67]
	s_setprio 0
	s_barrier
	s_add_i32 s20, s65, s31
	s_mov_b32 m0, s20
	ds_read_b128 v[186:189], v181 offset:49152
	ds_read_b128 v[190:193], v181 offset:50176
	ds_read_b128 v[194:197], v181 offset:51200
	ds_read_b128 v[198:201], v181 offset:52224
	ds_read_b128 v[202:205], v181 offset:53248
	ds_read_b128 v[206:209], v181 offset:54272
	ds_read_b128 v[210:213], v181 offset:55296
	ds_read_b128 v[214:217], v181 offset:56320
	global_load_lds_dwordx4 v154, s[98:99]
	s_add_i32 m0, s20, 0x2000
	s_add_u32 s20, s24, 0x160080
	s_addc_u32 s21, s25, 0
	s_add_i32 s24, s66, s31
	global_load_lds_dwordx4 v158, s[98:99]
	s_mov_b32 m0, s24
	s_nop 0
	global_load_lds_dwordx4 v154, s[20:21]
	s_add_i32 m0, s24, 0x2000
	s_nop 0
	global_load_lds_dwordx4 v158, s[20:21]
	s_mov_b32 m0, s39
	s_nop 0
	global_load_lds_dwordx4 v152, s[100:101]
	s_mov_b32 m0, s40
	s_nop 0
	global_load_lds_dwordx4 v156, s[100:101]
	s_waitcnt vmcnt(8)
	s_waitcnt lgkmcnt(0)
	s_barrier
	s_setprio 1
	s_waitcnt lgkmcnt(0)
	v_mfma_f32_16x16x32_bf16 v[60:63], v[132:135], v[186:189], v[60:63]
	v_mfma_f32_16x16x32_bf16 v[60:63], v[136:139], v[190:193], v[60:63]
	v_mfma_f32_16x16x32_bf16 v[56:59], v[140:143], v[186:189], v[56:59]
	v_mfma_f32_16x16x32_bf16 v[56:59], v[144:147], v[190:193], v[56:59]
	v_mfma_f32_16x16x32_bf16 v[44:47], v[132:135], v[194:197], v[44:47]
	v_mfma_f32_16x16x32_bf16 v[44:47], v[136:139], v[198:201], v[44:47]
	v_mfma_f32_16x16x32_bf16 v[40:43], v[140:143], v[194:197], v[40:43]
	v_mfma_f32_16x16x32_bf16 v[40:43], v[144:147], v[198:201], v[40:43]
	v_mfma_f32_16x16x32_bf16 v[28:31], v[132:135], v[202:205], v[28:31]
	v_mfma_f32_16x16x32_bf16 v[28:31], v[136:139], v[206:209], v[28:31]
	v_mfma_f32_16x16x32_bf16 v[24:27], v[140:143], v[202:205], v[24:27]
	v_mfma_f32_16x16x32_bf16 v[24:27], v[144:147], v[206:209], v[24:27]
	v_mfma_f32_16x16x32_bf16 v[12:15], v[132:135], v[210:213], v[12:15]
	v_mfma_f32_16x16x32_bf16 v[12:15], v[136:139], v[214:217], v[12:15]
	v_mfma_f32_16x16x32_bf16 v[8:11], v[140:143], v[210:213], v[8:11]
	v_mfma_f32_16x16x32_bf16 v[8:11], v[144:147], v[214:217], v[8:11]
	s_setprio 0
	s_setprio 1
	v_mfma_f32_16x16x32_bf16 v[52:55], v[148:151], v[186:189], v[52:55]
	v_mfma_f32_16x16x32_bf16 v[52:55], v[166:169], v[190:193], v[52:55]
	v_mfma_f32_16x16x32_bf16 v[48:51], v[170:173], v[186:189], v[48:51]
	v_mfma_f32_16x16x32_bf16 v[48:51], v[174:177], v[190:193], v[48:51]
	v_mfma_f32_16x16x32_bf16 v[36:39], v[148:151], v[194:197], v[36:39]
	v_mfma_f32_16x16x32_bf16 v[36:39], v[166:169], v[198:201], v[36:39]
	v_mfma_f32_16x16x32_bf16 v[32:35], v[170:173], v[194:197], v[32:35]
	v_mfma_f32_16x16x32_bf16 v[32:35], v[174:177], v[198:201], v[32:35]
	v_mfma_f32_16x16x32_bf16 v[20:23], v[148:151], v[202:205], v[20:23]
	v_mfma_f32_16x16x32_bf16 v[20:23], v[166:169], v[206:209], v[20:23]
	v_mfma_f32_16x16x32_bf16 v[16:19], v[170:173], v[202:205], v[16:19]
	v_mfma_f32_16x16x32_bf16 v[16:19], v[174:177], v[206:209], v[16:19]
	v_mfma_f32_16x16x32_bf16 v[4:7], v[148:151], v[210:213], v[4:7]
	v_mfma_f32_16x16x32_bf16 v[4:7], v[166:169], v[214:217], v[4:7]
	v_mfma_f32_16x16x32_bf16 v[0:3], v[170:173], v[210:213], v[0:3]
	v_mfma_f32_16x16x32_bf16 v[0:3], v[174:177], v[214:217], v[0:3]
	s_setprio 0
	s_barrier
	s_add_i32 s64, s64, 2
	s_cmpk_gt_u32 s64, 0x55
	s_mov_b64 s[20:21], s[22:23]
	s_cbranch_scc0 .LBB0_975
	s_and_b64 vcc, exec, s[8:9]
	s_cbranch_vccz .LBB0_978
	s_barrier
